# A/B: per-phase s_setprio 1/0 flips deleted from the five 8-phase GEMM loops (80 instructions)
# speedup vs baseline: 1.0077x; 1.0027x over previous
; #define PG8_STAGE(bufoff, gbase, voff) do { _Pragma("unroll") for (int _i = 0; _i < 2; ++_i) \
;         __builtin_amdgcn_global_load_lds((const unsigned*)((const char*)(gbase) + (voff)[_i]), (PG8_LAS unsigned*)(lds + (bufoff) + ldsw + _i * 8192), 16, 0, 0); } while (0)
; #define PG8_LDA(dst, b, h) do { _Pragma("unroll") for (int m = 0; m < 4; ++m) _Pragma("unroll") for (int k = 0; k < 2; ++k) dst[m][k] = *(const PG8_LAS bf16x8*)(lds + PG8_SA(b, h) + aoff + m * 2048 + k * 1024); } while (0)
; #define PG8_LDB(dst, b, h) do { _Pragma("unroll") for (int n = 0; n < 2; ++n) _Pragma("unroll") for (int k = 0; k < 2; ++k) dst[n][k] = *(const PG8_LAS bf16x8*)(lds + PG8_SB(b, h) + boff + n * 2048 + k * 1024); } while (0)
; #define PG8_MMA(ai, bj, At, Bt) do { __builtin_amdgcn_s_setprio(1); _Pragma("unroll") for (int m = 0; m < 4; ++m) _Pragma("unroll") for (int n = 0; n < 2; ++n) _Pragma("unroll") for (int k = 0; k < 2; ++k) \
;         acc[ai][bj][m][n] = __builtin_amdgcn_mfma_f32_16x16x32_bf16(Bt[n][k], At[m][k], acc[ai][bj][m][n], 0, 0, 0); __builtin_amdgcn_s_setprio(0); } while (0)
; #define PG8_WAIT_L(n) asm volatile("s_waitcnt lgkmcnt(" #n ")" ::: "memory")
; #define PG8_BAR __builtin_amdgcn_s_barrier()
; #define PG8_SCHED __builtin_amdgcn_sched_barrier(0)
; template <class Epi, class Sched>
; __device__ __forceinline__ void gemm_phase(PG8_LAS unsigned char* lds, const Gemm g, const Sched& S, const Epi& E) {
;     ...
;         for (int t = 0; t < nt; t += 2) {
;             const bool last = (t == nt - 2);
;             const char* a1 = cA + (size_t)(t + 1) * kstep;
;             const char* a2 = last ? nA : cA + (size_t)(t + 2) * kstep; const char* b2 = last ? nB : cB + (size_t)(t + 2) * kstep;
;             const char* a3 = a2 + kstep; const char* b3 = b2 + kstep;
;             if (last && has_next) S.a_ready(nxt);
;             PG8_LDB(B0, 0, 0); PG8_SCHED; PG8_LDA(At, 0, 0); PG8_STAGE(PG8_SA(1, 1), a1 + hstep, voffA);
;             PG8_WAIT_L(8); PG8_BAR; PG8_WAIT_L(0); PG8_MMA(0, 0, At, B0); PG8_BAR; PG8_SCHED;
;             PG8_LDB(B1, 0, 1); PG8_STAGE(PG8_SB(0, 0), b2, voffB);
;             PG8_BAR; PG8_WAIT_L(0); PG8_MMA(0, 1, At, B1); PG8_BAR;
;             PG8_LDA(At, 0, 1); PG8_STAGE(PG8_SA(0, 0), a2, voffA);
;             PG8_BAR; PG8_WAIT_L(0); PG8_MMA(1, 0, At, B0); PG8_BAR; PG8_SCHED;
.LBB0_114:
	s_add_u32 s20, s18, 0xfffc0080
	s_addc_u32 s21, s19, -1
	s_add_i32 s60, s46, 0x100
	v_add_u32_e32 v166, s60, v155
	ds_read_b128 v[150:153], v166
	ds_read_b128 v[158:161], v166 offset:1024
	ds_read_b128 v[162:165], v166 offset:2048
	ds_read_b128 v[166:169], v166 offset:3072
	s_cmp_eq_u32 s59, 12
	s_cselect_b32 s23, s1, s21
	s_cselect_b32 s22, s9, s20
	s_cselect_b32 s21, s7, s41
	s_cselect_b32 s20, s17, s40
	v_lshl_add_u64 v[186:187], s[18:19], 0, v[134:135]
	s_add_i32 m0, s31, 0xc000
	ds_read_b128 v[170:173], v157
	ds_read_b128 v[174:177], v157 offset:1024
	ds_read_b128 v[178:181], v157 offset:2048
	ds_read_b128 v[182:185], v157 offset:3072
	ds_read_b128 v[210:213], v157 offset:4096
	ds_read_b128 v[214:217], v157 offset:5120
	ds_read_b128 v[218:221], v157 offset:6144
	ds_read_b128 v[222:225], v157 offset:7168
	global_load_lds_dwordx4 v[186:187], off
	v_lshl_add_u64 v[186:187], s[18:19], 0, v[148:149]
	s_add_i32 m0, s31, 0xe000
	s_nop 0
	global_load_lds_dwordx4 v[186:187], off
	s_waitcnt lgkmcnt(8)
	s_barrier
	s_waitcnt lgkmcnt(0)
	s_waitcnt lgkmcnt(0)
	v_mfma_f32_16x16x32_bf16 v[124:127], v[150:153], v[170:173], v[124:127]
	v_mfma_f32_16x16x32_bf16 v[120:123], v[162:165], v[170:173], v[120:123]
	v_mfma_f32_16x16x32_bf16 v[112:115], v[150:153], v[178:181], v[112:115]
	v_mfma_f32_16x16x32_bf16 v[104:107], v[162:165], v[178:181], v[104:107]
	v_mfma_f32_16x16x32_bf16 v[96:99], v[150:153], v[210:213], v[96:99]
	v_mfma_f32_16x16x32_bf16 v[88:91], v[162:165], v[210:213], v[88:91]
	v_mfma_f32_16x16x32_bf16 v[80:83], v[150:153], v[218:221], v[80:83]
	v_mfma_f32_16x16x32_bf16 v[72:75], v[162:165], v[218:221], v[72:75]
	v_mfma_f32_16x16x32_bf16 v[124:127], v[158:161], v[174:177], v[124:127]
	v_mfma_f32_16x16x32_bf16 v[120:123], v[166:169], v[174:177], v[120:123]
	v_mfma_f32_16x16x32_bf16 v[112:115], v[158:161], v[182:185], v[112:115]
	v_mfma_f32_16x16x32_bf16 v[104:107], v[166:169], v[182:185], v[104:107]
	v_mfma_f32_16x16x32_bf16 v[96:99], v[158:161], v[214:217], v[96:99]
	v_mfma_f32_16x16x32_bf16 v[88:91], v[166:169], v[214:217], v[88:91]
	v_mfma_f32_16x16x32_bf16 v[80:83], v[158:161], v[222:225], v[80:83]
	v_mfma_f32_16x16x32_bf16 v[72:75], v[166:169], v[222:225], v[72:75]
	s_barrier
	s_add_i32 s62, s48, 0x100
	v_add_u32_e32 v186, s62, v155
	s_add_i32 s60, s60, s30
	ds_read_b128 v[226:229], v186
	ds_read_b128 v[230:233], v186 offset:1024
	ds_read_b128 v[234:237], v186 offset:2048
	ds_read_b128 v[238:241], v186 offset:3072
	v_lshl_add_u64 v[186:187], s[20:21], 0, v[138:139]
	s_mov_b32 m0, s60
	v_lshl_add_u64 v[242:243], s[20:21], 0, v[132:133]
	global_load_lds_dwordx4 v[186:187], off
	s_add_i32 m0, s60, 0x2000
	s_nop 0
	global_load_lds_dwordx4 v[242:243], off
	s_barrier
	s_waitcnt lgkmcnt(0)
	s_waitcnt lgkmcnt(0)
	v_mfma_f32_16x16x32_bf16 v[116:119], v[226:229], v[170:173], v[116:119]
	v_mfma_f32_16x16x32_bf16 v[108:111], v[234:237], v[170:173], v[108:111]
	v_mfma_f32_16x16x32_bf16 v[100:103], v[226:229], v[178:181], v[100:103]
	v_mfma_f32_16x16x32_bf16 v[92:95], v[234:237], v[178:181], v[92:95]
	v_mfma_f32_16x16x32_bf16 v[84:87], v[226:229], v[210:213], v[84:87]
	v_mfma_f32_16x16x32_bf16 v[76:79], v[234:237], v[210:213], v[76:79]
	v_mfma_f32_16x16x32_bf16 v[68:71], v[226:229], v[218:221], v[68:71]
	v_mfma_f32_16x16x32_bf16 v[64:67], v[234:237], v[218:221], v[64:67]
	v_mfma_f32_16x16x32_bf16 v[116:119], v[230:233], v[174:177], v[116:119]
	v_mfma_f32_16x16x32_bf16 v[108:111], v[238:241], v[174:177], v[108:111]
	v_mfma_f32_16x16x32_bf16 v[100:103], v[230:233], v[182:185], v[100:103]
	v_mfma_f32_16x16x32_bf16 v[92:95], v[238:241], v[182:185], v[92:95]
	v_mfma_f32_16x16x32_bf16 v[84:87], v[230:233], v[214:217], v[84:87]
	v_mfma_f32_16x16x32_bf16 v[76:79], v[238:241], v[214:217], v[76:79]
	v_mfma_f32_16x16x32_bf16 v[68:71], v[230:233], v[222:225], v[68:71]
	v_mfma_f32_16x16x32_bf16 v[64:67], v[238:241], v[222:225], v[64:67]
	s_mov_b32 m0, s31
	v_lshl_add_u64 v[244:245], s[22:23], 0, v[128:129]
	s_barrier
	ds_read_b128 v[170:173], v157 offset:16384
	ds_read_b128 v[174:177], v157 offset:17408
	ds_read_b128 v[178:181], v157 offset:18432
	ds_read_b128 v[182:185], v157 offset:19456
	ds_read_b128 v[210:213], v157 offset:20480
	ds_read_b128 v[214:217], v157 offset:21504
	ds_read_b128 v[218:221], v157 offset:22528
	ds_read_b128 v[222:225], v157 offset:23552
	global_load_lds_dwordx4 v[244:245], off
	v_lshl_add_u64 v[246:247], s[22:23], 0, v[130:131]
	s_mov_b32 m0, s33
	s_nop 0
	global_load_lds_dwordx4 v[246:247], off
	s_barrier
	s_waitcnt lgkmcnt(0)
	s_waitcnt lgkmcnt(0)
	v_mfma_f32_16x16x32_bf16 v[60:63], v[150:153], v[170:173], v[60:63]
	v_mfma_f32_16x16x32_bf16 v[56:59], v[162:165], v[170:173], v[56:59]
	v_mfma_f32_16x16x32_bf16 v[48:51], v[150:153], v[178:181], v[48:51]
	v_mfma_f32_16x16x32_bf16 v[40:43], v[162:165], v[178:181], v[40:43]
	v_mfma_f32_16x16x32_bf16 v[32:35], v[150:153], v[210:213], v[32:35]
	v_mfma_f32_16x16x32_bf16 v[24:27], v[162:165], v[210:213], v[24:27]
	v_mfma_f32_16x16x32_bf16 v[16:19], v[150:153], v[218:221], v[16:19]
	v_mfma_f32_16x16x32_bf16 v[8:11], v[162:165], v[218:221], v[8:11]
	v_mfma_f32_16x16x32_bf16 v[60:63], v[158:161], v[174:177], v[60:63]
	v_mfma_f32_16x16x32_bf16 v[56:59], v[166:169], v[174:177], v[56:59]
	v_mfma_f32_16x16x32_bf16 v[48:51], v[158:161], v[182:185], v[48:51]
	v_mfma_f32_16x16x32_bf16 v[40:43], v[166:169], v[182:185], v[40:43]
	v_mfma_f32_16x16x32_bf16 v[32:35], v[158:161], v[214:217], v[32:35]
	v_mfma_f32_16x16x32_bf16 v[24:27], v[166:169], v[214:217], v[24:27]
	v_mfma_f32_16x16x32_bf16 v[16:19], v[158:161], v[222:225], v[16:19]
	v_mfma_f32_16x16x32_bf16 v[8:11], v[166:169], v[222:225], v[8:11]
	s_barrier
; #define PG8_STAGE(bufoff, gbase, voff) do { _Pragma("unroll") for (int _i = 0; _i < 2; ++_i) \
;         __builtin_amdgcn_global_load_lds((const unsigned*)((const char*)(gbase) + (voff)[_i]), (PG8_LAS unsigned*)(lds + (bufoff) + ldsw + _i * 8192), 16, 0, 0); } while (0)
; #define PG8_LDA(dst, b, h) do { _Pragma("unroll") for (int m = 0; m < 4; ++m) _Pragma("unroll") for (int k = 0; k < 2; ++k) dst[m][k] = *(const PG8_LAS bf16x8*)(lds + PG8_SA(b, h) + aoff + m * 2048 + k * 1024); } while (0)
; #define PG8_LDB(dst, b, h) do { _Pragma("unroll") for (int n = 0; n < 2; ++n) _Pragma("unroll") for (int k = 0; k < 2; ++k) dst[n][k] = *(const PG8_LAS bf16x8*)(lds + PG8_SB(b, h) + boff + n * 2048 + k * 1024); } while (0)
; #define PG8_MMA(ai, bj, At, Bt) do { __builtin_amdgcn_s_setprio(1); _Pragma("unroll") for (int m = 0; m < 4; ++m) _Pragma("unroll") for (int n = 0; n < 2; ++n) _Pragma("unroll") for (int k = 0; k < 2; ++k) \
;         acc[ai][bj][m][n] = __builtin_amdgcn_mfma_f32_16x16x32_bf16(Bt[n][k], At[m][k], acc[ai][bj][m][n], 0, 0, 0); __builtin_amdgcn_s_setprio(0); } while (0)
; #define PG8_WAIT_V(n) asm volatile("s_waitcnt vmcnt(" #n ")" ::: "memory")
; #define PG8_WAIT_L(n) asm volatile("s_waitcnt lgkmcnt(" #n ")" ::: "memory")
; #define PG8_BAR __builtin_amdgcn_s_barrier()
; #define PG8_SCHED __builtin_amdgcn_sched_barrier(0)
; template <class Epi, class Sched>
; __device__ __forceinline__ void gemm_phase(PG8_LAS unsigned char* lds, const Gemm g, const Sched& S, const Epi& E) {
;     ...
;             PG8_STAGE(PG8_SB(0, 1), b2 + hstep, voffB);
;             PG8_WAIT_V(6); PG8_BAR; PG8_MMA(1, 1, At, B1); PG8_BAR;
;             PG8_LDB(B0, 1, 0); PG8_SCHED; PG8_LDA(At, 1, 0); PG8_STAGE(PG8_SA(0, 1), a2 + hstep, voffA);
;             PG8_WAIT_L(8); PG8_BAR; PG8_WAIT_L(0); PG8_MMA(0, 0, At, B0); PG8_BAR; PG8_SCHED;
;             PG8_LDB(B1, 1, 1); PG8_STAGE(PG8_SB(1, 0), b3, voffB);
;             PG8_BAR; PG8_WAIT_L(0); PG8_MMA(0, 1, At, B1); PG8_BAR;
;             PG8_LDA(At, 1, 1); PG8_STAGE(PG8_SA(1, 0), a3, voffA);
;             PG8_BAR; PG8_WAIT_L(0); PG8_MMA(1, 0, At, B0); PG8_BAR; PG8_SCHED;
	s_add_u32 s60, s20, 0x40000
	s_addc_u32 s61, s21, 0
	s_add_i32 s62, s62, s30
	v_lshl_add_u64 v[150:151], s[60:61], 0, v[138:139]
	s_mov_b32 m0, s62
	s_nop 0
	global_load_lds_dwordx4 v[150:151], off
	v_lshl_add_u64 v[150:151], s[60:61], 0, v[132:133]
	s_add_i32 m0, s62, 0x2000
	s_nop 0
	global_load_lds_dwordx4 v[150:151], off
	s_waitcnt vmcnt(6)
	s_barrier
	v_mfma_f32_16x16x32_bf16 v[52:55], v[226:229], v[170:173], v[52:55]
	v_mfma_f32_16x16x32_bf16 v[44:47], v[234:237], v[170:173], v[44:47]
	v_mfma_f32_16x16x32_bf16 v[36:39], v[226:229], v[178:181], v[36:39]
	v_mfma_f32_16x16x32_bf16 v[28:31], v[234:237], v[178:181], v[28:31]
	v_mfma_f32_16x16x32_bf16 v[20:23], v[226:229], v[210:213], v[20:23]
	v_mfma_f32_16x16x32_bf16 v[12:15], v[234:237], v[210:213], v[12:15]
	v_mfma_f32_16x16x32_bf16 v[4:7], v[226:229], v[218:221], v[4:7]
	v_mfma_f32_16x16x32_bf16 v[0:3], v[234:237], v[218:221], v[0:3]
	v_mfma_f32_16x16x32_bf16 v[52:55], v[230:233], v[174:177], v[52:55]
	v_mfma_f32_16x16x32_bf16 v[44:47], v[238:241], v[174:177], v[44:47]
	v_mfma_f32_16x16x32_bf16 v[36:39], v[230:233], v[182:185], v[36:39]
	v_mfma_f32_16x16x32_bf16 v[28:31], v[238:241], v[182:185], v[28:31]
	v_mfma_f32_16x16x32_bf16 v[20:23], v[230:233], v[214:217], v[20:23]
	v_mfma_f32_16x16x32_bf16 v[12:15], v[238:241], v[214:217], v[12:15]
	v_mfma_f32_16x16x32_bf16 v[4:7], v[230:233], v[222:225], v[4:7]
	v_mfma_f32_16x16x32_bf16 v[0:3], v[238:241], v[222:225], v[0:3]
	s_add_i32 s60, s51, 0x100
	v_add_u32_e32 v166, s60, v155
	s_barrier
	ds_read_b128 v[150:153], v166
	ds_read_b128 v[158:161], v166 offset:1024
	ds_read_b128 v[162:165], v166 offset:2048
	ds_read_b128 v[166:169], v166 offset:3072
	s_add_u32 s22, s22, 0x40000
	s_addc_u32 s23, s23, 0
	s_mov_b32 m0, s34
	v_lshl_add_u64 v[226:227], s[22:23], 0, v[128:129]
	ds_read_b128 v[170:173], v157 offset:32768
	ds_read_b128 v[174:177], v157 offset:33792
	ds_read_b128 v[178:181], v157 offset:34816
	ds_read_b128 v[182:185], v157 offset:35840
	ds_read_b128 v[210:213], v157 offset:36864
	ds_read_b128 v[214:217], v157 offset:37888
	ds_read_b128 v[218:221], v157 offset:38912
	ds_read_b128 v[222:225], v157 offset:39936
	global_load_lds_dwordx4 v[226:227], off
	v_lshl_add_u64 v[226:227], s[22:23], 0, v[130:131]
	s_mov_b32 m0, s35
	s_nop 0
	global_load_lds_dwordx4 v[226:227], off
	s_waitcnt lgkmcnt(8)
	s_barrier
	s_waitcnt lgkmcnt(0)
	s_waitcnt lgkmcnt(0)
	v_mfma_f32_16x16x32_bf16 v[124:127], v[150:153], v[170:173], v[124:127]
	v_mfma_f32_16x16x32_bf16 v[120:123], v[162:165], v[170:173], v[120:123]
	v_mfma_f32_16x16x32_bf16 v[112:115], v[150:153], v[178:181], v[112:115]
	v_mfma_f32_16x16x32_bf16 v[104:107], v[162:165], v[178:181], v[104:107]
	v_mfma_f32_16x16x32_bf16 v[96:99], v[150:153], v[210:213], v[96:99]
	v_mfma_f32_16x16x32_bf16 v[88:91], v[162:165], v[210:213], v[88:91]
	v_mfma_f32_16x16x32_bf16 v[80:83], v[150:153], v[218:221], v[80:83]
	v_mfma_f32_16x16x32_bf16 v[72:75], v[162:165], v[218:221], v[72:75]
	v_mfma_f32_16x16x32_bf16 v[124:127], v[158:161], v[174:177], v[124:127]
	v_mfma_f32_16x16x32_bf16 v[120:123], v[166:169], v[174:177], v[120:123]
	v_mfma_f32_16x16x32_bf16 v[112:115], v[158:161], v[182:185], v[112:115]
	v_mfma_f32_16x16x32_bf16 v[104:107], v[166:169], v[182:185], v[104:107]
	v_mfma_f32_16x16x32_bf16 v[96:99], v[158:161], v[214:217], v[96:99]
	v_mfma_f32_16x16x32_bf16 v[88:91], v[166:169], v[214:217], v[88:91]
	v_mfma_f32_16x16x32_bf16 v[80:83], v[158:161], v[222:225], v[80:83]
	v_mfma_f32_16x16x32_bf16 v[72:75], v[166:169], v[222:225], v[72:75]
	s_barrier
	s_add_i32 s22, s55, 0x100
	s_add_i32 s23, s60, s30
	v_add_u32_e32 v209, s22, v155
	v_lshl_add_u64 v[186:187], v[186:187], 0, s[94:95]
	s_mov_b32 m0, s23
	ds_read_b128 v[226:229], v209
	ds_read_b128 v[230:233], v209 offset:1024
	ds_read_b128 v[234:237], v209 offset:2048
	ds_read_b128 v[238:241], v209 offset:3072
	global_load_lds_dwordx4 v[186:187], off
	v_lshl_add_u64 v[186:187], v[242:243], 0, s[94:95]
	s_add_i32 m0, s23, 0x2000
	s_nop 0
	global_load_lds_dwordx4 v[186:187], off
	s_barrier
;   __device__ __forceinline__ bf16* y() const { unsigned o_ = (unsigned)(OFF_y); asm volatile("" : "+s"(o_)); return (bf16*)(ws + o_); }
; __device__ __forceinline__ unsigned pk2(float a, float b) { unsigned r; asm("v_cvt_pk_bf16_f32 %0, %1, %2" : "=v"(r) : "v"(a), "v"(b)); return r; }
; #define PG8_STAGE(bufoff, gbase, voff) do { _Pragma("unroll") for (int _i = 0; _i < 2; ++_i) \
;         __builtin_amdgcn_global_load_lds((const unsigned*)((const char*)(gbase) + (voff)[_i]), (PG8_LAS unsigned*)(lds + (bufoff) + ldsw + _i * 8192), 16, 0, 0); } while (0)
; #define PG8_MMA(ai, bj, At, Bt) do { __builtin_amdgcn_s_setprio(1); _Pragma("unroll") for (int m = 0; m < 4; ++m) _Pragma("unroll") for (int n = 0; n < 2; ++n) _Pragma("unroll") for (int k = 0; k < 2; ++k) \
;         acc[ai][bj][m][n] = __builtin_amdgcn_mfma_f32_16x16x32_bf16(Bt[n][k], At[m][k], acc[ai][bj][m][n], 0, 0, 0); __builtin_amdgcn_s_setprio(0); } while (0)
; #define PG8_WAIT_V(n) asm volatile("s_waitcnt vmcnt(" #n ")" ::: "memory")
; #define PG8_WAIT_L(n) asm volatile("s_waitcnt lgkmcnt(" #n ")" ::: "memory")
; #define PG8_BAR __builtin_amdgcn_s_barrier()
; template <class Epi, class Sched>
; __device__ __forceinline__ void gemm_phase(PG8_LAS unsigned char* lds, const Gemm g, const Sched& S, const Epi& E) {
;     ...
;             PG8_BAR; PG8_WAIT_L(0); PG8_MMA(1, 0, At, B0); PG8_BAR; PG8_SCHED;
;             PG8_STAGE(PG8_SB(1, 1), b3 + hstep, voffB);
;             PG8_WAIT_V(6); PG8_BAR; PG8_MMA(1, 1, At, B1); PG8_BAR;
;         }
;   __device__ __forceinline__ void operator()(const f32x4 (&acc)[2][2][4][2], const pg8::Unit& u, int wr, int wc, int fr, int fq) const {
;     const int row0 = u.pm * 256 + wr * 64 + fr, col0 = u.pn * 256 + wc * 32 + 8 * fq;
; #pragma unroll
;     for (int ai = 0; ai < 2; ++ai)
; #pragma unroll
;       for (int m = 0; m < 4; ++m) {
;         bf16* rowp = O + (size_t)(row0 + ai * 128 + m * 16) * US + col0;
; #pragma unroll
;         for (int bj = 0; bj < 2; ++bj) {
;           if (col0 + bj * 128 < US) {
;             uint4 o;
;             o.x = pk2(acc[ai][bj][m][0][0], acc[ai][bj][m][0][1]); o.y = pk2(acc[ai][bj][m][0][2], acc[ai][bj][m][0][3]);
;             o.z = pk2(acc[ai][bj][m][1][0], acc[ai][bj][m][1][1]); o.w = pk2(acc[ai][bj][m][1][2], acc[ai][bj][m][1][3]);
;             *(uint4*)(rowp + bj * 128) = o;
;           }
	s_waitcnt lgkmcnt(0)
	s_waitcnt lgkmcnt(0)
	v_mfma_f32_16x16x32_bf16 v[116:119], v[226:229], v[170:173], v[116:119]
	v_mfma_f32_16x16x32_bf16 v[108:111], v[234:237], v[170:173], v[108:111]
	v_mfma_f32_16x16x32_bf16 v[100:103], v[226:229], v[178:181], v[100:103]
	v_mfma_f32_16x16x32_bf16 v[92:95], v[234:237], v[178:181], v[92:95]
	v_mfma_f32_16x16x32_bf16 v[84:87], v[226:229], v[210:213], v[84:87]
	v_mfma_f32_16x16x32_bf16 v[76:79], v[234:237], v[210:213], v[76:79]
	v_mfma_f32_16x16x32_bf16 v[68:71], v[226:229], v[218:221], v[68:71]
	v_mfma_f32_16x16x32_bf16 v[64:67], v[234:237], v[218:221], v[64:67]
	v_mfma_f32_16x16x32_bf16 v[116:119], v[230:233], v[174:177], v[116:119]
	v_mfma_f32_16x16x32_bf16 v[108:111], v[238:241], v[174:177], v[108:111]
	v_mfma_f32_16x16x32_bf16 v[100:103], v[230:233], v[182:185], v[100:103]
	v_mfma_f32_16x16x32_bf16 v[92:95], v[238:241], v[182:185], v[92:95]
	v_mfma_f32_16x16x32_bf16 v[84:87], v[230:233], v[214:217], v[84:87]
	v_mfma_f32_16x16x32_bf16 v[76:79], v[238:241], v[214:217], v[76:79]
	v_mfma_f32_16x16x32_bf16 v[68:71], v[230:233], v[222:225], v[68:71]
	v_mfma_f32_16x16x32_bf16 v[64:67], v[238:241], v[222:225], v[64:67]
	s_mov_b32 m0, s36
	v_lshl_add_u64 v[186:187], v[244:245], 0, s[94:95]
	s_barrier
	ds_read_b128 v[170:173], v157 offset:49152
	ds_read_b128 v[174:177], v157 offset:50176
	ds_read_b128 v[178:181], v157 offset:51200
	ds_read_b128 v[182:185], v157 offset:52224
	ds_read_b128 v[210:213], v157 offset:53248
	ds_read_b128 v[214:217], v157 offset:54272
	ds_read_b128 v[218:221], v157 offset:55296
	ds_read_b128 v[222:225], v157 offset:56320
	global_load_lds_dwordx4 v[186:187], off
	v_lshl_add_u64 v[186:187], v[246:247], 0, s[94:95]
	s_mov_b32 m0, s37
	s_nop 0
	global_load_lds_dwordx4 v[186:187], off
	s_barrier
	s_waitcnt lgkmcnt(0)
	s_waitcnt lgkmcnt(0)
	v_mfma_f32_16x16x32_bf16 v[60:63], v[150:153], v[170:173], v[60:63]
	v_mfma_f32_16x16x32_bf16 v[56:59], v[162:165], v[170:173], v[56:59]
	v_mfma_f32_16x16x32_bf16 v[48:51], v[150:153], v[178:181], v[48:51]
	v_mfma_f32_16x16x32_bf16 v[40:43], v[162:165], v[178:181], v[40:43]
	v_mfma_f32_16x16x32_bf16 v[32:35], v[150:153], v[210:213], v[32:35]
	v_mfma_f32_16x16x32_bf16 v[24:27], v[162:165], v[210:213], v[24:27]
	v_mfma_f32_16x16x32_bf16 v[16:19], v[150:153], v[218:221], v[16:19]
	v_mfma_f32_16x16x32_bf16 v[8:11], v[162:165], v[218:221], v[8:11]
	v_mfma_f32_16x16x32_bf16 v[60:63], v[158:161], v[174:177], v[60:63]
	v_mfma_f32_16x16x32_bf16 v[56:59], v[166:169], v[174:177], v[56:59]
	v_mfma_f32_16x16x32_bf16 v[48:51], v[158:161], v[182:185], v[48:51]
	v_mfma_f32_16x16x32_bf16 v[40:43], v[166:169], v[182:185], v[40:43]
	v_mfma_f32_16x16x32_bf16 v[32:35], v[158:161], v[214:217], v[32:35]
	v_mfma_f32_16x16x32_bf16 v[24:27], v[166:169], v[214:217], v[24:27]
	v_mfma_f32_16x16x32_bf16 v[16:19], v[158:161], v[222:225], v[16:19]
	v_mfma_f32_16x16x32_bf16 v[8:11], v[166:169], v[222:225], v[8:11]
	s_barrier
	s_add_u32 s20, s20, 0x40080
	s_addc_u32 s21, s21, 0
	s_add_i32 s22, s22, s30
	v_lshl_add_u64 v[150:151], s[20:21], 0, v[138:139]
	s_mov_b32 m0, s22
	s_nop 0
	global_load_lds_dwordx4 v[150:151], off
	v_lshl_add_u64 v[150:151], s[20:21], 0, v[132:133]
	s_add_i32 m0, s22, 0x2000
	s_nop 0
	global_load_lds_dwordx4 v[150:151], off
	s_waitcnt vmcnt(6)
	s_barrier
	v_mfma_f32_16x16x32_bf16 v[52:55], v[226:229], v[170:173], v[52:55]
	v_mfma_f32_16x16x32_bf16 v[44:47], v[234:237], v[170:173], v[44:47]
	v_mfma_f32_16x16x32_bf16 v[36:39], v[226:229], v[178:181], v[36:39]
	v_mfma_f32_16x16x32_bf16 v[28:31], v[234:237], v[178:181], v[28:31]
	v_mfma_f32_16x16x32_bf16 v[20:23], v[226:229], v[210:213], v[20:23]
	v_mfma_f32_16x16x32_bf16 v[12:15], v[234:237], v[210:213], v[12:15]
	v_mfma_f32_16x16x32_bf16 v[4:7], v[226:229], v[218:221], v[4:7]
	v_mfma_f32_16x16x32_bf16 v[0:3], v[234:237], v[218:221], v[0:3]
	v_mfma_f32_16x16x32_bf16 v[52:55], v[230:233], v[174:177], v[52:55]
	v_mfma_f32_16x16x32_bf16 v[44:47], v[238:241], v[174:177], v[44:47]
	v_mfma_f32_16x16x32_bf16 v[36:39], v[230:233], v[182:185], v[36:39]
	v_mfma_f32_16x16x32_bf16 v[28:31], v[238:241], v[182:185], v[28:31]
	v_mfma_f32_16x16x32_bf16 v[20:23], v[230:233], v[214:217], v[20:23]
	v_mfma_f32_16x16x32_bf16 v[12:15], v[238:241], v[214:217], v[12:15]
	v_mfma_f32_16x16x32_bf16 v[4:7], v[230:233], v[222:225], v[4:7]
	v_mfma_f32_16x16x32_bf16 v[0:3], v[238:241], v[222:225], v[0:3]
	s_add_i32 s59, s59, 2
	s_add_u32 s18, s18, 0x100
	s_addc_u32 s19, s19, 0
	s_add_u32 s40, s40, 0x100
	s_addc_u32 s41, s41, 0
	s_cmp_gt_u32 s59, 13
	s_barrier
	s_cbranch_scc0 .LBB0_114
	v_lshl_add_u32 v158, s16, 8, v154
	v_lshl_or_b32 v150, s0, 8, v156
	v_mov_b64_e32 v[152:153], s[4:5]
	v_ashrrev_i32_e32 v151, 31, v150
	v_mad_i64_i32 v[152:153], s[0:1], v158, s54, v[152:153]
	v_lshl_add_u64 v[152:153], v[150:151], 1, v[152:153]
	v_cmp_gt_i32_e32 vcc, s11, v150
	s_and_saveexec_b64 s[0:1], vcc
	s_cbranch_execz .LBB0_117
	v_cvt_pk_bf16_f32 v124, v124, v125
	v_cvt_pk_bf16_f32 v125, v126, v127
	v_cvt_pk_bf16_f32 v126, v120, v121
	v_cvt_pk_bf16_f32 v127, v122, v123
	global_store_dwordx4 v[152:153], v[124:127], off

; #define PG8_STAGE(bufoff, gbase, voff) do { _Pragma("unroll") for (int _i = 0; _i < 2; ++_i) \
;         __builtin_amdgcn_global_load_lds((const unsigned*)((const char*)(gbase) + (voff)[_i]), (PG8_LAS unsigned*)(lds + (bufoff) + ldsw + _i * 8192), 16, 0, 0); } while (0)
; #define PG8_LDA(dst, b, h) do { _Pragma("unroll") for (int m = 0; m < 4; ++m) _Pragma("unroll") for (int k = 0; k < 2; ++k) dst[m][k] = *(const PG8_LAS bf16x8*)(lds + PG8_SA(b, h) + aoff + m * 2048 + k * 1024); } while (0)
; #define PG8_LDB(dst, b, h) do { _Pragma("unroll") for (int n = 0; n < 2; ++n) _Pragma("unroll") for (int k = 0; k < 2; ++k) dst[n][k] = *(const PG8_LAS bf16x8*)(lds + PG8_SB(b, h) + boff + n * 2048 + k * 1024); } while (0)
; #define PG8_MMA(ai, bj, At, Bt) do { __builtin_amdgcn_s_setprio(1); _Pragma("unroll") for (int m = 0; m < 4; ++m) _Pragma("unroll") for (int n = 0; n < 2; ++n) _Pragma("unroll") for (int k = 0; k < 2; ++k) \
;         acc[ai][bj][m][n] = __builtin_amdgcn_mfma_f32_16x16x32_bf16(Bt[n][k], At[m][k], acc[ai][bj][m][n], 0, 0, 0); __builtin_amdgcn_s_setprio(0); } while (0)
; #define PG8_WAIT_L(n) asm volatile("s_waitcnt lgkmcnt(" #n ")" ::: "memory")
; #define PG8_BAR __builtin_amdgcn_s_barrier()
; #define PG8_SCHED __builtin_amdgcn_sched_barrier(0)
; template <class Epi, class Sched>
; __device__ __forceinline__ void gemm_phase(PG8_LAS unsigned char* lds, const Gemm g, const Sched& S, const Epi& E) {
;     ...
;         for (int t = 0; t < nt; t += 2) {
;             const bool last = (t == nt - 2);
;             const char* a1 = cA + (size_t)(t + 1) * kstep;
;             const char* a2 = last ? nA : cA + (size_t)(t + 2) * kstep; const char* b2 = last ? nB : cB + (size_t)(t + 2) * kstep;
;             const char* a3 = a2 + kstep; const char* b3 = b2 + kstep;
;             if (last && has_next) S.a_ready(nxt);
;             PG8_LDB(B0, 0, 0); PG8_SCHED; PG8_LDA(At, 0, 0); PG8_STAGE(PG8_SA(1, 1), a1 + hstep, voffA);
;             PG8_WAIT_L(8); PG8_BAR; PG8_WAIT_L(0); PG8_MMA(0, 0, At, B0); PG8_BAR; PG8_SCHED;
;             PG8_LDB(B1, 0, 1); PG8_STAGE(PG8_SB(0, 0), b2, voffB);
;             PG8_BAR; PG8_WAIT_L(0); PG8_MMA(0, 1, At, B1); PG8_BAR;
;             PG8_LDA(At, 0, 1); PG8_STAGE(PG8_SA(0, 0), a2, voffA);
;             PG8_BAR; PG8_WAIT_L(0); PG8_MMA(1, 0, At, B0); PG8_BAR; PG8_SCHED;
.LBB0_803:
	s_add_u32 s12, s4, s24
	s_addc_u32 s13, s5, s25
	s_add_u32 s12, s12, 0x100
	s_addc_u32 s13, s13, 0
	s_add_u32 s26, s83, s24
	s_addc_u32 s27, s84, s25
	s_add_i32 s91, s46, 0x100
	v_add_u32_e32 v159, s91, v155
	ds_read_b128 v[160:163], v159
	ds_read_b128 v[164:167], v159 offset:1024
	ds_read_b128 v[168:171], v159 offset:2048
	ds_read_b128 v[172:175], v159 offset:3072
	s_cmpk_eq_i32 s24, 0x700
	s_cselect_b32 s29, s19, s13
	s_cselect_b32 s28, s85, s12
	s_cselect_b32 s27, s7, s27
	s_cselect_b32 s26, vcc_lo, s26
	v_lshl_add_u64 v[230:231], v[150:151], 0, s[24:25]
	s_add_i32 m0, s17, 0xc000
	ds_read_b128 v[176:179], v158
	ds_read_b128 v[180:183], v158 offset:1024
	ds_read_b128 v[184:187], v158 offset:2048
	ds_read_b128 v[210:213], v158 offset:3072
	ds_read_b128 v[214:217], v158 offset:4096
	ds_read_b128 v[218:221], v158 offset:5120
	ds_read_b128 v[222:225], v158 offset:6144
	ds_read_b128 v[226:229], v158 offset:7168
	global_load_lds_dwordx4 v[230:231], off
	v_lshl_add_u64 v[230:231], v[152:153], 0, s[24:25]
	s_add_i32 m0, s17, 0xe000
	s_nop 0
	global_load_lds_dwordx4 v[230:231], off
	s_waitcnt lgkmcnt(8)
	s_barrier
	s_waitcnt lgkmcnt(0)
	s_waitcnt lgkmcnt(0)
	v_mfma_f32_16x16x32_bf16 v[124:127], v[160:163], v[176:179], v[124:127]
	v_mfma_f32_16x16x32_bf16 v[120:123], v[168:171], v[176:179], v[120:123]
	v_mfma_f32_16x16x32_bf16 v[116:119], v[160:163], v[184:187], v[116:119]
	v_mfma_f32_16x16x32_bf16 v[112:115], v[168:171], v[184:187], v[112:115]
	v_mfma_f32_16x16x32_bf16 v[108:111], v[160:163], v[214:217], v[108:111]
	v_mfma_f32_16x16x32_bf16 v[104:107], v[168:171], v[214:217], v[104:107]
	v_mfma_f32_16x16x32_bf16 v[100:103], v[160:163], v[222:225], v[100:103]
	v_mfma_f32_16x16x32_bf16 v[96:99], v[168:171], v[222:225], v[96:99]
	v_mfma_f32_16x16x32_bf16 v[124:127], v[164:167], v[180:183], v[124:127]
	v_mfma_f32_16x16x32_bf16 v[120:123], v[172:175], v[180:183], v[120:123]
	v_mfma_f32_16x16x32_bf16 v[116:119], v[164:167], v[210:213], v[116:119]
	v_mfma_f32_16x16x32_bf16 v[112:115], v[172:175], v[210:213], v[112:115]
	v_mfma_f32_16x16x32_bf16 v[108:111], v[164:167], v[218:221], v[108:111]
	v_mfma_f32_16x16x32_bf16 v[104:107], v[172:175], v[218:221], v[104:107]
	v_mfma_f32_16x16x32_bf16 v[100:103], v[164:167], v[226:229], v[100:103]
	v_mfma_f32_16x16x32_bf16 v[96:99], v[172:175], v[226:229], v[96:99]
	s_barrier
	s_add_i32 s69, s48, 0x100
	s_add_i32 s12, s91, s59
	v_add_u32_e32 v159, s69, v155
	v_lshl_add_u64 v[246:247], s[26:27], 0, v[138:139]
	s_mov_b32 m0, s12
	ds_read_b128 v[230:233], v159
	ds_read_b128 v[234:237], v159 offset:1024
	ds_read_b128 v[238:241], v159 offset:2048
	ds_read_b128 v[242:245], v159 offset:3072
	global_load_lds_dwordx4 v[246:247], off
	v_lshl_add_u64 v[248:249], s[26:27], 0, v[132:133]
	s_add_i32 m0, s12, 0x2000
	s_nop 0
	global_load_lds_dwordx4 v[248:249], off
	s_barrier
	s_waitcnt lgkmcnt(0)
	s_waitcnt lgkmcnt(0)
	v_mfma_f32_16x16x32_bf16 v[60:63], v[230:233], v[176:179], v[60:63]
	v_mfma_f32_16x16x32_bf16 v[56:59], v[238:241], v[176:179], v[56:59]
	v_mfma_f32_16x16x32_bf16 v[52:55], v[230:233], v[184:187], v[52:55]
	v_mfma_f32_16x16x32_bf16 v[48:51], v[238:241], v[184:187], v[48:51]
	v_mfma_f32_16x16x32_bf16 v[44:47], v[230:233], v[214:217], v[44:47]
	v_mfma_f32_16x16x32_bf16 v[40:43], v[238:241], v[214:217], v[40:43]
	v_mfma_f32_16x16x32_bf16 v[36:39], v[230:233], v[222:225], v[36:39]
	v_mfma_f32_16x16x32_bf16 v[32:35], v[238:241], v[222:225], v[32:35]
	v_mfma_f32_16x16x32_bf16 v[60:63], v[234:237], v[180:183], v[60:63]
	v_mfma_f32_16x16x32_bf16 v[56:59], v[242:245], v[180:183], v[56:59]
	v_mfma_f32_16x16x32_bf16 v[52:55], v[234:237], v[210:213], v[52:55]
	v_mfma_f32_16x16x32_bf16 v[48:51], v[242:245], v[210:213], v[48:51]
	v_mfma_f32_16x16x32_bf16 v[44:47], v[234:237], v[218:221], v[44:47]
	v_mfma_f32_16x16x32_bf16 v[40:43], v[242:245], v[218:221], v[40:43]
	v_mfma_f32_16x16x32_bf16 v[36:39], v[234:237], v[226:229], v[36:39]
	v_mfma_f32_16x16x32_bf16 v[32:35], v[242:245], v[226:229], v[32:35]
	s_mov_b32 m0, s17
	v_lshl_add_u64 v[250:251], s[28:29], 0, v[128:129]
	s_barrier
	ds_read_b128 v[176:179], v158 offset:16384
	ds_read_b128 v[180:183], v158 offset:17408
	ds_read_b128 v[184:187], v158 offset:18432
	ds_read_b128 v[210:213], v158 offset:19456
	ds_read_b128 v[214:217], v158 offset:20480
	ds_read_b128 v[218:221], v158 offset:21504
	ds_read_b128 v[222:225], v158 offset:22528
	ds_read_b128 v[226:229], v158 offset:23552
	global_load_lds_dwordx4 v[250:251], off
	v_lshl_add_u64 v[252:253], s[28:29], 0, v[130:131]
	s_mov_b32 m0, s63
	s_nop 0
	global_load_lds_dwordx4 v[252:253], off
	s_barrier
	s_waitcnt lgkmcnt(0)
	s_waitcnt lgkmcnt(0)
	v_mfma_f32_16x16x32_bf16 v[92:95], v[160:163], v[176:179], v[92:95]
	v_mfma_f32_16x16x32_bf16 v[88:91], v[168:171], v[176:179], v[88:91]
	v_mfma_f32_16x16x32_bf16 v[84:87], v[160:163], v[184:187], v[84:87]
	v_mfma_f32_16x16x32_bf16 v[80:83], v[168:171], v[184:187], v[80:83]
	v_mfma_f32_16x16x32_bf16 v[76:79], v[160:163], v[214:217], v[76:79]
	v_mfma_f32_16x16x32_bf16 v[72:75], v[168:171], v[214:217], v[72:75]
	v_mfma_f32_16x16x32_bf16 v[68:71], v[160:163], v[222:225], v[68:71]
	v_mfma_f32_16x16x32_bf16 v[64:67], v[168:171], v[222:225], v[64:67]
	v_mfma_f32_16x16x32_bf16 v[92:95], v[164:167], v[180:183], v[92:95]
	v_mfma_f32_16x16x32_bf16 v[88:91], v[172:175], v[180:183], v[88:91]
	v_mfma_f32_16x16x32_bf16 v[84:87], v[164:167], v[210:213], v[84:87]
	v_mfma_f32_16x16x32_bf16 v[80:83], v[172:175], v[210:213], v[80:83]
	v_mfma_f32_16x16x32_bf16 v[76:79], v[164:167], v[218:221], v[76:79]
	v_mfma_f32_16x16x32_bf16 v[72:75], v[172:175], v[218:221], v[72:75]
	v_mfma_f32_16x16x32_bf16 v[68:71], v[164:167], v[226:229], v[68:71]
	v_mfma_f32_16x16x32_bf16 v[64:67], v[172:175], v[226:229], v[64:67]
	s_barrier
; #define PG8_STAGE(bufoff, gbase, voff) do { _Pragma("unroll") for (int _i = 0; _i < 2; ++_i) \
;         __builtin_amdgcn_global_load_lds((const unsigned*)((const char*)(gbase) + (voff)[_i]), (PG8_LAS unsigned*)(lds + (bufoff) + ldsw + _i * 8192), 16, 0, 0); } while (0)
; #define PG8_LDA(dst, b, h) do { _Pragma("unroll") for (int m = 0; m < 4; ++m) _Pragma("unroll") for (int k = 0; k < 2; ++k) dst[m][k] = *(const PG8_LAS bf16x8*)(lds + PG8_SA(b, h) + aoff + m * 2048 + k * 1024); } while (0)
; #define PG8_LDB(dst, b, h) do { _Pragma("unroll") for (int n = 0; n < 2; ++n) _Pragma("unroll") for (int k = 0; k < 2; ++k) dst[n][k] = *(const PG8_LAS bf16x8*)(lds + PG8_SB(b, h) + boff + n * 2048 + k * 1024); } while (0)
; #define PG8_MMA(ai, bj, At, Bt) do { __builtin_amdgcn_s_setprio(1); _Pragma("unroll") for (int m = 0; m < 4; ++m) _Pragma("unroll") for (int n = 0; n < 2; ++n) _Pragma("unroll") for (int k = 0; k < 2; ++k) \
;         acc[ai][bj][m][n] = __builtin_amdgcn_mfma_f32_16x16x32_bf16(Bt[n][k], At[m][k], acc[ai][bj][m][n], 0, 0, 0); __builtin_amdgcn_s_setprio(0); } while (0)
; #define PG8_WAIT_V(n) asm volatile("s_waitcnt vmcnt(" #n ")" ::: "memory")
; #define PG8_WAIT_L(n) asm volatile("s_waitcnt lgkmcnt(" #n ")" ::: "memory")
; #define PG8_BAR __builtin_amdgcn_s_barrier()
; #define PG8_SCHED __builtin_amdgcn_sched_barrier(0)
; template <class Epi, class Sched>
; __device__ __forceinline__ void gemm_phase(PG8_LAS unsigned char* lds, const Gemm g, const Sched& S, const Epi& E) {
;     ...
;             PG8_STAGE(PG8_SB(0, 1), b2 + hstep, voffB);
;             PG8_WAIT_V(6); PG8_BAR; PG8_MMA(1, 1, At, B1); PG8_BAR;
;             PG8_LDB(B0, 1, 0); PG8_SCHED; PG8_LDA(At, 1, 0); PG8_STAGE(PG8_SA(0, 1), a2 + hstep, voffA);
;             PG8_WAIT_L(8); PG8_BAR; PG8_WAIT_L(0); PG8_MMA(0, 0, At, B0); PG8_BAR; PG8_SCHED;
;             PG8_LDB(B1, 1, 1); PG8_STAGE(PG8_SB(1, 0), b3, voffB);
;             PG8_BAR; PG8_WAIT_L(0); PG8_MMA(0, 1, At, B1); PG8_BAR;
;             PG8_LDA(At, 1, 1); PG8_STAGE(PG8_SA(1, 0), a3, voffA);
;             PG8_BAR; PG8_WAIT_L(0); PG8_MMA(1, 0, At, B0); PG8_BAR; PG8_SCHED;
	s_add_u32 s12, s26, 0x40000
	s_addc_u32 s13, s27, 0
	s_add_i32 s69, s69, s59
	v_lshl_add_u64 v[160:161], s[12:13], 0, v[138:139]
	s_mov_b32 m0, s69
	s_nop 0
	global_load_lds_dwordx4 v[160:161], off
	v_lshl_add_u64 v[160:161], s[12:13], 0, v[132:133]
	s_add_i32 m0, s69, 0x2000
	s_nop 0
	global_load_lds_dwordx4 v[160:161], off
	s_waitcnt vmcnt(6)
	s_barrier
	v_mfma_f32_16x16x32_bf16 v[28:31], v[230:233], v[176:179], v[28:31]
	v_mfma_f32_16x16x32_bf16 v[24:27], v[238:241], v[176:179], v[24:27]
	v_mfma_f32_16x16x32_bf16 v[20:23], v[230:233], v[184:187], v[20:23]
	v_mfma_f32_16x16x32_bf16 v[16:19], v[238:241], v[184:187], v[16:19]
	v_mfma_f32_16x16x32_bf16 v[12:15], v[230:233], v[214:217], v[12:15]
	v_mfma_f32_16x16x32_bf16 v[8:11], v[238:241], v[214:217], v[8:11]
	v_mfma_f32_16x16x32_bf16 v[4:7], v[230:233], v[222:225], v[4:7]
	v_mfma_f32_16x16x32_bf16 v[0:3], v[238:241], v[222:225], v[0:3]
	v_mfma_f32_16x16x32_bf16 v[28:31], v[234:237], v[180:183], v[28:31]
	v_mfma_f32_16x16x32_bf16 v[24:27], v[242:245], v[180:183], v[24:27]
	v_mfma_f32_16x16x32_bf16 v[20:23], v[234:237], v[210:213], v[20:23]
	v_mfma_f32_16x16x32_bf16 v[16:19], v[242:245], v[210:213], v[16:19]
	v_mfma_f32_16x16x32_bf16 v[12:15], v[234:237], v[218:221], v[12:15]
	v_mfma_f32_16x16x32_bf16 v[8:11], v[242:245], v[218:221], v[8:11]
	v_mfma_f32_16x16x32_bf16 v[4:7], v[234:237], v[226:229], v[4:7]
	v_mfma_f32_16x16x32_bf16 v[0:3], v[242:245], v[226:229], v[0:3]
	s_add_i32 s69, s51, 0x100
	v_add_u32_e32 v159, s69, v155
	s_barrier
	ds_read_b128 v[160:163], v159
	ds_read_b128 v[164:167], v159 offset:1024
	ds_read_b128 v[168:171], v159 offset:2048
	ds_read_b128 v[172:175], v159 offset:3072
	s_add_u32 s12, s28, 0x40000
	s_addc_u32 s13, s29, 0
	s_mov_b32 m0, s64
	v_lshl_add_u64 v[230:231], s[12:13], 0, v[128:129]
	ds_read_b128 v[176:179], v158 offset:32768
	ds_read_b128 v[180:183], v158 offset:33792
	ds_read_b128 v[184:187], v158 offset:34816
	ds_read_b128 v[210:213], v158 offset:35840
	ds_read_b128 v[214:217], v158 offset:36864
	ds_read_b128 v[218:221], v158 offset:37888
	ds_read_b128 v[222:225], v158 offset:38912
	ds_read_b128 v[226:229], v158 offset:39936
	global_load_lds_dwordx4 v[230:231], off
	v_lshl_add_u64 v[230:231], s[12:13], 0, v[130:131]
	s_mov_b32 m0, s65
	s_nop 0
	global_load_lds_dwordx4 v[230:231], off
	s_waitcnt lgkmcnt(8)
	s_barrier
	s_waitcnt lgkmcnt(0)
	s_waitcnt lgkmcnt(0)
	v_mfma_f32_16x16x32_bf16 v[124:127], v[160:163], v[176:179], v[124:127]
	v_mfma_f32_16x16x32_bf16 v[120:123], v[168:171], v[176:179], v[120:123]
	v_mfma_f32_16x16x32_bf16 v[116:119], v[160:163], v[184:187], v[116:119]
	v_mfma_f32_16x16x32_bf16 v[112:115], v[168:171], v[184:187], v[112:115]
	v_mfma_f32_16x16x32_bf16 v[108:111], v[160:163], v[214:217], v[108:111]
	v_mfma_f32_16x16x32_bf16 v[104:107], v[168:171], v[214:217], v[104:107]
	v_mfma_f32_16x16x32_bf16 v[100:103], v[160:163], v[222:225], v[100:103]
	v_mfma_f32_16x16x32_bf16 v[96:99], v[168:171], v[222:225], v[96:99]
	v_mfma_f32_16x16x32_bf16 v[124:127], v[164:167], v[180:183], v[124:127]
	v_mfma_f32_16x16x32_bf16 v[120:123], v[172:175], v[180:183], v[120:123]
	v_mfma_f32_16x16x32_bf16 v[116:119], v[164:167], v[210:213], v[116:119]
	v_mfma_f32_16x16x32_bf16 v[112:115], v[172:175], v[210:213], v[112:115]
	v_mfma_f32_16x16x32_bf16 v[108:111], v[164:167], v[218:221], v[108:111]
	v_mfma_f32_16x16x32_bf16 v[104:107], v[172:175], v[218:221], v[104:107]
	v_mfma_f32_16x16x32_bf16 v[100:103], v[164:167], v[226:229], v[100:103]
	v_mfma_f32_16x16x32_bf16 v[96:99], v[172:175], v[226:229], v[96:99]
	s_barrier
	s_add_i32 s28, s55, 0x100
	s_add_i32 s12, s69, s59
	v_add_u32_e32 v159, s28, v155
	v_lshl_add_u64 v[246:247], v[246:247], 0, s[94:95]
	s_mov_b32 m0, s12
	ds_read_b128 v[230:233], v159
	ds_read_b128 v[234:237], v159 offset:1024
	ds_read_b128 v[238:241], v159 offset:2048
	ds_read_b128 v[242:245], v159 offset:3072
	global_load_lds_dwordx4 v[246:247], off
	v_lshl_add_u64 v[246:247], v[248:249], 0, s[94:95]
	s_add_i32 m0, s12, 0x2000
	s_nop 0
	global_load_lds_dwordx4 v[246:247], off
	s_barrier
	s_waitcnt lgkmcnt(0)
	s_waitcnt lgkmcnt(0)
	v_mfma_f32_16x16x32_bf16 v[60:63], v[230:233], v[176:179], v[60:63]
	v_mfma_f32_16x16x32_bf16 v[56:59], v[238:241], v[176:179], v[56:59]
	v_mfma_f32_16x16x32_bf16 v[52:55], v[230:233], v[184:187], v[52:55]
	v_mfma_f32_16x16x32_bf16 v[48:51], v[238:241], v[184:187], v[48:51]
	v_mfma_f32_16x16x32_bf16 v[44:47], v[230:233], v[214:217], v[44:47]
	v_mfma_f32_16x16x32_bf16 v[40:43], v[238:241], v[214:217], v[40:43]
	v_mfma_f32_16x16x32_bf16 v[36:39], v[230:233], v[222:225], v[36:39]
	v_mfma_f32_16x16x32_bf16 v[32:35], v[238:241], v[222:225], v[32:35]
	v_mfma_f32_16x16x32_bf16 v[60:63], v[234:237], v[180:183], v[60:63]
	v_mfma_f32_16x16x32_bf16 v[56:59], v[242:245], v[180:183], v[56:59]
	v_mfma_f32_16x16x32_bf16 v[52:55], v[234:237], v[210:213], v[52:55]
	v_mfma_f32_16x16x32_bf16 v[48:51], v[242:245], v[210:213], v[48:51]
	v_mfma_f32_16x16x32_bf16 v[44:47], v[234:237], v[218:221], v[44:47]
	v_mfma_f32_16x16x32_bf16 v[40:43], v[242:245], v[218:221], v[40:43]
	v_mfma_f32_16x16x32_bf16 v[36:39], v[234:237], v[226:229], v[36:39]
	v_mfma_f32_16x16x32_bf16 v[32:35], v[242:245], v[226:229], v[32:35]
	s_mov_b32 m0, s66
	v_lshl_add_u64 v[246:247], v[250:251], 0, s[94:95]
	s_barrier
	ds_read_b128 v[176:179], v158 offset:49152
	ds_read_b128 v[180:183], v158 offset:50176
	ds_read_b128 v[184:187], v158 offset:51200
	ds_read_b128 v[210:213], v158 offset:52224
	ds_read_b128 v[214:217], v158 offset:53248
	ds_read_b128 v[218:221], v158 offset:54272
	ds_read_b128 v[222:225], v158 offset:55296
	ds_read_b128 v[226:229], v158 offset:56320
	global_load_lds_dwordx4 v[246:247], off
	v_lshl_add_u64 v[246:247], v[252:253], 0, s[94:95]
	s_mov_b32 m0, s67
	s_nop 0
	global_load_lds_dwordx4 v[246:247], off
	s_barrier
; #define PG8_STAGE(bufoff, gbase, voff) do { _Pragma("unroll") for (int _i = 0; _i < 2; ++_i) \
;         __builtin_amdgcn_global_load_lds((const unsigned*)((const char*)(gbase) + (voff)[_i]), (PG8_LAS unsigned*)(lds + (bufoff) + ldsw + _i * 8192), 16, 0, 0); } while (0)
; #define PG8_MMA(ai, bj, At, Bt) do { __builtin_amdgcn_s_setprio(1); _Pragma("unroll") for (int m = 0; m < 4; ++m) _Pragma("unroll") for (int n = 0; n < 2; ++n) _Pragma("unroll") for (int k = 0; k < 2; ++k) \
;         acc[ai][bj][m][n] = __builtin_amdgcn_mfma_f32_16x16x32_bf16(Bt[n][k], At[m][k], acc[ai][bj][m][n], 0, 0, 0); __builtin_amdgcn_s_setprio(0); } while (0)
; #define PG8_WAIT_V(n) asm volatile("s_waitcnt vmcnt(" #n ")" ::: "memory")
; #define PG8_WAIT_L(n) asm volatile("s_waitcnt lgkmcnt(" #n ")" ::: "memory")
; #define PG8_BAR __builtin_amdgcn_s_barrier()
; #define PG8_SCHED __builtin_amdgcn_sched_barrier(0)
; template <class Epi, class Sched>
; __device__ __forceinline__ void gemm_phase(PG8_LAS unsigned char* lds, const Gemm g, const Sched& S, const Epi& E) {
;     ...
;             PG8_BAR; PG8_WAIT_L(0); PG8_MMA(1, 0, At, B0); PG8_BAR; PG8_SCHED;
;             PG8_STAGE(PG8_SB(1, 1), b3 + hstep, voffB);
;             PG8_WAIT_V(6); PG8_BAR; PG8_MMA(1, 1, At, B1); PG8_BAR;
;         }
;         if constexpr (!Epi::AFTER_DRAIN) { E(acc, cur, wr, wc, fr, fq); S.done(cur); }
;         if (!has_next) break;
; #pragma unroll
;         for (int a = 0; a < 2; ++a)
; #pragma unroll
;             for (int b = 0; b < 2; ++b)
; #pragma unroll
;                 for (int m = 0; m < 4; ++m)
; #pragma unroll
;                     for (int n = 0; n < 2; ++n) acc[a][b][m][n] = (f32x4){0.f, 0.f, 0.f, 0.f};
;         cur = nxt; cA = nA; cB = nB; ++ui;
	s_waitcnt lgkmcnt(0)
	s_waitcnt lgkmcnt(0)
	v_mfma_f32_16x16x32_bf16 v[92:95], v[160:163], v[176:179], v[92:95]
	v_mfma_f32_16x16x32_bf16 v[88:91], v[168:171], v[176:179], v[88:91]
	v_mfma_f32_16x16x32_bf16 v[84:87], v[160:163], v[184:187], v[84:87]
	v_mfma_f32_16x16x32_bf16 v[80:83], v[168:171], v[184:187], v[80:83]
	v_mfma_f32_16x16x32_bf16 v[76:79], v[160:163], v[214:217], v[76:79]
	v_mfma_f32_16x16x32_bf16 v[72:75], v[168:171], v[214:217], v[72:75]
	v_mfma_f32_16x16x32_bf16 v[68:71], v[160:163], v[222:225], v[68:71]
	v_mfma_f32_16x16x32_bf16 v[64:67], v[168:171], v[222:225], v[64:67]
	v_mfma_f32_16x16x32_bf16 v[92:95], v[164:167], v[180:183], v[92:95]
	v_mfma_f32_16x16x32_bf16 v[88:91], v[172:175], v[180:183], v[88:91]
	v_mfma_f32_16x16x32_bf16 v[84:87], v[164:167], v[210:213], v[84:87]
	v_mfma_f32_16x16x32_bf16 v[80:83], v[172:175], v[210:213], v[80:83]
	v_mfma_f32_16x16x32_bf16 v[76:79], v[164:167], v[218:221], v[76:79]
	v_mfma_f32_16x16x32_bf16 v[72:75], v[172:175], v[218:221], v[72:75]
	v_mfma_f32_16x16x32_bf16 v[68:71], v[164:167], v[226:229], v[68:71]
	v_mfma_f32_16x16x32_bf16 v[64:67], v[172:175], v[226:229], v[64:67]
	s_barrier
	s_add_u32 s12, s26, 0x40080
	s_addc_u32 s13, s27, 0
	s_add_i32 s26, s28, s59
	v_lshl_add_u64 v[160:161], s[12:13], 0, v[138:139]
	s_mov_b32 m0, s26
	s_nop 0
	global_load_lds_dwordx4 v[160:161], off
	v_lshl_add_u64 v[160:161], s[12:13], 0, v[132:133]
	s_add_i32 m0, s26, 0x2000
	s_nop 0
	global_load_lds_dwordx4 v[160:161], off
	s_waitcnt vmcnt(6)
	s_barrier
	v_mfma_f32_16x16x32_bf16 v[28:31], v[230:233], v[176:179], v[28:31]
	v_mfma_f32_16x16x32_bf16 v[24:27], v[238:241], v[176:179], v[24:27]
	v_mfma_f32_16x16x32_bf16 v[20:23], v[230:233], v[184:187], v[20:23]
	v_mfma_f32_16x16x32_bf16 v[16:19], v[238:241], v[184:187], v[16:19]
	v_mfma_f32_16x16x32_bf16 v[12:15], v[230:233], v[214:217], v[12:15]
	v_mfma_f32_16x16x32_bf16 v[8:11], v[238:241], v[214:217], v[8:11]
	v_mfma_f32_16x16x32_bf16 v[4:7], v[230:233], v[222:225], v[4:7]
	v_mfma_f32_16x16x32_bf16 v[0:3], v[238:241], v[222:225], v[0:3]
	v_mfma_f32_16x16x32_bf16 v[28:31], v[234:237], v[180:183], v[28:31]
	v_mfma_f32_16x16x32_bf16 v[24:27], v[242:245], v[180:183], v[24:27]
	v_mfma_f32_16x16x32_bf16 v[20:23], v[234:237], v[210:213], v[20:23]
	v_mfma_f32_16x16x32_bf16 v[16:19], v[242:245], v[210:213], v[16:19]
	v_mfma_f32_16x16x32_bf16 v[12:15], v[234:237], v[218:221], v[12:15]
	v_mfma_f32_16x16x32_bf16 v[8:11], v[242:245], v[218:221], v[8:11]
	v_mfma_f32_16x16x32_bf16 v[4:7], v[234:237], v[226:229], v[4:7]
	v_mfma_f32_16x16x32_bf16 v[0:3], v[242:245], v[226:229], v[0:3]
	s_add_i32 vcc_hi, vcc_hi, 2
	s_add_u32 s24, s24, 0x100
	s_addc_u32 s25, s25, 0
	s_cmp_gt_u32 vcc_hi, 13
	s_barrier
	s_cbranch_scc0 .LBB0_803
	s_add_u32 s24, s83, 0xffffff00
	s_addc_u32 s25, s84, -1
	s_andn2_b64 vcc, exec, s[0:1]
	s_cbranch_vccnz .LBB0_806
	v_mov_b32_e32 v0, 0
	s_mov_b32 s34, s6
	s_mov_b32 s16, s18
	s_mov_b64 s[4:5], s[22:23]
	s_mov_b32 s68, s82
	v_mov_b32_e32 v1, v0
	v_mov_b32_e32 v2, v0
	v_mov_b32_e32 v3, v0
	v_mov_b32_e32 v4, v0
	v_mov_b32_e32 v5, v0
	v_mov_b32_e32 v6, v0
	v_mov_b32_e32 v7, v0
	v_mov_b32_e32 v8, v0
	v_mov_b32_e32 v9, v0
	v_mov_b32_e32 v10, v0
	v_mov_b32_e32 v11, v0
	v_mov_b32_e32 v12, v0
	v_mov_b32_e32 v13, v0
	v_mov_b32_e32 v14, v0
	v_mov_b32_e32 v15, v0
	v_mov_b32_e32 v16, v0
	v_mov_b32_e32 v17, v0
	v_mov_b32_e32 v18, v0
	v_mov_b32_e32 v19, v0
	v_mov_b32_e32 v20, v0
	v_mov_b32_e32 v21, v0
	v_mov_b32_e32 v22, v0
	v_mov_b32_e32 v23, v0
	v_mov_b32_e32 v24, v0
	v_mov_b32_e32 v25, v0
	v_mov_b32_e32 v26, v0
	v_mov_b32_e32 v27, v0
	v_mov_b32_e32 v28, v0
	v_mov_b32_e32 v29, v0
	v_mov_b32_e32 v30, v0
	v_mov_b32_e32 v31, v0
	v_mov_b32_e32 v64, v0
	v_mov_b32_e32 v65, v0
	v_mov_b32_e32 v66, v0
	v_mov_b32_e32 v67, v0
	v_mov_b32_e32 v68, v0
	v_mov_b32_e32 v69, v0
	v_mov_b32_e32 v70, v0
	v_mov_b32_e32 v71, v0
	v_mov_b32_e32 v72, v0
	v_mov_b32_e32 v73, v0
	v_mov_b32_e32 v74, v0
	v_mov_b32_e32 v75, v0
	v_mov_b32_e32 v76, v0
	v_mov_b32_e32 v77, v0
	v_mov_b32_e32 v78, v0
	v_mov_b32_e32 v79, v0
	v_mov_b32_e32 v80, v0
	v_mov_b32_e32 v81, v0
	v_mov_b32_e32 v82, v0
	v_mov_b32_e32 v83, v0
	v_mov_b32_e32 v84, v0
	v_mov_b32_e32 v85, v0
	v_mov_b32_e32 v86, v0
	v_mov_b32_e32 v87, v0
	v_mov_b32_e32 v88, v0
	v_mov_b32_e32 v89, v0
	v_mov_b32_e32 v90, v0
	v_mov_b32_e32 v91, v0
	v_mov_b32_e32 v92, v0
	v_mov_b32_e32 v93, v0
	v_mov_b32_e32 v94, v0
	v_mov_b32_e32 v95, v0
	v_mov_b32_e32 v32, v0
	v_mov_b32_e32 v33, v0
	v_mov_b32_e32 v34, v0
	v_mov_b32_e32 v35, v0
	v_mov_b32_e32 v36, v0
	v_mov_b32_e32 v37, v0
	v_mov_b32_e32 v38, v0
	v_mov_b32_e32 v39, v0
	v_mov_b32_e32 v40, v0
	v_mov_b32_e32 v41, v0
	v_mov_b32_e32 v42, v0
	v_mov_b32_e32 v43, v0
	v_mov_b32_e32 v44, v0
	v_mov_b32_e32 v45, v0
	v_mov_b32_e32 v46, v0
	v_mov_b32_e32 v47, v0
	v_mov_b32_e32 v48, v0
	v_mov_b32_e32 v49, v0
	v_mov_b32_e32 v50, v0
	v_mov_b32_e32 v51, v0
	v_mov_b32_e32 v52, v0
	v_mov_b32_e32 v53, v0
	v_mov_b32_e32 v54, v0
	v_mov_b32_e32 v55, v0
	v_mov_b32_e32 v56, v0
	v_mov_b32_e32 v57, v0
	v_mov_b32_e32 v58, v0
	v_mov_b32_e32 v59, v0
	v_mov_b32_e32 v60, v0
	v_mov_b32_e32 v61, v0
	v_mov_b32_e32 v62, v0
	v_mov_b32_e32 v63, v0
	v_mov_b32_e32 v96, v0
	v_mov_b32_e32 v97, v0
	v_mov_b32_e32 v98, v0
	v_mov_b32_e32 v99, v0
	v_mov_b32_e32 v100, v0
	v_mov_b32_e32 v101, v0
	v_mov_b32_e32 v102, v0
	v_mov_b32_e32 v103, v0
	v_mov_b32_e32 v104, v0
	v_mov_b32_e32 v105, v0
	v_mov_b32_e32 v106, v0
	v_mov_b32_e32 v107, v0
	v_mov_b32_e32 v108, v0
	v_mov_b32_e32 v109, v0
	v_mov_b32_e32 v110, v0
	v_mov_b32_e32 v111, v0
	v_mov_b32_e32 v112, v0
	v_mov_b32_e32 v113, v0
	v_mov_b32_e32 v114, v0
	v_mov_b32_e32 v115, v0
	v_mov_b32_e32 v116, v0
	v_mov_b32_e32 v117, v0
	v_mov_b32_e32 v118, v0
	v_mov_b32_e32 v119, v0
	v_mov_b32_e32 v120, v0
	v_mov_b32_e32 v121, v0
	v_mov_b32_e32 v122, v0
	v_mov_b32_e32 v123, v0
	v_mov_b32_e32 v124, v0
	v_mov_b32_e32 v125, v0
	v_mov_b32_e32 v126, v0
	v_mov_b32_e32 v127, v0
	s_mov_b32 s91, 0x12000
	s_andn2_b64 vcc, exec, s[2:3]
	s_cbranch_vccnz .LBB0_807
	s_branch .LBB0_808

; #define PG8_STAGE(bufoff, gbase, voff) do { _Pragma("unroll") for (int _i = 0; _i < 2; ++_i) \
;         __builtin_amdgcn_global_load_lds((const unsigned*)((const char*)(gbase) + (voff)[_i]), (PG8_LAS unsigned*)(lds + (bufoff) + ldsw + _i * 8192), 16, 0, 0); } while (0)
; #define PG8_LDA(dst, b, h) do { _Pragma("unroll") for (int m = 0; m < 4; ++m) _Pragma("unroll") for (int k = 0; k < 2; ++k) dst[m][k] = *(const PG8_LAS bf16x8*)(lds + PG8_SA(b, h) + aoff + m * 2048 + k * 1024); } while (0)
; #define PG8_LDB(dst, b, h) do { _Pragma("unroll") for (int n = 0; n < 2; ++n) _Pragma("unroll") for (int k = 0; k < 2; ++k) dst[n][k] = *(const PG8_LAS bf16x8*)(lds + PG8_SB(b, h) + boff + n * 2048 + k * 1024); } while (0)
; #define PG8_MMA(ai, bj, At, Bt) do { __builtin_amdgcn_s_setprio(1); _Pragma("unroll") for (int m = 0; m < 4; ++m) _Pragma("unroll") for (int n = 0; n < 2; ++n) _Pragma("unroll") for (int k = 0; k < 2; ++k) \
;         acc[ai][bj][m][n] = __builtin_amdgcn_mfma_f32_16x16x32_bf16(Bt[n][k], At[m][k], acc[ai][bj][m][n], 0, 0, 0); __builtin_amdgcn_s_setprio(0); } while (0)
; #define PG8_WAIT_L(n) asm volatile("s_waitcnt lgkmcnt(" #n ")" ::: "memory")
; #define PG8_BAR __builtin_amdgcn_s_barrier()
; #define PG8_SCHED __builtin_amdgcn_sched_barrier(0)
; template <class Epi, class Sched>
; __device__ __forceinline__ void gemm_phase(PG8_LAS unsigned char* lds, const Gemm g, const Sched& S, const Epi& E) {
;     ...
;         for (int t = 0; t < nt; t += 2) {
;             const bool last = (t == nt - 2);
;             const char* a1 = cA + (size_t)(t + 1) * kstep;
;             const char* a2 = last ? nA : cA + (size_t)(t + 2) * kstep; const char* b2 = last ? nB : cB + (size_t)(t + 2) * kstep;
;             const char* a3 = a2 + kstep; const char* b3 = b2 + kstep;
;             if (last && has_next) S.a_ready(nxt);
;             PG8_LDB(B0, 0, 0); PG8_SCHED; PG8_LDA(At, 0, 0); PG8_STAGE(PG8_SA(1, 1), a1 + hstep, voffA);
;             PG8_WAIT_L(8); PG8_BAR; PG8_WAIT_L(0); PG8_MMA(0, 0, At, B0); PG8_BAR; PG8_SCHED;
;             PG8_LDB(B1, 0, 1); PG8_STAGE(PG8_SB(0, 0), b2, voffB);
;             PG8_BAR; PG8_WAIT_L(0); PG8_MMA(0, 1, At, B1); PG8_BAR;
;             PG8_LDA(At, 0, 1); PG8_STAGE(PG8_SA(0, 0), a2, voffA);
;             PG8_BAR; PG8_WAIT_L(0); PG8_MMA(1, 0, At, B0); PG8_BAR; PG8_SCHED;
.LBB0_997:
	s_add_u32 s12, s18, 0xfffc0080
	s_addc_u32 s13, s19, -1
	s_add_i32 s61, s46, 0x100
	v_add_u32_e32 v166, s61, v155
	ds_read_b128 v[150:153], v166
	ds_read_b128 v[158:161], v166 offset:1024
	ds_read_b128 v[162:165], v166 offset:2048
	ds_read_b128 v[166:169], v166 offset:3072
	s_cmp_eq_u32 s60, 12
	s_cselect_b32 s23, s7, s13
	s_cselect_b32 s22, s40, s12
	s_cselect_b32 s21, s5, s59
	s_cselect_b32 s20, s41, s58
	v_lshl_add_u64 v[186:187], s[18:19], 0, v[134:135]
	s_add_i32 m0, s17, 0xc000
	ds_read_b128 v[170:173], v157
	ds_read_b128 v[174:177], v157 offset:1024
	ds_read_b128 v[178:181], v157 offset:2048
	ds_read_b128 v[182:185], v157 offset:3072
	ds_read_b128 v[210:213], v157 offset:4096
	ds_read_b128 v[214:217], v157 offset:5120
	ds_read_b128 v[218:221], v157 offset:6144
	ds_read_b128 v[222:225], v157 offset:7168
	global_load_lds_dwordx4 v[186:187], off
	v_lshl_add_u64 v[186:187], s[18:19], 0, v[148:149]
	s_add_i32 m0, s17, 0xe000
	s_nop 0
	global_load_lds_dwordx4 v[186:187], off
	s_waitcnt lgkmcnt(8)
	s_barrier
	s_waitcnt lgkmcnt(0)
	s_waitcnt lgkmcnt(0)
	v_mfma_f32_16x16x32_bf16 v[124:127], v[150:153], v[170:173], v[124:127]
	v_mfma_f32_16x16x32_bf16 v[116:119], v[162:165], v[170:173], v[116:119]
	v_mfma_f32_16x16x32_bf16 v[108:111], v[150:153], v[178:181], v[108:111]
	v_mfma_f32_16x16x32_bf16 v[100:103], v[162:165], v[178:181], v[100:103]
	v_mfma_f32_16x16x32_bf16 v[92:95], v[150:153], v[210:213], v[92:95]
	v_mfma_f32_16x16x32_bf16 v[84:87], v[162:165], v[210:213], v[84:87]
	v_mfma_f32_16x16x32_bf16 v[76:79], v[150:153], v[218:221], v[76:79]
	v_mfma_f32_16x16x32_bf16 v[68:71], v[162:165], v[218:221], v[68:71]
	v_mfma_f32_16x16x32_bf16 v[124:127], v[158:161], v[174:177], v[124:127]
	v_mfma_f32_16x16x32_bf16 v[116:119], v[166:169], v[174:177], v[116:119]
	v_mfma_f32_16x16x32_bf16 v[108:111], v[158:161], v[182:185], v[108:111]
	v_mfma_f32_16x16x32_bf16 v[100:103], v[166:169], v[182:185], v[100:103]
	v_mfma_f32_16x16x32_bf16 v[92:95], v[158:161], v[214:217], v[92:95]
	v_mfma_f32_16x16x32_bf16 v[84:87], v[166:169], v[214:217], v[84:87]
	v_mfma_f32_16x16x32_bf16 v[76:79], v[158:161], v[222:225], v[76:79]
	v_mfma_f32_16x16x32_bf16 v[68:71], v[166:169], v[222:225], v[68:71]
	s_barrier
	s_add_i32 s62, s48, 0x100
	v_add_u32_e32 v186, s62, v155
	s_add_i32 s12, s61, s31
	ds_read_b128 v[226:229], v186
	ds_read_b128 v[230:233], v186 offset:1024
	ds_read_b128 v[234:237], v186 offset:2048
	ds_read_b128 v[238:241], v186 offset:3072
	v_lshl_add_u64 v[186:187], s[20:21], 0, v[138:139]
	s_mov_b32 m0, s12
	v_lshl_add_u64 v[242:243], s[20:21], 0, v[132:133]
	global_load_lds_dwordx4 v[186:187], off
	s_add_i32 m0, s12, 0x2000
	s_nop 0
	global_load_lds_dwordx4 v[242:243], off
	s_barrier
	s_waitcnt lgkmcnt(0)
	s_waitcnt lgkmcnt(0)
	v_mfma_f32_16x16x32_bf16 v[120:123], v[226:229], v[170:173], v[120:123]
	v_mfma_f32_16x16x32_bf16 v[112:115], v[234:237], v[170:173], v[112:115]
	v_mfma_f32_16x16x32_bf16 v[104:107], v[226:229], v[178:181], v[104:107]
	v_mfma_f32_16x16x32_bf16 v[96:99], v[234:237], v[178:181], v[96:99]
	v_mfma_f32_16x16x32_bf16 v[88:91], v[226:229], v[210:213], v[88:91]
	v_mfma_f32_16x16x32_bf16 v[80:83], v[234:237], v[210:213], v[80:83]
	v_mfma_f32_16x16x32_bf16 v[72:75], v[226:229], v[218:221], v[72:75]
	v_mfma_f32_16x16x32_bf16 v[64:67], v[234:237], v[218:221], v[64:67]
	v_mfma_f32_16x16x32_bf16 v[120:123], v[230:233], v[174:177], v[120:123]
	v_mfma_f32_16x16x32_bf16 v[112:115], v[238:241], v[174:177], v[112:115]
	v_mfma_f32_16x16x32_bf16 v[104:107], v[230:233], v[182:185], v[104:107]
	v_mfma_f32_16x16x32_bf16 v[96:99], v[238:241], v[182:185], v[96:99]
	v_mfma_f32_16x16x32_bf16 v[88:91], v[230:233], v[214:217], v[88:91]
	v_mfma_f32_16x16x32_bf16 v[80:83], v[238:241], v[214:217], v[80:83]
	v_mfma_f32_16x16x32_bf16 v[72:75], v[230:233], v[222:225], v[72:75]
	v_mfma_f32_16x16x32_bf16 v[64:67], v[238:241], v[222:225], v[64:67]
	s_mov_b32 m0, s17
	v_lshl_add_u64 v[244:245], s[22:23], 0, v[128:129]
	s_barrier
	ds_read_b128 v[170:173], v157 offset:16384
	ds_read_b128 v[174:177], v157 offset:17408
	ds_read_b128 v[178:181], v157 offset:18432
	ds_read_b128 v[182:185], v157 offset:19456
	ds_read_b128 v[210:213], v157 offset:20480
	ds_read_b128 v[214:217], v157 offset:21504
	ds_read_b128 v[218:221], v157 offset:22528
	ds_read_b128 v[222:225], v157 offset:23552
	global_load_lds_dwordx4 v[244:245], off
	v_lshl_add_u64 v[246:247], s[22:23], 0, v[130:131]
	s_mov_b32 m0, s33
	s_nop 0
	global_load_lds_dwordx4 v[246:247], off
	s_barrier
	s_waitcnt lgkmcnt(0)
	s_waitcnt lgkmcnt(0)
	v_mfma_f32_16x16x32_bf16 v[60:63], v[150:153], v[170:173], v[60:63]
	v_mfma_f32_16x16x32_bf16 v[52:55], v[162:165], v[170:173], v[52:55]
	v_mfma_f32_16x16x32_bf16 v[44:47], v[150:153], v[178:181], v[44:47]
	v_mfma_f32_16x16x32_bf16 v[36:39], v[162:165], v[178:181], v[36:39]
	v_mfma_f32_16x16x32_bf16 v[28:31], v[150:153], v[210:213], v[28:31]
	v_mfma_f32_16x16x32_bf16 v[20:23], v[162:165], v[210:213], v[20:23]
	v_mfma_f32_16x16x32_bf16 v[12:15], v[150:153], v[218:221], v[12:15]
	v_mfma_f32_16x16x32_bf16 v[4:7], v[162:165], v[218:221], v[4:7]
	v_mfma_f32_16x16x32_bf16 v[60:63], v[158:161], v[174:177], v[60:63]
	v_mfma_f32_16x16x32_bf16 v[52:55], v[166:169], v[174:177], v[52:55]
	v_mfma_f32_16x16x32_bf16 v[44:47], v[158:161], v[182:185], v[44:47]
	v_mfma_f32_16x16x32_bf16 v[36:39], v[166:169], v[182:185], v[36:39]
	v_mfma_f32_16x16x32_bf16 v[28:31], v[158:161], v[214:217], v[28:31]
	v_mfma_f32_16x16x32_bf16 v[20:23], v[166:169], v[214:217], v[20:23]
	v_mfma_f32_16x16x32_bf16 v[12:15], v[158:161], v[222:225], v[12:15]
	v_mfma_f32_16x16x32_bf16 v[4:7], v[166:169], v[222:225], v[4:7]
	s_barrier
; #define PG8_STAGE(bufoff, gbase, voff) do { _Pragma("unroll") for (int _i = 0; _i < 2; ++_i) \
;         __builtin_amdgcn_global_load_lds((const unsigned*)((const char*)(gbase) + (voff)[_i]), (PG8_LAS unsigned*)(lds + (bufoff) + ldsw + _i * 8192), 16, 0, 0); } while (0)
; #define PG8_LDA(dst, b, h) do { _Pragma("unroll") for (int m = 0; m < 4; ++m) _Pragma("unroll") for (int k = 0; k < 2; ++k) dst[m][k] = *(const PG8_LAS bf16x8*)(lds + PG8_SA(b, h) + aoff + m * 2048 + k * 1024); } while (0)
; #define PG8_LDB(dst, b, h) do { _Pragma("unroll") for (int n = 0; n < 2; ++n) _Pragma("unroll") for (int k = 0; k < 2; ++k) dst[n][k] = *(const PG8_LAS bf16x8*)(lds + PG8_SB(b, h) + boff + n * 2048 + k * 1024); } while (0)
; #define PG8_MMA(ai, bj, At, Bt) do { __builtin_amdgcn_s_setprio(1); _Pragma("unroll") for (int m = 0; m < 4; ++m) _Pragma("unroll") for (int n = 0; n < 2; ++n) _Pragma("unroll") for (int k = 0; k < 2; ++k) \
;         acc[ai][bj][m][n] = __builtin_amdgcn_mfma_f32_16x16x32_bf16(Bt[n][k], At[m][k], acc[ai][bj][m][n], 0, 0, 0); __builtin_amdgcn_s_setprio(0); } while (0)
; #define PG8_WAIT_V(n) asm volatile("s_waitcnt vmcnt(" #n ")" ::: "memory")
; #define PG8_WAIT_L(n) asm volatile("s_waitcnt lgkmcnt(" #n ")" ::: "memory")
; #define PG8_BAR __builtin_amdgcn_s_barrier()
; #define PG8_SCHED __builtin_amdgcn_sched_barrier(0)
; template <class Epi, class Sched>
; __device__ __forceinline__ void gemm_phase(PG8_LAS unsigned char* lds, const Gemm g, const Sched& S, const Epi& E) {
;     ...
;             PG8_STAGE(PG8_SB(0, 1), b2 + hstep, voffB);
;             PG8_WAIT_V(6); PG8_BAR; PG8_MMA(1, 1, At, B1); PG8_BAR;
;             PG8_LDB(B0, 1, 0); PG8_SCHED; PG8_LDA(At, 1, 0); PG8_STAGE(PG8_SA(0, 1), a2 + hstep, voffA);
;             PG8_WAIT_L(8); PG8_BAR; PG8_WAIT_L(0); PG8_MMA(0, 0, At, B0); PG8_BAR; PG8_SCHED;
;             PG8_LDB(B1, 1, 1); PG8_STAGE(PG8_SB(1, 0), b3, voffB);
;             PG8_BAR; PG8_WAIT_L(0); PG8_MMA(0, 1, At, B1); PG8_BAR;
;             PG8_LDA(At, 1, 1); PG8_STAGE(PG8_SA(1, 0), a3, voffA);
;             PG8_BAR; PG8_WAIT_L(0); PG8_MMA(1, 0, At, B0); PG8_BAR; PG8_SCHED;
	s_add_u32 s12, s20, 0x40000
	s_addc_u32 s13, s21, 0
	s_add_i32 s61, s62, s31
	v_lshl_add_u64 v[150:151], s[12:13], 0, v[138:139]
	s_mov_b32 m0, s61
	s_nop 0
	global_load_lds_dwordx4 v[150:151], off
	v_lshl_add_u64 v[150:151], s[12:13], 0, v[132:133]
	s_add_i32 m0, s61, 0x2000
	s_nop 0
	global_load_lds_dwordx4 v[150:151], off
	s_waitcnt vmcnt(6)
	s_barrier
	v_mfma_f32_16x16x32_bf16 v[56:59], v[226:229], v[170:173], v[56:59]
	v_mfma_f32_16x16x32_bf16 v[48:51], v[234:237], v[170:173], v[48:51]
	v_mfma_f32_16x16x32_bf16 v[40:43], v[226:229], v[178:181], v[40:43]
	v_mfma_f32_16x16x32_bf16 v[32:35], v[234:237], v[178:181], v[32:35]
	v_mfma_f32_16x16x32_bf16 v[24:27], v[226:229], v[210:213], v[24:27]
	v_mfma_f32_16x16x32_bf16 v[16:19], v[234:237], v[210:213], v[16:19]
	v_mfma_f32_16x16x32_bf16 v[8:11], v[226:229], v[218:221], v[8:11]
	v_mfma_f32_16x16x32_bf16 v[0:3], v[234:237], v[218:221], v[0:3]
	v_mfma_f32_16x16x32_bf16 v[56:59], v[230:233], v[174:177], v[56:59]
	v_mfma_f32_16x16x32_bf16 v[48:51], v[238:241], v[174:177], v[48:51]
	v_mfma_f32_16x16x32_bf16 v[40:43], v[230:233], v[182:185], v[40:43]
	v_mfma_f32_16x16x32_bf16 v[32:35], v[238:241], v[182:185], v[32:35]
	v_mfma_f32_16x16x32_bf16 v[24:27], v[230:233], v[214:217], v[24:27]
	v_mfma_f32_16x16x32_bf16 v[16:19], v[238:241], v[214:217], v[16:19]
	v_mfma_f32_16x16x32_bf16 v[8:11], v[230:233], v[222:225], v[8:11]
	v_mfma_f32_16x16x32_bf16 v[0:3], v[238:241], v[222:225], v[0:3]
	s_add_i32 s61, s51, 0x100
	v_add_u32_e32 v166, s61, v155
	s_barrier
	ds_read_b128 v[150:153], v166
	ds_read_b128 v[158:161], v166 offset:1024
	ds_read_b128 v[162:165], v166 offset:2048
	ds_read_b128 v[166:169], v166 offset:3072
	s_add_u32 s12, s22, 0x40000
	s_addc_u32 s13, s23, 0
	s_mov_b32 m0, s34
	v_lshl_add_u64 v[226:227], s[12:13], 0, v[128:129]
	ds_read_b128 v[170:173], v157 offset:32768
	ds_read_b128 v[174:177], v157 offset:33792
	ds_read_b128 v[178:181], v157 offset:34816
	ds_read_b128 v[182:185], v157 offset:35840
	ds_read_b128 v[210:213], v157 offset:36864
	ds_read_b128 v[214:217], v157 offset:37888
	ds_read_b128 v[218:221], v157 offset:38912
	ds_read_b128 v[222:225], v157 offset:39936
	global_load_lds_dwordx4 v[226:227], off
	v_lshl_add_u64 v[226:227], s[12:13], 0, v[130:131]
	s_mov_b32 m0, s35
	s_nop 0
	global_load_lds_dwordx4 v[226:227], off
	s_waitcnt lgkmcnt(8)
	s_barrier
	s_waitcnt lgkmcnt(0)
	s_waitcnt lgkmcnt(0)
	v_mfma_f32_16x16x32_bf16 v[124:127], v[150:153], v[170:173], v[124:127]
	v_mfma_f32_16x16x32_bf16 v[116:119], v[162:165], v[170:173], v[116:119]
	v_mfma_f32_16x16x32_bf16 v[108:111], v[150:153], v[178:181], v[108:111]
	v_mfma_f32_16x16x32_bf16 v[100:103], v[162:165], v[178:181], v[100:103]
	v_mfma_f32_16x16x32_bf16 v[92:95], v[150:153], v[210:213], v[92:95]
	v_mfma_f32_16x16x32_bf16 v[84:87], v[162:165], v[210:213], v[84:87]
	v_mfma_f32_16x16x32_bf16 v[76:79], v[150:153], v[218:221], v[76:79]
	v_mfma_f32_16x16x32_bf16 v[68:71], v[162:165], v[218:221], v[68:71]
	v_mfma_f32_16x16x32_bf16 v[124:127], v[158:161], v[174:177], v[124:127]
	v_mfma_f32_16x16x32_bf16 v[116:119], v[166:169], v[174:177], v[116:119]
	v_mfma_f32_16x16x32_bf16 v[108:111], v[158:161], v[182:185], v[108:111]
	v_mfma_f32_16x16x32_bf16 v[100:103], v[166:169], v[182:185], v[100:103]
	v_mfma_f32_16x16x32_bf16 v[92:95], v[158:161], v[214:217], v[92:95]
	v_mfma_f32_16x16x32_bf16 v[84:87], v[166:169], v[214:217], v[84:87]
	v_mfma_f32_16x16x32_bf16 v[76:79], v[158:161], v[222:225], v[76:79]
	v_mfma_f32_16x16x32_bf16 v[68:71], v[166:169], v[222:225], v[68:71]
	s_barrier
	s_add_i32 s22, s55, 0x100
	s_add_i32 s12, s61, s31
	v_add_u32_e32 v209, s22, v155
	v_lshl_add_u64 v[186:187], v[186:187], 0, s[94:95]
	s_mov_b32 m0, s12
	ds_read_b128 v[226:229], v209
	ds_read_b128 v[230:233], v209 offset:1024
	ds_read_b128 v[234:237], v209 offset:2048
	ds_read_b128 v[238:241], v209 offset:3072
	global_load_lds_dwordx4 v[186:187], off
	v_lshl_add_u64 v[186:187], v[242:243], 0, s[94:95]
	s_add_i32 m0, s12, 0x2000
	s_nop 0
	global_load_lds_dwordx4 v[186:187], off
	s_barrier
	s_waitcnt lgkmcnt(0)
	s_waitcnt lgkmcnt(0)
	v_mfma_f32_16x16x32_bf16 v[120:123], v[226:229], v[170:173], v[120:123]
	v_mfma_f32_16x16x32_bf16 v[112:115], v[234:237], v[170:173], v[112:115]
	v_mfma_f32_16x16x32_bf16 v[104:107], v[226:229], v[178:181], v[104:107]
	v_mfma_f32_16x16x32_bf16 v[96:99], v[234:237], v[178:181], v[96:99]
	v_mfma_f32_16x16x32_bf16 v[88:91], v[226:229], v[210:213], v[88:91]
	v_mfma_f32_16x16x32_bf16 v[80:83], v[234:237], v[210:213], v[80:83]
	v_mfma_f32_16x16x32_bf16 v[72:75], v[226:229], v[218:221], v[72:75]
	v_mfma_f32_16x16x32_bf16 v[64:67], v[234:237], v[218:221], v[64:67]
	v_mfma_f32_16x16x32_bf16 v[120:123], v[230:233], v[174:177], v[120:123]
	v_mfma_f32_16x16x32_bf16 v[112:115], v[238:241], v[174:177], v[112:115]
	v_mfma_f32_16x16x32_bf16 v[104:107], v[230:233], v[182:185], v[104:107]
	v_mfma_f32_16x16x32_bf16 v[96:99], v[238:241], v[182:185], v[96:99]
	v_mfma_f32_16x16x32_bf16 v[88:91], v[230:233], v[214:217], v[88:91]
	v_mfma_f32_16x16x32_bf16 v[80:83], v[238:241], v[214:217], v[80:83]
	v_mfma_f32_16x16x32_bf16 v[72:75], v[230:233], v[222:225], v[72:75]
	v_mfma_f32_16x16x32_bf16 v[64:67], v[238:241], v[222:225], v[64:67]
	s_mov_b32 m0, s36
	v_lshl_add_u64 v[186:187], v[244:245], 0, s[94:95]
	s_barrier
	ds_read_b128 v[170:173], v157 offset:49152
	ds_read_b128 v[174:177], v157 offset:50176
	ds_read_b128 v[178:181], v157 offset:51200
	ds_read_b128 v[182:185], v157 offset:52224
	ds_read_b128 v[210:213], v157 offset:53248
	ds_read_b128 v[214:217], v157 offset:54272
	ds_read_b128 v[218:221], v157 offset:55296
	ds_read_b128 v[222:225], v157 offset:56320
	global_load_lds_dwordx4 v[186:187], off
	v_lshl_add_u64 v[186:187], v[246:247], 0, s[94:95]
	s_mov_b32 m0, s37
	s_nop 0
	global_load_lds_dwordx4 v[186:187], off
	s_barrier
;   __device__ __forceinline__ bf16* y() const { unsigned o_ = (unsigned)(OFF_y); asm volatile("" : "+s"(o_)); return (bf16*)(ws + o_); }
; __device__ __forceinline__ unsigned pk2(float a, float b) { unsigned r; asm("v_cvt_pk_bf16_f32 %0, %1, %2" : "=v"(r) : "v"(a), "v"(b)); return r; }
; __device__ __forceinline__ float silu(float x) { return x * sigm(x); }
; #define PG8_STAGE(bufoff, gbase, voff) do { _Pragma("unroll") for (int _i = 0; _i < 2; ++_i) \
;         __builtin_amdgcn_global_load_lds((const unsigned*)((const char*)(gbase) + (voff)[_i]), (PG8_LAS unsigned*)(lds + (bufoff) + ldsw + _i * 8192), 16, 0, 0); } while (0)
; #define PG8_MMA(ai, bj, At, Bt) do { __builtin_amdgcn_s_setprio(1); _Pragma("unroll") for (int m = 0; m < 4; ++m) _Pragma("unroll") for (int n = 0; n < 2; ++n) _Pragma("unroll") for (int k = 0; k < 2; ++k) \
;         acc[ai][bj][m][n] = __builtin_amdgcn_mfma_f32_16x16x32_bf16(Bt[n][k], At[m][k], acc[ai][bj][m][n], 0, 0, 0); __builtin_amdgcn_s_setprio(0); } while (0)
; #define PG8_WAIT_V(n) asm volatile("s_waitcnt vmcnt(" #n ")" ::: "memory")
; #define PG8_WAIT_L(n) asm volatile("s_waitcnt lgkmcnt(" #n ")" ::: "memory")
; #define PG8_BAR __builtin_amdgcn_s_barrier()
; #define PG8_SCHED __builtin_amdgcn_sched_barrier(0)
; template <class Epi, class Sched>
; __device__ __forceinline__ void gemm_phase(PG8_LAS unsigned char* lds, const Gemm g, const Sched& S, const Epi& E) {
;     ...
;             PG8_BAR; PG8_WAIT_L(0); PG8_MMA(1, 0, At, B0); PG8_BAR; PG8_SCHED;
;             PG8_STAGE(PG8_SB(1, 1), b3 + hstep, voffB);
;             PG8_WAIT_V(6); PG8_BAR; PG8_MMA(1, 1, At, B1); PG8_BAR;
;         }
;   __device__ __forceinline__ void operator()(const f32x4 (&acc)[2][2][4][2], const pg8::Unit& u, int wr, int wc, int fr, int fq) const {
;     ...
;         const f32x4 g0 = acc[ai][0][m][0], g1 = acc[ai][0][m][1], u0 = acc[ai][1][m][0], u1 = acc[ai][1][m][1];
;         uint4 o;
;         o.x = pk2(silu(g0[0]) * u0[0], silu(g0[1]) * u0[1]); o.y = pk2(silu(g0[2]) * u0[2], silu(g0[3]) * u0[3]);
;         o.z = pk2(silu(g1[0]) * u1[0], silu(g1[1]) * u1[1]); o.w = pk2(silu(g1[2]) * u1[2], silu(g1[3]) * u1[3]);
;         *(uint4*)rowp = o;
	s_waitcnt lgkmcnt(0)
	s_waitcnt lgkmcnt(0)
	v_mfma_f32_16x16x32_bf16 v[60:63], v[150:153], v[170:173], v[60:63]
	v_mfma_f32_16x16x32_bf16 v[52:55], v[162:165], v[170:173], v[52:55]
	v_mfma_f32_16x16x32_bf16 v[44:47], v[150:153], v[178:181], v[44:47]
	v_mfma_f32_16x16x32_bf16 v[36:39], v[162:165], v[178:181], v[36:39]
	v_mfma_f32_16x16x32_bf16 v[28:31], v[150:153], v[210:213], v[28:31]
	v_mfma_f32_16x16x32_bf16 v[20:23], v[162:165], v[210:213], v[20:23]
	v_mfma_f32_16x16x32_bf16 v[12:15], v[150:153], v[218:221], v[12:15]
	v_mfma_f32_16x16x32_bf16 v[4:7], v[162:165], v[218:221], v[4:7]
	v_mfma_f32_16x16x32_bf16 v[60:63], v[158:161], v[174:177], v[60:63]
	v_mfma_f32_16x16x32_bf16 v[52:55], v[166:169], v[174:177], v[52:55]
	v_mfma_f32_16x16x32_bf16 v[44:47], v[158:161], v[182:185], v[44:47]
	v_mfma_f32_16x16x32_bf16 v[36:39], v[166:169], v[182:185], v[36:39]
	v_mfma_f32_16x16x32_bf16 v[28:31], v[158:161], v[214:217], v[28:31]
	v_mfma_f32_16x16x32_bf16 v[20:23], v[166:169], v[214:217], v[20:23]
	v_mfma_f32_16x16x32_bf16 v[12:15], v[158:161], v[222:225], v[12:15]
	v_mfma_f32_16x16x32_bf16 v[4:7], v[166:169], v[222:225], v[4:7]
	s_barrier
	s_add_u32 s12, s20, 0x40080
	s_addc_u32 s13, s21, 0
	s_add_i32 s20, s22, s31
	v_lshl_add_u64 v[150:151], s[12:13], 0, v[138:139]
	s_mov_b32 m0, s20
	s_nop 0
	global_load_lds_dwordx4 v[150:151], off
	v_lshl_add_u64 v[150:151], s[12:13], 0, v[132:133]
	s_add_i32 m0, s20, 0x2000
	s_nop 0
	global_load_lds_dwordx4 v[150:151], off
	s_waitcnt vmcnt(6)
	s_barrier
	v_mfma_f32_16x16x32_bf16 v[56:59], v[226:229], v[170:173], v[56:59]
	v_mfma_f32_16x16x32_bf16 v[48:51], v[234:237], v[170:173], v[48:51]
	v_mfma_f32_16x16x32_bf16 v[40:43], v[226:229], v[178:181], v[40:43]
	v_mfma_f32_16x16x32_bf16 v[32:35], v[234:237], v[178:181], v[32:35]
	v_mfma_f32_16x16x32_bf16 v[24:27], v[226:229], v[210:213], v[24:27]
	v_mfma_f32_16x16x32_bf16 v[16:19], v[234:237], v[210:213], v[16:19]
	v_mfma_f32_16x16x32_bf16 v[8:11], v[226:229], v[218:221], v[8:11]
	v_mfma_f32_16x16x32_bf16 v[0:3], v[234:237], v[218:221], v[0:3]
	v_mfma_f32_16x16x32_bf16 v[56:59], v[230:233], v[174:177], v[56:59]
	v_mfma_f32_16x16x32_bf16 v[48:51], v[238:241], v[174:177], v[48:51]
	v_mfma_f32_16x16x32_bf16 v[40:43], v[230:233], v[182:185], v[40:43]
	v_mfma_f32_16x16x32_bf16 v[32:35], v[238:241], v[182:185], v[32:35]
	v_mfma_f32_16x16x32_bf16 v[24:27], v[230:233], v[214:217], v[24:27]
	v_mfma_f32_16x16x32_bf16 v[16:19], v[238:241], v[214:217], v[16:19]
	v_mfma_f32_16x16x32_bf16 v[8:11], v[230:233], v[222:225], v[8:11]
	v_mfma_f32_16x16x32_bf16 v[0:3], v[238:241], v[222:225], v[0:3]
	s_add_i32 s60, s60, 2
	s_add_u32 s18, s18, 0x100
	s_addc_u32 s19, s19, 0
	s_add_u32 s58, s58, 0x100
	s_addc_u32 s59, s59, 0
	s_cmp_gt_u32 s60, 13
	s_barrier
	s_cbranch_scc0 .LBB0_997
	v_mul_f32_e32 v159, 0xbfb8aa3b, v124
	v_exp_f32_e32 v159, v159
	v_lshl_add_u32 v158, s16, 8, v154
	v_lshl_or_b32 v152, s39, 7, v156
	v_ashrrev_i32_e32 v153, 31, v152
	v_add_f32_e32 v159, 1.0, v159
	v_rcp_f32_e32 v159, v159
	v_mov_b64_e32 v[150:151], s[0:1]
	v_mad_i64_i32 v[160:161], s[12:13], v158, s52, v[150:151]
	v_mul_f32_e32 v124, v124, v159
	v_mul_f32_e32 v120, v124, v120
	v_mul_f32_e32 v124, 0xbfb8aa3b, v125
	v_exp_f32_e32 v124, v124
	v_lshlrev_b64 v[152:153], 1, v[152:153]
	v_lshl_add_u64 v[160:161], v[160:161], 0, v[152:153]
	s_and_b64 vcc, exec, s[2:3]
	v_add_f32_e32 v124, 1.0, v124
	v_rcp_f32_e32 v124, v124
	s_mov_b32 s39, s4
	s_mov_b32 s16, s6
	s_mov_b64 s[20:21], s[14:15]
	v_mul_f32_e32 v124, v125, v124
	v_mul_f32_e32 v121, v124, v121
	v_cvt_pk_bf16_f32 v120, v120, v121
	v_mul_f32_e32 v121, 0xbfb8aa3b, v126
	v_exp_f32_e32 v121, v121
	s_mov_b64 s[18:19], s[8:9]
	v_add_f32_e32 v121, 1.0, v121
	v_rcp_f32_e32 v121, v121
	s_nop 0
	v_mul_f32_e32 v121, v126, v121
	v_mul_f32_e32 v121, v121, v122
	v_mul_f32_e32 v122, 0xbfb8aa3b, v127
	v_exp_f32_e32 v122, v122
	s_nop 0
	v_add_f32_e32 v122, 1.0, v122
	v_rcp_f32_e32 v122, v122
	s_nop 0
	v_mul_f32_e32 v122, v127, v122
	v_mul_f32_e32 v122, v122, v123
	v_cvt_pk_bf16_f32 v121, v121, v122
	v_mul_f32_e32 v122, 0xbfb8aa3b, v116
	v_exp_f32_e32 v122, v122
	s_nop 0
	v_add_f32_e32 v122, 1.0, v122
	v_rcp_f32_e32 v122, v122
	s_nop 0
	v_mul_f32_e32 v116, v116, v122
	v_mul_f32_e32 v112, v116, v112
	v_mul_f32_e32 v116, 0xbfb8aa3b, v117
	v_exp_f32_e32 v116, v116
	s_nop 0
	v_add_f32_e32 v116, 1.0, v116
	v_rcp_f32_e32 v116, v116
	s_nop 0
	v_mul_f32_e32 v116, v117, v116
	v_mul_f32_e32 v113, v116, v113
	v_cvt_pk_bf16_f32 v122, v112, v113
	v_mul_f32_e32 v112, 0xbfb8aa3b, v118
	v_exp_f32_e32 v112, v112
	v_mul_f32_e32 v113, 0xbfb8aa3b, v119
	v_exp_f32_e32 v113, v113
	v_add_f32_e32 v112, 1.0, v112
	v_rcp_f32_e32 v112, v112
	v_add_f32_e32 v113, 1.0, v113
	v_rcp_f32_e32 v113, v113
	v_mul_f32_e32 v112, v118, v112
	v_mul_f32_e32 v112, v112, v114
	v_mul_f32_e32 v114, 0xbfb8aa3b, v108
	v_exp_f32_e32 v114, v114
	v_mul_f32_e32 v113, v119, v113
	v_mul_f32_e32 v113, v113, v115
	v_cvt_pk_bf16_f32 v123, v112, v113
	v_add_f32_e32 v114, 1.0, v114
	v_rcp_f32_e32 v114, v114
	v_or_b32_e32 v112, 16, v158
	v_mad_i64_i32 v[112:113], s[12:13], v112, s52, v[150:151]
	v_mul_f32_e32 v108, v108, v114
	v_mul_f32_e32 v104, v108, v104
	v_mul_f32_e32 v108, 0xbfb8aa3b, v109
	v_exp_f32_e32 v108, v108
	v_lshl_add_u64 v[112:113], v[112:113], 0, v[152:153]
	global_store_dwordx4 v[160:161], v[120:123], off
	v_add_f32_e32 v108, 1.0, v108
	v_rcp_f32_e32 v108, v108
	s_nop 0
	v_mul_f32_e32 v108, v109, v108
	v_mul_f32_e32 v105, v108, v105
	v_cvt_pk_bf16_f32 v104, v104, v105
	v_mul_f32_e32 v105, 0xbfb8aa3b, v110
	v_exp_f32_e32 v105, v105
	s_nop 0
	v_add_f32_e32 v105, 1.0, v105
	v_rcp_f32_e32 v105, v105
	s_nop 0
;   __device__ __forceinline__ bf16* y() const { unsigned o_ = (unsigned)(OFF_y); asm volatile("" : "+s"(o_)); return (bf16*)(ws + o_); }
; __device__ __forceinline__ unsigned pk2(float a, float b) { unsigned r; asm("v_cvt_pk_bf16_f32 %0, %1, %2" : "=v"(r) : "v"(a), "v"(b)); return r; }
; __device__ __forceinline__ float silu(float x) { return x * sigm(x); }
;   __device__ __forceinline__ void operator()(const f32x4 (&acc)[2][2][4][2], const pg8::Unit& u, int wr, int wc, int fr, int fq) const {
;     const int row0 = u.pm * 256 + wr * 64 + fr, col0 = u.pn * 128 + wc * 32 + 8 * fq;
; #pragma unroll
;     for (int ai = 0; ai < 2; ++ai)
; #pragma unroll
;       for (int m = 0; m < 4; ++m) {
;         bf16* rowp = O + (size_t)(row0 + ai * 128 + m * 16) * FF + col0;
;         const f32x4 g0 = acc[ai][0][m][0], g1 = acc[ai][0][m][1], u0 = acc[ai][1][m][0], u1 = acc[ai][1][m][1];
;         uint4 o;
;         o.x = pk2(silu(g0[0]) * u0[0], silu(g0[1]) * u0[1]); o.y = pk2(silu(g0[2]) * u0[2], silu(g0[3]) * u0[3]);
;         o.z = pk2(silu(g1[0]) * u1[0], silu(g1[1]) * u1[1]); o.w = pk2(silu(g1[2]) * u1[2], silu(g1[3]) * u1[3]);
;         *(uint4*)rowp = o;
;       }
;   }
	v_mul_f32_e32 v105, v110, v105
	v_mul_f32_e32 v105, v105, v106
	v_mul_f32_e32 v106, 0xbfb8aa3b, v111
	v_exp_f32_e32 v106, v106
	s_nop 0
	v_add_f32_e32 v106, 1.0, v106
	v_rcp_f32_e32 v106, v106
	s_nop 0
	v_mul_f32_e32 v106, v111, v106
	v_mul_f32_e32 v106, v106, v107
	v_cvt_pk_bf16_f32 v105, v105, v106
	v_mul_f32_e32 v106, 0xbfb8aa3b, v100
	v_exp_f32_e32 v106, v106
	s_nop 0
	v_add_f32_e32 v106, 1.0, v106
	v_rcp_f32_e32 v106, v106
	s_nop 0
	v_mul_f32_e32 v100, v100, v106
	v_mul_f32_e32 v96, v100, v96
	v_mul_f32_e32 v100, 0xbfb8aa3b, v101
	v_exp_f32_e32 v100, v100
	s_nop 0
	v_add_f32_e32 v100, 1.0, v100
	v_rcp_f32_e32 v100, v100
	s_nop 0
	v_mul_f32_e32 v100, v101, v100
	v_mul_f32_e32 v97, v100, v97
	v_cvt_pk_bf16_f32 v106, v96, v97
	v_mul_f32_e32 v96, 0xbfb8aa3b, v102
	v_exp_f32_e32 v96, v96
	v_mul_f32_e32 v97, 0xbfb8aa3b, v103
	v_exp_f32_e32 v97, v97
	v_add_f32_e32 v96, 1.0, v96
	v_rcp_f32_e32 v96, v96
	v_add_f32_e32 v97, 1.0, v97
	v_rcp_f32_e32 v97, v97
	v_mul_f32_e32 v96, v102, v96
	v_mul_f32_e32 v96, v96, v98
	v_mul_f32_e32 v98, 0xbfb8aa3b, v92
	v_exp_f32_e32 v98, v98
	v_mul_f32_e32 v97, v103, v97
	v_mul_f32_e32 v97, v97, v99
	v_cvt_pk_bf16_f32 v107, v96, v97
	v_add_f32_e32 v98, 1.0, v98
	v_rcp_f32_e32 v98, v98
	v_or_b32_e32 v96, 32, v158
	v_mad_i64_i32 v[96:97], s[12:13], v96, s52, v[150:151]
	v_mul_f32_e32 v92, v92, v98
	v_mul_f32_e32 v88, v92, v88
	v_mul_f32_e32 v92, 0xbfb8aa3b, v93
	v_exp_f32_e32 v92, v92
	v_lshl_add_u64 v[96:97], v[96:97], 0, v[152:153]
	global_store_dwordx4 v[112:113], v[104:107], off
	v_add_f32_e32 v92, 1.0, v92
	v_rcp_f32_e32 v92, v92
	s_nop 0
	v_mul_f32_e32 v92, v93, v92
	v_mul_f32_e32 v89, v92, v89
	v_cvt_pk_bf16_f32 v88, v88, v89
	v_mul_f32_e32 v89, 0xbfb8aa3b, v94
	v_exp_f32_e32 v89, v89
	s_nop 0
	v_add_f32_e32 v89, 1.0, v89
	v_rcp_f32_e32 v89, v89
	s_nop 0
	v_mul_f32_e32 v89, v94, v89
	v_mul_f32_e32 v89, v89, v90
	v_mul_f32_e32 v90, 0xbfb8aa3b, v95
	v_exp_f32_e32 v90, v90
	s_nop 0
	v_add_f32_e32 v90, 1.0, v90
	v_rcp_f32_e32 v90, v90
	s_nop 0
	v_mul_f32_e32 v90, v95, v90
	v_mul_f32_e32 v90, v90, v91
	v_cvt_pk_bf16_f32 v89, v89, v90
	v_mul_f32_e32 v90, 0xbfb8aa3b, v84
	v_exp_f32_e32 v90, v90
	s_nop 0
	v_add_f32_e32 v90, 1.0, v90
	v_rcp_f32_e32 v90, v90
	s_nop 0
	v_mul_f32_e32 v84, v84, v90
	v_mul_f32_e32 v80, v84, v80
	v_mul_f32_e32 v84, 0xbfb8aa3b, v85
	v_exp_f32_e32 v84, v84
	s_nop 0
	v_add_f32_e32 v84, 1.0, v84
	v_rcp_f32_e32 v84, v84
	s_nop 0
	v_mul_f32_e32 v84, v85, v84
	v_mul_f32_e32 v81, v84, v81
	v_cvt_pk_bf16_f32 v90, v80, v81
	v_mul_f32_e32 v80, 0xbfb8aa3b, v86
	v_exp_f32_e32 v80, v80
	v_mul_f32_e32 v81, 0xbfb8aa3b, v87
	v_exp_f32_e32 v81, v81
	v_add_f32_e32 v80, 1.0, v80
	v_rcp_f32_e32 v80, v80
	v_add_f32_e32 v81, 1.0, v81
	v_rcp_f32_e32 v81, v81
	v_mul_f32_e32 v80, v86, v80
	v_mul_f32_e32 v80, v80, v82
	v_mul_f32_e32 v82, 0xbfb8aa3b, v76
	v_exp_f32_e32 v82, v82
	v_mul_f32_e32 v81, v87, v81
	v_mul_f32_e32 v81, v81, v83
	v_cvt_pk_bf16_f32 v91, v80, v81
	v_add_f32_e32 v82, 1.0, v82
	v_rcp_f32_e32 v82, v82
	v_or_b32_e32 v80, 48, v158
	v_mad_i64_i32 v[80:81], s[12:13], v80, s52, v[150:151]
	v_mul_f32_e32 v76, v76, v82
	v_mul_f32_e32 v72, v76, v72
	v_mul_f32_e32 v76, 0xbfb8aa3b, v77
	v_exp_f32_e32 v76, v76
	v_lshl_add_u64 v[80:81], v[80:81], 0, v[152:153]
	global_store_dwordx4 v[96:97], v[88:91], off
	v_add_f32_e32 v76, 1.0, v76
	v_rcp_f32_e32 v76, v76
	s_nop 0
	v_mul_f32_e32 v76, v77, v76
	v_mul_f32_e32 v73, v76, v73
	v_cvt_pk_bf16_f32 v72, v72, v73
	v_mul_f32_e32 v73, 0xbfb8aa3b, v78
	v_exp_f32_e32 v73, v73
	s_nop 0
	v_add_f32_e32 v73, 1.0, v73
	v_rcp_f32_e32 v73, v73
	s_nop 0
	v_mul_f32_e32 v73, v78, v73
	v_mul_f32_e32 v73, v73, v74
	v_mul_f32_e32 v74, 0xbfb8aa3b, v79
	v_exp_f32_e32 v74, v74
	s_nop 0
	v_add_f32_e32 v74, 1.0, v74
	v_rcp_f32_e32 v74, v74
	s_nop 0
	v_mul_f32_e32 v74, v79, v74
	v_mul_f32_e32 v74, v74, v75
	v_cvt_pk_bf16_f32 v73, v73, v74
	v_mul_f32_e32 v74, 0xbfb8aa3b, v68
	v_exp_f32_e32 v74, v74
	s_nop 0
	v_add_f32_e32 v74, 1.0, v74
	v_rcp_f32_e32 v74, v74
	s_nop 0
	v_mul_f32_e32 v68, v68, v74
	v_mul_f32_e32 v64, v68, v64
	v_mul_f32_e32 v68, 0xbfb8aa3b, v69
	v_exp_f32_e32 v68, v68
	s_nop 0
	v_add_f32_e32 v68, 1.0, v68
	v_rcp_f32_e32 v68, v68
	s_nop 0
	v_mul_f32_e32 v68, v69, v68
	v_mul_f32_e32 v65, v68, v65
	v_cvt_pk_bf16_f32 v74, v64, v65
	v_mul_f32_e32 v64, 0xbfb8aa3b, v70
	v_exp_f32_e32 v64, v64
	v_mul_f32_e32 v65, 0xbfb8aa3b, v71
	v_exp_f32_e32 v65, v65
	v_add_f32_e32 v64, 1.0, v64
	v_rcp_f32_e32 v64, v64
	v_add_f32_e32 v65, 1.0, v65
	v_rcp_f32_e32 v65, v65
	v_mul_f32_e32 v64, v70, v64
	v_mul_f32_e32 v64, v64, v66
	v_mul_f32_e32 v66, 0xbfb8aa3b, v60
	v_exp_f32_e32 v66, v66
	v_mul_f32_e32 v65, v71, v65
	v_mul_f32_e32 v65, v65, v67
	v_cvt_pk_bf16_f32 v75, v64, v65
	v_add_f32_e32 v66, 1.0, v66
	v_rcp_f32_e32 v66, v66
	v_add_u32_e32 v64, 0x80, v158
	v_mad_i64_i32 v[64:65], s[12:13], v64, s52, v[150:151]
	v_mul_f32_e32 v60, v60, v66
	v_mul_f32_e32 v56, v60, v56
	v_mul_f32_e32 v60, 0xbfb8aa3b, v61
	v_exp_f32_e32 v60, v60
	v_lshl_add_u64 v[64:65], v[64:65], 0, v[152:153]
	global_store_dwordx4 v[80:81], v[72:75], off
	v_add_f32_e32 v60, 1.0, v60
	v_rcp_f32_e32 v60, v60
	s_nop 0
	v_mul_f32_e32 v60, v61, v60
	v_mul_f32_e32 v57, v60, v57
	v_cvt_pk_bf16_f32 v56, v56, v57
	v_mul_f32_e32 v57, 0xbfb8aa3b, v62
	v_exp_f32_e32 v57, v57
	s_nop 0
	v_add_f32_e32 v57, 1.0, v57
	v_rcp_f32_e32 v57, v57
	s_nop 0
	v_mul_f32_e32 v57, v62, v57
	v_mul_f32_e32 v57, v57, v58
	v_mul_f32_e32 v58, 0xbfb8aa3b, v63
	v_exp_f32_e32 v58, v58
	s_nop 0
	v_add_f32_e32 v58, 1.0, v58
	v_rcp_f32_e32 v58, v58
	s_nop 0
	v_mul_f32_e32 v58, v63, v58
	v_mul_f32_e32 v58, v58, v59
	v_cvt_pk_bf16_f32 v57, v57, v58
;   __device__ __forceinline__ bf16* y() const { unsigned o_ = (unsigned)(OFF_y); asm volatile("" : "+s"(o_)); return (bf16*)(ws + o_); }
; __device__ __forceinline__ unsigned pk2(float a, float b) { unsigned r; asm("v_cvt_pk_bf16_f32 %0, %1, %2" : "=v"(r) : "v"(a), "v"(b)); return r; }
; __device__ __forceinline__ float silu(float x) { return x * sigm(x); }
; #define PG8_WAIT_V(n) asm volatile("s_waitcnt vmcnt(" #n ")" ::: "memory")
; #define PG8_BAR __builtin_amdgcn_s_barrier()
; template <class Epi, class Sched>
; __device__ __forceinline__ void gemm_phase(PG8_LAS unsigned char* lds, const Gemm g, const Sched& S, const Epi& E) {
;     ...
;     PG8_WAIT_V(0);
;     if (wr == 0) PG8_BAR;
;     PG8_BAR;
;   __device__ __forceinline__ void operator()(const f32x4 (&acc)[2][2][4][2], const pg8::Unit& u, int wr, int wc, int fr, int fq) const {
;     ...
;     for (int ai = 0; ai < 2; ++ai)
; #pragma unroll
;       for (int m = 0; m < 4; ++m) {
;         bf16* rowp = O + (size_t)(row0 + ai * 128 + m * 16) * FF + col0;
;         const f32x4 g0 = acc[ai][0][m][0], g1 = acc[ai][0][m][1], u0 = acc[ai][1][m][0], u1 = acc[ai][1][m][1];
;         uint4 o;
;         o.x = pk2(silu(g0[0]) * u0[0], silu(g0[1]) * u0[1]); o.y = pk2(silu(g0[2]) * u0[2], silu(g0[3]) * u0[3]);
;         o.z = pk2(silu(g1[0]) * u1[0], silu(g1[1]) * u1[1]); o.w = pk2(silu(g1[2]) * u1[2], silu(g1[3]) * u1[3]);
;         *(uint4*)rowp = o;
;       }
;   }
	v_mul_f32_e32 v58, 0xbfb8aa3b, v52
	v_exp_f32_e32 v58, v58
	s_nop 0
	v_add_f32_e32 v58, 1.0, v58
	v_rcp_f32_e32 v58, v58
	s_nop 0
	v_mul_f32_e32 v52, v52, v58
	v_mul_f32_e32 v48, v52, v48
	v_mul_f32_e32 v52, 0xbfb8aa3b, v53
	v_exp_f32_e32 v52, v52
	s_nop 0
	v_add_f32_e32 v52, 1.0, v52
	v_rcp_f32_e32 v52, v52
	s_nop 0
	v_mul_f32_e32 v52, v53, v52
	v_mul_f32_e32 v49, v52, v49
	v_cvt_pk_bf16_f32 v58, v48, v49
	v_mul_f32_e32 v48, 0xbfb8aa3b, v54
	v_exp_f32_e32 v48, v48
	v_mul_f32_e32 v49, 0xbfb8aa3b, v55
	v_exp_f32_e32 v49, v49
	v_add_f32_e32 v48, 1.0, v48
	v_rcp_f32_e32 v48, v48
	v_add_f32_e32 v49, 1.0, v49
	v_rcp_f32_e32 v49, v49
	v_mul_f32_e32 v48, v54, v48
	v_mul_f32_e32 v48, v48, v50
	v_mul_f32_e32 v50, 0xbfb8aa3b, v44
	v_exp_f32_e32 v50, v50
	v_mul_f32_e32 v49, v55, v49
	v_mul_f32_e32 v49, v49, v51
	v_cvt_pk_bf16_f32 v59, v48, v49
	v_add_f32_e32 v50, 1.0, v50
	v_rcp_f32_e32 v50, v50
	v_add_u32_e32 v48, 0x90, v158
	v_mad_i64_i32 v[48:49], s[12:13], v48, s52, v[150:151]
	v_mul_f32_e32 v44, v44, v50
	v_mul_f32_e32 v40, v44, v40
	v_mul_f32_e32 v44, 0xbfb8aa3b, v45
	v_exp_f32_e32 v44, v44
	v_lshl_add_u64 v[48:49], v[48:49], 0, v[152:153]
	global_store_dwordx4 v[64:65], v[56:59], off
	v_add_f32_e32 v44, 1.0, v44
	v_rcp_f32_e32 v44, v44
	s_nop 0
	v_mul_f32_e32 v44, v45, v44
	v_mul_f32_e32 v41, v44, v41
	v_cvt_pk_bf16_f32 v40, v40, v41
	v_mul_f32_e32 v41, 0xbfb8aa3b, v46
	v_exp_f32_e32 v41, v41
	s_nop 0
	v_add_f32_e32 v41, 1.0, v41
	v_rcp_f32_e32 v41, v41
	s_nop 0
	v_mul_f32_e32 v41, v46, v41
	v_mul_f32_e32 v41, v41, v42
	v_mul_f32_e32 v42, 0xbfb8aa3b, v47
	v_exp_f32_e32 v42, v42
	s_nop 0
	v_add_f32_e32 v42, 1.0, v42
	v_rcp_f32_e32 v42, v42
	s_nop 0
	v_mul_f32_e32 v42, v47, v42
	v_mul_f32_e32 v42, v42, v43
	v_cvt_pk_bf16_f32 v41, v41, v42
	v_mul_f32_e32 v42, 0xbfb8aa3b, v36
	v_exp_f32_e32 v42, v42
	s_nop 0
	v_add_f32_e32 v42, 1.0, v42
	v_rcp_f32_e32 v42, v42
	s_nop 0
	v_mul_f32_e32 v36, v36, v42
	v_mul_f32_e32 v32, v36, v32
	v_mul_f32_e32 v36, 0xbfb8aa3b, v37
	v_exp_f32_e32 v36, v36
	s_nop 0
	v_add_f32_e32 v36, 1.0, v36
	v_rcp_f32_e32 v36, v36
	s_nop 0
	v_mul_f32_e32 v36, v37, v36
	v_mul_f32_e32 v33, v36, v33
	v_cvt_pk_bf16_f32 v42, v32, v33
	v_mul_f32_e32 v32, 0xbfb8aa3b, v38
	v_exp_f32_e32 v32, v32
	v_mul_f32_e32 v33, 0xbfb8aa3b, v39
	v_exp_f32_e32 v33, v33
	v_add_f32_e32 v32, 1.0, v32
	v_rcp_f32_e32 v32, v32
	v_add_f32_e32 v33, 1.0, v33
	v_rcp_f32_e32 v33, v33
	v_mul_f32_e32 v32, v38, v32
	v_mul_f32_e32 v32, v32, v34
	v_mul_f32_e32 v34, 0xbfb8aa3b, v28
	v_exp_f32_e32 v34, v34
	v_mul_f32_e32 v33, v39, v33
	v_mul_f32_e32 v33, v33, v35
	v_cvt_pk_bf16_f32 v43, v32, v33
	v_add_f32_e32 v34, 1.0, v34
	v_rcp_f32_e32 v34, v34
	v_add_u32_e32 v32, 0xa0, v158
	v_mad_i64_i32 v[32:33], s[12:13], v32, s52, v[150:151]
	v_mul_f32_e32 v28, v28, v34
	v_mul_f32_e32 v24, v28, v24
	v_mul_f32_e32 v28, 0xbfb8aa3b, v29
	v_exp_f32_e32 v28, v28
	v_lshl_add_u64 v[32:33], v[32:33], 0, v[152:153]
	global_store_dwordx4 v[48:49], v[40:43], off
	v_add_f32_e32 v28, 1.0, v28
	v_rcp_f32_e32 v28, v28
	s_nop 0
	v_mul_f32_e32 v28, v29, v28
	v_mul_f32_e32 v25, v28, v25
	v_cvt_pk_bf16_f32 v24, v24, v25
	v_mul_f32_e32 v25, 0xbfb8aa3b, v30
	v_exp_f32_e32 v25, v25
	s_nop 0
	v_add_f32_e32 v25, 1.0, v25
	v_rcp_f32_e32 v25, v25
	s_nop 0
	v_mul_f32_e32 v25, v30, v25
	v_mul_f32_e32 v25, v25, v26
	v_mul_f32_e32 v26, 0xbfb8aa3b, v31
	v_exp_f32_e32 v26, v26
	s_nop 0
	v_add_f32_e32 v26, 1.0, v26
	v_rcp_f32_e32 v26, v26
	s_nop 0
	v_mul_f32_e32 v26, v31, v26
	v_mul_f32_e32 v26, v26, v27
	v_cvt_pk_bf16_f32 v25, v25, v26
	v_mul_f32_e32 v26, 0xbfb8aa3b, v20
	v_exp_f32_e32 v26, v26
	s_nop 0
	v_add_f32_e32 v26, 1.0, v26
	v_rcp_f32_e32 v26, v26
	s_nop 0
	v_mul_f32_e32 v20, v20, v26
	v_mul_f32_e32 v16, v20, v16
	v_mul_f32_e32 v20, 0xbfb8aa3b, v21
	v_exp_f32_e32 v20, v20
	s_nop 0
	v_add_f32_e32 v20, 1.0, v20
	v_rcp_f32_e32 v20, v20
	s_nop 0
	v_mul_f32_e32 v20, v21, v20
	v_mul_f32_e32 v17, v20, v17
	v_cvt_pk_bf16_f32 v26, v16, v17
	v_mul_f32_e32 v16, 0xbfb8aa3b, v22
	v_exp_f32_e32 v16, v16
	v_mul_f32_e32 v17, 0xbfb8aa3b, v23
	v_exp_f32_e32 v17, v17
	v_add_f32_e32 v16, 1.0, v16
	v_rcp_f32_e32 v16, v16
	v_add_f32_e32 v17, 1.0, v17
	v_rcp_f32_e32 v17, v17
	v_mul_f32_e32 v16, v22, v16
	v_mul_f32_e32 v16, v16, v18
	v_mul_f32_e32 v18, 0xbfb8aa3b, v12
	v_exp_f32_e32 v18, v18
	v_mul_f32_e32 v17, v23, v17
	v_mul_f32_e32 v17, v17, v19
	v_cvt_pk_bf16_f32 v27, v16, v17
	v_add_f32_e32 v18, 1.0, v18
	v_rcp_f32_e32 v18, v18
	v_add_u32_e32 v16, 0xb0, v158
	v_mad_i64_i32 v[16:17], s[12:13], v16, s52, v[150:151]
	v_mul_f32_e32 v12, v12, v18
	v_mul_f32_e32 v8, v12, v8
	v_mul_f32_e32 v12, 0xbfb8aa3b, v13
	v_exp_f32_e32 v12, v12
	v_lshl_add_u64 v[16:17], v[16:17], 0, v[152:153]
	global_store_dwordx4 v[32:33], v[24:27], off
	v_add_f32_e32 v12, 1.0, v12
	v_rcp_f32_e32 v12, v12
	s_nop 0
	v_mul_f32_e32 v12, v13, v12
	v_mul_f32_e32 v9, v12, v9
	v_cvt_pk_bf16_f32 v8, v8, v9
	v_mul_f32_e32 v9, 0xbfb8aa3b, v14
	v_exp_f32_e32 v9, v9
	s_nop 0
	v_add_f32_e32 v9, 1.0, v9
	v_rcp_f32_e32 v9, v9
	s_nop 0
	v_mul_f32_e32 v9, v14, v9
	v_mul_f32_e32 v9, v9, v10
	v_mul_f32_e32 v10, 0xbfb8aa3b, v15
	v_exp_f32_e32 v10, v10
	s_nop 0
	v_add_f32_e32 v10, 1.0, v10
	v_rcp_f32_e32 v10, v10
	s_nop 0
	v_mul_f32_e32 v10, v15, v10
	v_mul_f32_e32 v10, v10, v11
	v_cvt_pk_bf16_f32 v9, v9, v10
	v_mul_f32_e32 v10, 0xbfb8aa3b, v4
	v_exp_f32_e32 v10, v10
	s_nop 0
	v_add_f32_e32 v10, 1.0, v10
	v_rcp_f32_e32 v10, v10
	s_nop 0
	v_mul_f32_e32 v4, v4, v10
	v_mul_f32_e32 v0, v4, v0
	v_mul_f32_e32 v4, 0xbfb8aa3b, v5
	v_exp_f32_e32 v4, v4
	s_nop 0
	v_add_f32_e32 v4, 1.0, v4
	v_rcp_f32_e32 v4, v4
	s_nop 0
	v_mul_f32_e32 v4, v5, v4
	v_mul_f32_e32 v1, v4, v1
	v_cvt_pk_bf16_f32 v10, v0, v1
	v_mul_f32_e32 v0, 0xbfb8aa3b, v6
	v_mul_f32_e32 v1, 0xbfb8aa3b, v7
	v_exp_f32_e32 v0, v0
	v_exp_f32_e32 v1, v1
	v_add_f32_e32 v0, 1.0, v0
	v_add_f32_e32 v1, 1.0, v1
	v_rcp_f32_e32 v0, v0
	v_rcp_f32_e32 v1, v1
	v_mul_f32_e32 v0, v6, v0
	v_mul_f32_e32 v1, v7, v1
	v_mul_f32_e32 v0, v0, v2
	v_mul_f32_e32 v1, v1, v3
	v_cvt_pk_bf16_f32 v11, v0, v1
	global_store_dwordx4 v[16:17], v[8:11], off
	s_cbranch_vccz .LBB0_990
	s_waitcnt vmcnt(0)
	s_cmpk_gt_u32 s25, 0xff
	s_cbranch_scc1 .LBB0_1001
	s_barrier

; #define PG8_STAGE(bufoff, gbase, voff) do { _Pragma("unroll") for (int _i = 0; _i < 2; ++_i) \
;         __builtin_amdgcn_global_load_lds((const unsigned*)((const char*)(gbase) + (voff)[_i]), (PG8_LAS unsigned*)(lds + (bufoff) + ldsw + _i * 8192), 16, 0, 0); } while (0)
; #define PG8_LDA(dst, b, h) do { _Pragma("unroll") for (int m = 0; m < 4; ++m) _Pragma("unroll") for (int k = 0; k < 2; ++k) dst[m][k] = *(const PG8_LAS bf16x8*)(lds + PG8_SA(b, h) + aoff + m * 2048 + k * 1024); } while (0)
; #define PG8_LDB(dst, b, h) do { _Pragma("unroll") for (int n = 0; n < 2; ++n) _Pragma("unroll") for (int k = 0; k < 2; ++k) dst[n][k] = *(const PG8_LAS bf16x8*)(lds + PG8_SB(b, h) + boff + n * 2048 + k * 1024); } while (0)
; #define PG8_MMA(ai, bj, At, Bt) do { __builtin_amdgcn_s_setprio(1); _Pragma("unroll") for (int m = 0; m < 4; ++m) _Pragma("unroll") for (int n = 0; n < 2; ++n) _Pragma("unroll") for (int k = 0; k < 2; ++k) \
;         acc[ai][bj][m][n] = __builtin_amdgcn_mfma_f32_16x16x32_bf16(Bt[n][k], At[m][k], acc[ai][bj][m][n], 0, 0, 0); __builtin_amdgcn_s_setprio(0); } while (0)
; #define PG8_WAIT_L(n) asm volatile("s_waitcnt lgkmcnt(" #n ")" ::: "memory")
; #define PG8_BAR __builtin_amdgcn_s_barrier()
; #define PG8_SCHED __builtin_amdgcn_sched_barrier(0)
; template <class Epi, class Sched>
; __device__ __forceinline__ void gemm_phase(PG8_LAS unsigned char* lds, const Gemm g, const Sched& S, const Epi& E) {
;     ...
;         for (int t = 0; t < nt; t += 2) {
;             const bool last = (t == nt - 2);
;             const char* a1 = cA + (size_t)(t + 1) * kstep;
;             const char* a2 = last ? nA : cA + (size_t)(t + 2) * kstep; const char* b2 = last ? nB : cB + (size_t)(t + 2) * kstep;
;             const char* a3 = a2 + kstep; const char* b3 = b2 + kstep;
;             if (last && has_next) S.a_ready(nxt);
;             PG8_LDB(B0, 0, 0); PG8_SCHED; PG8_LDA(At, 0, 0); PG8_STAGE(PG8_SA(1, 1), a1 + hstep, voffA);
;             PG8_WAIT_L(8); PG8_BAR; PG8_WAIT_L(0); PG8_MMA(0, 0, At, B0); PG8_BAR; PG8_SCHED;
;             PG8_LDB(B1, 0, 1); PG8_STAGE(PG8_SB(0, 0), b2, voffB);
;             PG8_BAR; PG8_WAIT_L(0); PG8_MMA(0, 1, At, B1); PG8_BAR;
;             PG8_LDA(At, 0, 1); PG8_STAGE(PG8_SA(0, 0), a2, voffA);
;             PG8_BAR; PG8_WAIT_L(0); PG8_MMA(1, 0, At, B0); PG8_BAR; PG8_SCHED;
.LBB0_1074:
	s_add_u32 s12, s8, s20
	s_addc_u32 s13, s9, s21
	s_add_u32 s12, s12, 0x100
	s_addc_u32 s13, s13, 0
	s_add_u32 s22, s68, s20
	s_addc_u32 s23, s82, s21
	s_add_i32 s69, s46, 0x100
	v_add_u32_e32 v159, s69, v155
	ds_read_b128 v[160:163], v159
	ds_read_b128 v[164:167], v159 offset:1024
	ds_read_b128 v[168:171], v159 offset:2048
	ds_read_b128 v[172:175], v159 offset:3072
	s_cmpk_eq_i32 s20, 0x1500
	s_cselect_b32 s25, s19, s13
	s_cselect_b32 s24, s18, s12
	s_cselect_b32 s23, s7, s23
	s_cselect_b32 s22, s6, s22
	v_lshl_add_u64 v[230:231], v[150:151], 0, s[20:21]
	s_add_i32 m0, s58, 0xc000
	ds_read_b128 v[176:179], v158
	ds_read_b128 v[180:183], v158 offset:1024
	ds_read_b128 v[184:187], v158 offset:2048
	ds_read_b128 v[210:213], v158 offset:3072
	ds_read_b128 v[214:217], v158 offset:4096
	ds_read_b128 v[218:221], v158 offset:5120
	ds_read_b128 v[222:225], v158 offset:6144
	ds_read_b128 v[226:229], v158 offset:7168
	global_load_lds_dwordx4 v[230:231], off
	v_lshl_add_u64 v[230:231], v[152:153], 0, s[20:21]
	s_add_i32 m0, s58, 0xe000
	s_nop 0
	global_load_lds_dwordx4 v[230:231], off
	s_waitcnt lgkmcnt(8)
	s_barrier
	s_waitcnt lgkmcnt(0)
	s_waitcnt lgkmcnt(0)
	v_mfma_f32_16x16x32_bf16 v[124:127], v[160:163], v[176:179], v[124:127]
	v_mfma_f32_16x16x32_bf16 v[120:123], v[168:171], v[176:179], v[120:123]
	v_mfma_f32_16x16x32_bf16 v[116:119], v[160:163], v[184:187], v[116:119]
	v_mfma_f32_16x16x32_bf16 v[112:115], v[168:171], v[184:187], v[112:115]
	v_mfma_f32_16x16x32_bf16 v[108:111], v[160:163], v[214:217], v[108:111]
	v_mfma_f32_16x16x32_bf16 v[104:107], v[168:171], v[214:217], v[104:107]
	v_mfma_f32_16x16x32_bf16 v[100:103], v[160:163], v[222:225], v[100:103]
	v_mfma_f32_16x16x32_bf16 v[96:99], v[168:171], v[222:225], v[96:99]
	v_mfma_f32_16x16x32_bf16 v[124:127], v[164:167], v[180:183], v[124:127]
	v_mfma_f32_16x16x32_bf16 v[120:123], v[172:175], v[180:183], v[120:123]
	v_mfma_f32_16x16x32_bf16 v[116:119], v[164:167], v[210:213], v[116:119]
	v_mfma_f32_16x16x32_bf16 v[112:115], v[172:175], v[210:213], v[112:115]
	v_mfma_f32_16x16x32_bf16 v[108:111], v[164:167], v[218:221], v[108:111]
	v_mfma_f32_16x16x32_bf16 v[104:107], v[172:175], v[218:221], v[104:107]
	v_mfma_f32_16x16x32_bf16 v[100:103], v[164:167], v[226:229], v[100:103]
	v_mfma_f32_16x16x32_bf16 v[96:99], v[172:175], v[226:229], v[96:99]
	s_barrier
	s_add_i32 s84, s48, 0x100
	s_add_i32 s12, s69, s41
	v_add_u32_e32 v159, s84, v155
	v_lshl_add_u64 v[246:247], s[22:23], 0, v[138:139]
	s_mov_b32 m0, s12
	ds_read_b128 v[230:233], v159
	ds_read_b128 v[234:237], v159 offset:1024
	ds_read_b128 v[238:241], v159 offset:2048
	ds_read_b128 v[242:245], v159 offset:3072
	global_load_lds_dwordx4 v[246:247], off
	v_lshl_add_u64 v[248:249], s[22:23], 0, v[132:133]
	s_add_i32 m0, s12, 0x2000
	s_nop 0
	global_load_lds_dwordx4 v[248:249], off
	s_barrier
	s_waitcnt lgkmcnt(0)
	s_waitcnt lgkmcnt(0)
	v_mfma_f32_16x16x32_bf16 v[60:63], v[230:233], v[176:179], v[60:63]
	v_mfma_f32_16x16x32_bf16 v[56:59], v[238:241], v[176:179], v[56:59]
	v_mfma_f32_16x16x32_bf16 v[52:55], v[230:233], v[184:187], v[52:55]
	v_mfma_f32_16x16x32_bf16 v[48:51], v[238:241], v[184:187], v[48:51]
	v_mfma_f32_16x16x32_bf16 v[44:47], v[230:233], v[214:217], v[44:47]
	v_mfma_f32_16x16x32_bf16 v[40:43], v[238:241], v[214:217], v[40:43]
	v_mfma_f32_16x16x32_bf16 v[36:39], v[230:233], v[222:225], v[36:39]
	v_mfma_f32_16x16x32_bf16 v[32:35], v[238:241], v[222:225], v[32:35]
	v_mfma_f32_16x16x32_bf16 v[60:63], v[234:237], v[180:183], v[60:63]
	v_mfma_f32_16x16x32_bf16 v[56:59], v[242:245], v[180:183], v[56:59]
	v_mfma_f32_16x16x32_bf16 v[52:55], v[234:237], v[210:213], v[52:55]
	v_mfma_f32_16x16x32_bf16 v[48:51], v[242:245], v[210:213], v[48:51]
	v_mfma_f32_16x16x32_bf16 v[44:47], v[234:237], v[218:221], v[44:47]
	v_mfma_f32_16x16x32_bf16 v[40:43], v[242:245], v[218:221], v[40:43]
	v_mfma_f32_16x16x32_bf16 v[36:39], v[234:237], v[226:229], v[36:39]
	v_mfma_f32_16x16x32_bf16 v[32:35], v[242:245], v[226:229], v[32:35]
	s_mov_b32 m0, s58
	v_lshl_add_u64 v[250:251], s[24:25], 0, v[128:129]
	s_barrier
	ds_read_b128 v[176:179], v158 offset:16384
	ds_read_b128 v[180:183], v158 offset:17408
	ds_read_b128 v[184:187], v158 offset:18432
	ds_read_b128 v[210:213], v158 offset:19456
	ds_read_b128 v[214:217], v158 offset:20480
	ds_read_b128 v[218:221], v158 offset:21504
	ds_read_b128 v[222:225], v158 offset:22528
	ds_read_b128 v[226:229], v158 offset:23552
	global_load_lds_dwordx4 v[250:251], off
	v_lshl_add_u64 v[252:253], s[24:25], 0, v[130:131]
	s_mov_b32 m0, s59
	s_nop 0
	global_load_lds_dwordx4 v[252:253], off
	s_barrier
	s_waitcnt lgkmcnt(0)
	s_waitcnt lgkmcnt(0)
	v_mfma_f32_16x16x32_bf16 v[92:95], v[160:163], v[176:179], v[92:95]
	v_mfma_f32_16x16x32_bf16 v[88:91], v[168:171], v[176:179], v[88:91]
	v_mfma_f32_16x16x32_bf16 v[84:87], v[160:163], v[184:187], v[84:87]
	v_mfma_f32_16x16x32_bf16 v[80:83], v[168:171], v[184:187], v[80:83]
	v_mfma_f32_16x16x32_bf16 v[76:79], v[160:163], v[214:217], v[76:79]
	v_mfma_f32_16x16x32_bf16 v[72:75], v[168:171], v[214:217], v[72:75]
	v_mfma_f32_16x16x32_bf16 v[68:71], v[160:163], v[222:225], v[68:71]
	v_mfma_f32_16x16x32_bf16 v[64:67], v[168:171], v[222:225], v[64:67]
	v_mfma_f32_16x16x32_bf16 v[92:95], v[164:167], v[180:183], v[92:95]
	v_mfma_f32_16x16x32_bf16 v[88:91], v[172:175], v[180:183], v[88:91]
	v_mfma_f32_16x16x32_bf16 v[84:87], v[164:167], v[210:213], v[84:87]
	v_mfma_f32_16x16x32_bf16 v[80:83], v[172:175], v[210:213], v[80:83]
	v_mfma_f32_16x16x32_bf16 v[76:79], v[164:167], v[218:221], v[76:79]
	v_mfma_f32_16x16x32_bf16 v[72:75], v[172:175], v[218:221], v[72:75]
	v_mfma_f32_16x16x32_bf16 v[68:71], v[164:167], v[226:229], v[68:71]
	v_mfma_f32_16x16x32_bf16 v[64:67], v[172:175], v[226:229], v[64:67]
	s_barrier
; #define PG8_STAGE(bufoff, gbase, voff) do { _Pragma("unroll") for (int _i = 0; _i < 2; ++_i) \
;         __builtin_amdgcn_global_load_lds((const unsigned*)((const char*)(gbase) + (voff)[_i]), (PG8_LAS unsigned*)(lds + (bufoff) + ldsw + _i * 8192), 16, 0, 0); } while (0)
; #define PG8_LDA(dst, b, h) do { _Pragma("unroll") for (int m = 0; m < 4; ++m) _Pragma("unroll") for (int k = 0; k < 2; ++k) dst[m][k] = *(const PG8_LAS bf16x8*)(lds + PG8_SA(b, h) + aoff + m * 2048 + k * 1024); } while (0)
; #define PG8_LDB(dst, b, h) do { _Pragma("unroll") for (int n = 0; n < 2; ++n) _Pragma("unroll") for (int k = 0; k < 2; ++k) dst[n][k] = *(const PG8_LAS bf16x8*)(lds + PG8_SB(b, h) + boff + n * 2048 + k * 1024); } while (0)
; #define PG8_MMA(ai, bj, At, Bt) do { __builtin_amdgcn_s_setprio(1); _Pragma("unroll") for (int m = 0; m < 4; ++m) _Pragma("unroll") for (int n = 0; n < 2; ++n) _Pragma("unroll") for (int k = 0; k < 2; ++k) \
;         acc[ai][bj][m][n] = __builtin_amdgcn_mfma_f32_16x16x32_bf16(Bt[n][k], At[m][k], acc[ai][bj][m][n], 0, 0, 0); __builtin_amdgcn_s_setprio(0); } while (0)
; #define PG8_WAIT_V(n) asm volatile("s_waitcnt vmcnt(" #n ")" ::: "memory")
; #define PG8_WAIT_L(n) asm volatile("s_waitcnt lgkmcnt(" #n ")" ::: "memory")
; #define PG8_BAR __builtin_amdgcn_s_barrier()
; #define PG8_SCHED __builtin_amdgcn_sched_barrier(0)
; template <class Epi, class Sched>
; __device__ __forceinline__ void gemm_phase(PG8_LAS unsigned char* lds, const Gemm g, const Sched& S, const Epi& E) {
;     ...
;             PG8_STAGE(PG8_SB(0, 1), b2 + hstep, voffB);
;             PG8_WAIT_V(6); PG8_BAR; PG8_MMA(1, 1, At, B1); PG8_BAR;
;             PG8_LDB(B0, 1, 0); PG8_SCHED; PG8_LDA(At, 1, 0); PG8_STAGE(PG8_SA(0, 1), a2 + hstep, voffA);
;             PG8_WAIT_L(8); PG8_BAR; PG8_WAIT_L(0); PG8_MMA(0, 0, At, B0); PG8_BAR; PG8_SCHED;
;             PG8_LDB(B1, 1, 1); PG8_STAGE(PG8_SB(1, 0), b3, voffB);
;             PG8_BAR; PG8_WAIT_L(0); PG8_MMA(0, 1, At, B1); PG8_BAR;
;             PG8_LDA(At, 1, 1); PG8_STAGE(PG8_SA(1, 0), a3, voffA);
;             PG8_BAR; PG8_WAIT_L(0); PG8_MMA(1, 0, At, B0); PG8_BAR; PG8_SCHED;
	s_add_u32 s12, s22, 0xb0000
	s_addc_u32 s13, s23, 0
	s_add_i32 s69, s84, s41
	v_lshl_add_u64 v[160:161], s[12:13], 0, v[138:139]
	s_mov_b32 m0, s69
	s_nop 0
	global_load_lds_dwordx4 v[160:161], off
	v_lshl_add_u64 v[160:161], s[12:13], 0, v[132:133]
	s_add_i32 m0, s69, 0x2000
	s_nop 0
	global_load_lds_dwordx4 v[160:161], off
	s_waitcnt vmcnt(6)
	s_barrier
	v_mfma_f32_16x16x32_bf16 v[28:31], v[230:233], v[176:179], v[28:31]
	v_mfma_f32_16x16x32_bf16 v[24:27], v[238:241], v[176:179], v[24:27]
	v_mfma_f32_16x16x32_bf16 v[20:23], v[230:233], v[184:187], v[20:23]
	v_mfma_f32_16x16x32_bf16 v[16:19], v[238:241], v[184:187], v[16:19]
	v_mfma_f32_16x16x32_bf16 v[12:15], v[230:233], v[214:217], v[12:15]
	v_mfma_f32_16x16x32_bf16 v[8:11], v[238:241], v[214:217], v[8:11]
	v_mfma_f32_16x16x32_bf16 v[4:7], v[230:233], v[222:225], v[4:7]
	v_mfma_f32_16x16x32_bf16 v[0:3], v[238:241], v[222:225], v[0:3]
	v_mfma_f32_16x16x32_bf16 v[28:31], v[234:237], v[180:183], v[28:31]
	v_mfma_f32_16x16x32_bf16 v[24:27], v[242:245], v[180:183], v[24:27]
	v_mfma_f32_16x16x32_bf16 v[20:23], v[234:237], v[210:213], v[20:23]
	v_mfma_f32_16x16x32_bf16 v[16:19], v[242:245], v[210:213], v[16:19]
	v_mfma_f32_16x16x32_bf16 v[12:15], v[234:237], v[218:221], v[12:15]
	v_mfma_f32_16x16x32_bf16 v[8:11], v[242:245], v[218:221], v[8:11]
	v_mfma_f32_16x16x32_bf16 v[4:7], v[234:237], v[226:229], v[4:7]
	v_mfma_f32_16x16x32_bf16 v[0:3], v[242:245], v[226:229], v[0:3]
	s_add_i32 s69, s51, 0x100
	v_add_u32_e32 v159, s69, v155
	s_barrier
	ds_read_b128 v[160:163], v159
	ds_read_b128 v[164:167], v159 offset:1024
	ds_read_b128 v[168:171], v159 offset:2048
	ds_read_b128 v[172:175], v159 offset:3072
	s_add_u32 s12, s24, 0xb0000
	s_addc_u32 s13, s25, 0
	s_mov_b32 m0, s60
	v_lshl_add_u64 v[230:231], s[12:13], 0, v[128:129]
	ds_read_b128 v[176:179], v158 offset:32768
	ds_read_b128 v[180:183], v158 offset:33792
	ds_read_b128 v[184:187], v158 offset:34816
	ds_read_b128 v[210:213], v158 offset:35840
	ds_read_b128 v[214:217], v158 offset:36864
	ds_read_b128 v[218:221], v158 offset:37888
	ds_read_b128 v[222:225], v158 offset:38912
	ds_read_b128 v[226:229], v158 offset:39936
	global_load_lds_dwordx4 v[230:231], off
	v_lshl_add_u64 v[230:231], s[12:13], 0, v[130:131]
	s_mov_b32 m0, s61
	s_nop 0
	global_load_lds_dwordx4 v[230:231], off
	s_waitcnt lgkmcnt(8)
	s_barrier
	s_waitcnt lgkmcnt(0)
	s_waitcnt lgkmcnt(0)
	v_mfma_f32_16x16x32_bf16 v[124:127], v[160:163], v[176:179], v[124:127]
	v_mfma_f32_16x16x32_bf16 v[120:123], v[168:171], v[176:179], v[120:123]
	v_mfma_f32_16x16x32_bf16 v[116:119], v[160:163], v[184:187], v[116:119]
	v_mfma_f32_16x16x32_bf16 v[112:115], v[168:171], v[184:187], v[112:115]
	v_mfma_f32_16x16x32_bf16 v[108:111], v[160:163], v[214:217], v[108:111]
	v_mfma_f32_16x16x32_bf16 v[104:107], v[168:171], v[214:217], v[104:107]
	v_mfma_f32_16x16x32_bf16 v[100:103], v[160:163], v[222:225], v[100:103]
	v_mfma_f32_16x16x32_bf16 v[96:99], v[168:171], v[222:225], v[96:99]
	v_mfma_f32_16x16x32_bf16 v[124:127], v[164:167], v[180:183], v[124:127]
	v_mfma_f32_16x16x32_bf16 v[120:123], v[172:175], v[180:183], v[120:123]
	v_mfma_f32_16x16x32_bf16 v[116:119], v[164:167], v[210:213], v[116:119]
	v_mfma_f32_16x16x32_bf16 v[112:115], v[172:175], v[210:213], v[112:115]
	v_mfma_f32_16x16x32_bf16 v[108:111], v[164:167], v[218:221], v[108:111]
	v_mfma_f32_16x16x32_bf16 v[104:107], v[172:175], v[218:221], v[104:107]
	v_mfma_f32_16x16x32_bf16 v[100:103], v[164:167], v[226:229], v[100:103]
	v_mfma_f32_16x16x32_bf16 v[96:99], v[172:175], v[226:229], v[96:99]
	s_barrier
	s_add_i32 s24, s55, 0x100
	s_add_i32 s12, s69, s41
	v_add_u32_e32 v159, s24, v155
	v_lshl_add_u64 v[246:247], v[246:247], 0, s[94:95]
	s_mov_b32 m0, s12
	ds_read_b128 v[230:233], v159
	ds_read_b128 v[234:237], v159 offset:1024
	ds_read_b128 v[238:241], v159 offset:2048
	ds_read_b128 v[242:245], v159 offset:3072
	global_load_lds_dwordx4 v[246:247], off
	v_lshl_add_u64 v[246:247], v[248:249], 0, s[94:95]
	s_add_i32 m0, s12, 0x2000
	s_nop 0
	global_load_lds_dwordx4 v[246:247], off
	s_barrier
	s_waitcnt lgkmcnt(0)
	s_waitcnt lgkmcnt(0)
	v_mfma_f32_16x16x32_bf16 v[60:63], v[230:233], v[176:179], v[60:63]
	v_mfma_f32_16x16x32_bf16 v[56:59], v[238:241], v[176:179], v[56:59]
	v_mfma_f32_16x16x32_bf16 v[52:55], v[230:233], v[184:187], v[52:55]
	v_mfma_f32_16x16x32_bf16 v[48:51], v[238:241], v[184:187], v[48:51]
	v_mfma_f32_16x16x32_bf16 v[44:47], v[230:233], v[214:217], v[44:47]
	v_mfma_f32_16x16x32_bf16 v[40:43], v[238:241], v[214:217], v[40:43]
	v_mfma_f32_16x16x32_bf16 v[36:39], v[230:233], v[222:225], v[36:39]
	v_mfma_f32_16x16x32_bf16 v[32:35], v[238:241], v[222:225], v[32:35]
	v_mfma_f32_16x16x32_bf16 v[60:63], v[234:237], v[180:183], v[60:63]
	v_mfma_f32_16x16x32_bf16 v[56:59], v[242:245], v[180:183], v[56:59]
	v_mfma_f32_16x16x32_bf16 v[52:55], v[234:237], v[210:213], v[52:55]
	v_mfma_f32_16x16x32_bf16 v[48:51], v[242:245], v[210:213], v[48:51]
	v_mfma_f32_16x16x32_bf16 v[44:47], v[234:237], v[218:221], v[44:47]
	v_mfma_f32_16x16x32_bf16 v[40:43], v[242:245], v[218:221], v[40:43]
	v_mfma_f32_16x16x32_bf16 v[36:39], v[234:237], v[226:229], v[36:39]
	v_mfma_f32_16x16x32_bf16 v[32:35], v[242:245], v[226:229], v[32:35]
	s_mov_b32 m0, s62
	v_lshl_add_u64 v[246:247], v[250:251], 0, s[94:95]
	s_barrier
	ds_read_b128 v[176:179], v158 offset:49152
	ds_read_b128 v[180:183], v158 offset:50176
	ds_read_b128 v[184:187], v158 offset:51200
	ds_read_b128 v[210:213], v158 offset:52224
	ds_read_b128 v[214:217], v158 offset:53248
	ds_read_b128 v[218:221], v158 offset:54272
	ds_read_b128 v[222:225], v158 offset:55296
	ds_read_b128 v[226:229], v158 offset:56320
	global_load_lds_dwordx4 v[246:247], off
	v_lshl_add_u64 v[246:247], v[252:253], 0, s[94:95]
	s_mov_b32 m0, s63
	s_nop 0
	global_load_lds_dwordx4 v[246:247], off
	s_barrier
; #define PG8_STAGE(bufoff, gbase, voff) do { _Pragma("unroll") for (int _i = 0; _i < 2; ++_i) \
;         __builtin_amdgcn_global_load_lds((const unsigned*)((const char*)(gbase) + (voff)[_i]), (PG8_LAS unsigned*)(lds + (bufoff) + ldsw + _i * 8192), 16, 0, 0); } while (0)
; #define PG8_MMA(ai, bj, At, Bt) do { __builtin_amdgcn_s_setprio(1); _Pragma("unroll") for (int m = 0; m < 4; ++m) _Pragma("unroll") for (int n = 0; n < 2; ++n) _Pragma("unroll") for (int k = 0; k < 2; ++k) \
;         acc[ai][bj][m][n] = __builtin_amdgcn_mfma_f32_16x16x32_bf16(Bt[n][k], At[m][k], acc[ai][bj][m][n], 0, 0, 0); __builtin_amdgcn_s_setprio(0); } while (0)
; #define PG8_WAIT_V(n) asm volatile("s_waitcnt vmcnt(" #n ")" ::: "memory")
; #define PG8_WAIT_L(n) asm volatile("s_waitcnt lgkmcnt(" #n ")" ::: "memory")
; #define PG8_BAR __builtin_amdgcn_s_barrier()
; #define PG8_SCHED __builtin_amdgcn_sched_barrier(0)
; template <class Epi, class Sched>
; __device__ __forceinline__ void gemm_phase(PG8_LAS unsigned char* lds, const Gemm g, const Sched& S, const Epi& E) {
;     ...
;             PG8_BAR; PG8_WAIT_L(0); PG8_MMA(1, 0, At, B0); PG8_BAR; PG8_SCHED;
;             PG8_STAGE(PG8_SB(1, 1), b3 + hstep, voffB);
;             PG8_WAIT_V(6); PG8_BAR; PG8_MMA(1, 1, At, B1); PG8_BAR;
;         }
;         if constexpr (!Epi::AFTER_DRAIN) { E(acc, cur, wr, wc, fr, fq); S.done(cur); }
;         if (!has_next) break;
; #pragma unroll
;         for (int a = 0; a < 2; ++a)
; #pragma unroll
;             for (int b = 0; b < 2; ++b)
; #pragma unroll
;                 for (int m = 0; m < 4; ++m)
; #pragma unroll
;                     for (int n = 0; n < 2; ++n) acc[a][b][m][n] = (f32x4){0.f, 0.f, 0.f, 0.f};
;         cur = nxt; cA = nA; cB = nB; ++ui;
	s_waitcnt lgkmcnt(0)
	s_waitcnt lgkmcnt(0)
	v_mfma_f32_16x16x32_bf16 v[92:95], v[160:163], v[176:179], v[92:95]
	v_mfma_f32_16x16x32_bf16 v[88:91], v[168:171], v[176:179], v[88:91]
	v_mfma_f32_16x16x32_bf16 v[84:87], v[160:163], v[184:187], v[84:87]
	v_mfma_f32_16x16x32_bf16 v[80:83], v[168:171], v[184:187], v[80:83]
	v_mfma_f32_16x16x32_bf16 v[76:79], v[160:163], v[214:217], v[76:79]
	v_mfma_f32_16x16x32_bf16 v[72:75], v[168:171], v[214:217], v[72:75]
	v_mfma_f32_16x16x32_bf16 v[68:71], v[160:163], v[222:225], v[68:71]
	v_mfma_f32_16x16x32_bf16 v[64:67], v[168:171], v[222:225], v[64:67]
	v_mfma_f32_16x16x32_bf16 v[92:95], v[164:167], v[180:183], v[92:95]
	v_mfma_f32_16x16x32_bf16 v[88:91], v[172:175], v[180:183], v[88:91]
	v_mfma_f32_16x16x32_bf16 v[84:87], v[164:167], v[210:213], v[84:87]
	v_mfma_f32_16x16x32_bf16 v[80:83], v[172:175], v[210:213], v[80:83]
	v_mfma_f32_16x16x32_bf16 v[76:79], v[164:167], v[218:221], v[76:79]
	v_mfma_f32_16x16x32_bf16 v[72:75], v[172:175], v[218:221], v[72:75]
	v_mfma_f32_16x16x32_bf16 v[68:71], v[164:167], v[226:229], v[68:71]
	v_mfma_f32_16x16x32_bf16 v[64:67], v[172:175], v[226:229], v[64:67]
	s_barrier
	s_add_u32 s12, s22, 0xb0080
	s_addc_u32 s13, s23, 0
	s_add_i32 s22, s24, s41
	v_lshl_add_u64 v[160:161], s[12:13], 0, v[138:139]
	s_mov_b32 m0, s22
	s_nop 0
	global_load_lds_dwordx4 v[160:161], off
	v_lshl_add_u64 v[160:161], s[12:13], 0, v[132:133]
	s_add_i32 m0, s22, 0x2000
	s_nop 0
	global_load_lds_dwordx4 v[160:161], off
	s_waitcnt vmcnt(6)
	s_barrier
	v_mfma_f32_16x16x32_bf16 v[28:31], v[230:233], v[176:179], v[28:31]
	v_mfma_f32_16x16x32_bf16 v[24:27], v[238:241], v[176:179], v[24:27]
	v_mfma_f32_16x16x32_bf16 v[20:23], v[230:233], v[184:187], v[20:23]
	v_mfma_f32_16x16x32_bf16 v[16:19], v[238:241], v[184:187], v[16:19]
	v_mfma_f32_16x16x32_bf16 v[12:15], v[230:233], v[214:217], v[12:15]
	v_mfma_f32_16x16x32_bf16 v[8:11], v[238:241], v[214:217], v[8:11]
	v_mfma_f32_16x16x32_bf16 v[4:7], v[230:233], v[222:225], v[4:7]
	v_mfma_f32_16x16x32_bf16 v[0:3], v[238:241], v[222:225], v[0:3]
	v_mfma_f32_16x16x32_bf16 v[28:31], v[234:237], v[180:183], v[28:31]
	v_mfma_f32_16x16x32_bf16 v[24:27], v[242:245], v[180:183], v[24:27]
	v_mfma_f32_16x16x32_bf16 v[20:23], v[234:237], v[210:213], v[20:23]
	v_mfma_f32_16x16x32_bf16 v[16:19], v[242:245], v[210:213], v[16:19]
	v_mfma_f32_16x16x32_bf16 v[12:15], v[234:237], v[218:221], v[12:15]
	v_mfma_f32_16x16x32_bf16 v[8:11], v[242:245], v[218:221], v[8:11]
	v_mfma_f32_16x16x32_bf16 v[4:7], v[234:237], v[226:229], v[4:7]
	v_mfma_f32_16x16x32_bf16 v[0:3], v[242:245], v[226:229], v[0:3]
	s_add_i32 s83, s83, 2
	s_add_u32 s20, s20, 0x100
	s_addc_u32 s21, s21, 0
	s_cmp_gt_u32 s83, 41
	s_barrier
	s_cbranch_scc0 .LBB0_1074
	s_add_u32 s20, s68, 0xffffff00
	s_addc_u32 s21, s82, -1
	s_and_b64 vcc, exec, s[0:1]
	s_cbranch_vccnz .LBB0_1077
	v_mov_b32_e32 v0, 0
	s_mov_b32 s29, s65
	s_mov_b32 s16, s66
	s_mov_b64 s[8:9], s[18:19]
	s_mov_b32 s64, s67
	v_mov_b32_e32 v1, v0
	v_mov_b32_e32 v2, v0
	v_mov_b32_e32 v3, v0
	v_mov_b32_e32 v4, v0
	v_mov_b32_e32 v5, v0
	v_mov_b32_e32 v6, v0
	v_mov_b32_e32 v7, v0
	v_mov_b32_e32 v8, v0
	v_mov_b32_e32 v9, v0
	v_mov_b32_e32 v10, v0
	v_mov_b32_e32 v11, v0
	v_mov_b32_e32 v12, v0
	v_mov_b32_e32 v13, v0
	v_mov_b32_e32 v14, v0
	v_mov_b32_e32 v15, v0
	v_mov_b32_e32 v16, v0
	v_mov_b32_e32 v17, v0
	v_mov_b32_e32 v18, v0
	v_mov_b32_e32 v19, v0
	v_mov_b32_e32 v20, v0
	v_mov_b32_e32 v21, v0
	v_mov_b32_e32 v22, v0
	v_mov_b32_e32 v23, v0
	v_mov_b32_e32 v24, v0
	v_mov_b32_e32 v25, v0
	v_mov_b32_e32 v26, v0
	v_mov_b32_e32 v27, v0
	v_mov_b32_e32 v28, v0
	v_mov_b32_e32 v29, v0
	v_mov_b32_e32 v30, v0
	v_mov_b32_e32 v31, v0
	v_mov_b32_e32 v64, v0
	v_mov_b32_e32 v65, v0
	v_mov_b32_e32 v66, v0
	v_mov_b32_e32 v67, v0
	v_mov_b32_e32 v68, v0
	v_mov_b32_e32 v69, v0
	v_mov_b32_e32 v70, v0
	v_mov_b32_e32 v71, v0
	v_mov_b32_e32 v72, v0
	v_mov_b32_e32 v73, v0
	v_mov_b32_e32 v74, v0
	v_mov_b32_e32 v75, v0
	v_mov_b32_e32 v76, v0
	v_mov_b32_e32 v77, v0
	v_mov_b32_e32 v78, v0
	v_mov_b32_e32 v79, v0
	v_mov_b32_e32 v80, v0
	v_mov_b32_e32 v81, v0
	v_mov_b32_e32 v82, v0
	v_mov_b32_e32 v83, v0
	v_mov_b32_e32 v84, v0
	v_mov_b32_e32 v85, v0
	v_mov_b32_e32 v86, v0
	v_mov_b32_e32 v87, v0
	v_mov_b32_e32 v88, v0
	v_mov_b32_e32 v89, v0
	v_mov_b32_e32 v90, v0
	v_mov_b32_e32 v91, v0
	v_mov_b32_e32 v92, v0
	v_mov_b32_e32 v93, v0
	v_mov_b32_e32 v94, v0
	v_mov_b32_e32 v95, v0
	v_mov_b32_e32 v32, v0
	v_mov_b32_e32 v33, v0
	v_mov_b32_e32 v34, v0
	v_mov_b32_e32 v35, v0
	v_mov_b32_e32 v36, v0
	v_mov_b32_e32 v37, v0
	v_mov_b32_e32 v38, v0
	v_mov_b32_e32 v39, v0
	v_mov_b32_e32 v40, v0
	v_mov_b32_e32 v41, v0
	v_mov_b32_e32 v42, v0
	v_mov_b32_e32 v43, v0
	v_mov_b32_e32 v44, v0
	v_mov_b32_e32 v45, v0
	v_mov_b32_e32 v46, v0
	v_mov_b32_e32 v47, v0
	v_mov_b32_e32 v48, v0
	v_mov_b32_e32 v49, v0
	v_mov_b32_e32 v50, v0
	v_mov_b32_e32 v51, v0
	v_mov_b32_e32 v52, v0
	v_mov_b32_e32 v53, v0
	v_mov_b32_e32 v54, v0
	v_mov_b32_e32 v55, v0
	v_mov_b32_e32 v56, v0
	v_mov_b32_e32 v57, v0
	v_mov_b32_e32 v58, v0
	v_mov_b32_e32 v59, v0
	v_mov_b32_e32 v60, v0
	v_mov_b32_e32 v61, v0
	v_mov_b32_e32 v62, v0
	v_mov_b32_e32 v63, v0
	v_mov_b32_e32 v96, v0
	v_mov_b32_e32 v97, v0
	v_mov_b32_e32 v98, v0
	v_mov_b32_e32 v99, v0
	v_mov_b32_e32 v100, v0
	v_mov_b32_e32 v101, v0
	v_mov_b32_e32 v102, v0
	v_mov_b32_e32 v103, v0
	v_mov_b32_e32 v104, v0
	v_mov_b32_e32 v105, v0
	v_mov_b32_e32 v106, v0
	v_mov_b32_e32 v107, v0
	v_mov_b32_e32 v108, v0
	v_mov_b32_e32 v109, v0
	v_mov_b32_e32 v110, v0
	v_mov_b32_e32 v111, v0
	v_mov_b32_e32 v112, v0
	v_mov_b32_e32 v113, v0
	v_mov_b32_e32 v114, v0
	v_mov_b32_e32 v115, v0
	v_mov_b32_e32 v116, v0
	v_mov_b32_e32 v117, v0
	v_mov_b32_e32 v118, v0
	v_mov_b32_e32 v119, v0
	v_mov_b32_e32 v120, v0
	v_mov_b32_e32 v121, v0
	v_mov_b32_e32 v122, v0
	v_mov_b32_e32 v123, v0
	v_mov_b32_e32 v124, v0
	v_mov_b32_e32 v125, v0
	v_mov_b32_e32 v126, v0
	v_mov_b32_e32 v127, v0
	s_andn2_b64 vcc, exec, s[4:5]
	s_cbranch_vccnz .LBB0_1078
	s_branch .LBB0_1079

; #define PG8_STAGE(bufoff, gbase, voff) do { _Pragma("unroll") for (int _i = 0; _i < 2; ++_i) \
;         __builtin_amdgcn_global_load_lds((const unsigned*)((const char*)(gbase) + (voff)[_i]), (PG8_LAS unsigned*)(lds + (bufoff) + ldsw + _i * 8192), 16, 0, 0); } while (0)
; #define PG8_LDA(dst, b, h) do { _Pragma("unroll") for (int m = 0; m < 4; ++m) _Pragma("unroll") for (int k = 0; k < 2; ++k) dst[m][k] = *(const PG8_LAS bf16x8*)(lds + PG8_SA(b, h) + aoff + m * 2048 + k * 1024); } while (0)
; #define PG8_LDB(dst, b, h) do { _Pragma("unroll") for (int n = 0; n < 2; ++n) _Pragma("unroll") for (int k = 0; k < 2; ++k) dst[n][k] = *(const PG8_LAS bf16x8*)(lds + PG8_SB(b, h) + boff + n * 2048 + k * 1024); } while (0)
; #define PG8_MMA(ai, bj, At, Bt) do { __builtin_amdgcn_s_setprio(1); _Pragma("unroll") for (int m = 0; m < 4; ++m) _Pragma("unroll") for (int n = 0; n < 2; ++n) _Pragma("unroll") for (int k = 0; k < 2; ++k) \
;         acc[ai][bj][m][n] = __builtin_amdgcn_mfma_f32_16x16x32_bf16(Bt[n][k], At[m][k], acc[ai][bj][m][n], 0, 0, 0); __builtin_amdgcn_s_setprio(0); } while (0)
; #define PG8_WAIT_L(n) asm volatile("s_waitcnt lgkmcnt(" #n ")" ::: "memory")
; #define PG8_BAR __builtin_amdgcn_s_barrier()
; #define PG8_SCHED __builtin_amdgcn_sched_barrier(0)
; template <class Epi, class Sched>
; __device__ __forceinline__ void gemm_phase(PG8_LAS unsigned char* lds, const Gemm g, const Sched& S, const Epi& E) {
;     ...
;         for (int t = 0; t < nt; t += 2) {
;             const bool last = (t == nt - 2);
;             const char* a1 = cA + (size_t)(t + 1) * kstep;
;             const char* a2 = last ? nA : cA + (size_t)(t + 2) * kstep; const char* b2 = last ? nB : cB + (size_t)(t + 2) * kstep;
;             const char* a3 = a2 + kstep; const char* b3 = b2 + kstep;
;             if (last && has_next) S.a_ready(nxt);
;             PG8_LDB(B0, 0, 0); PG8_SCHED; PG8_LDA(At, 0, 0); PG8_STAGE(PG8_SA(1, 1), a1 + hstep, voffA);
;             PG8_WAIT_L(8); PG8_BAR; PG8_WAIT_L(0); PG8_MMA(0, 0, At, B0); PG8_BAR; PG8_SCHED;
;             PG8_LDB(B1, 0, 1); PG8_STAGE(PG8_SB(0, 0), b2, voffB);
;             PG8_BAR; PG8_WAIT_L(0); PG8_MMA(0, 1, At, B1); PG8_BAR;
;             PG8_LDA(At, 0, 1); PG8_STAGE(PG8_SA(0, 0), a2, voffA);
;             PG8_BAR; PG8_WAIT_L(0); PG8_MMA(1, 0, At, B0); PG8_BAR; PG8_SCHED;
.LBB0_1165:
	s_add_u32 s12, s16, s20
	s_addc_u32 s13, s17, s21
	s_add_u32 s12, s12, 0x100
	s_addc_u32 s13, s13, 0
	s_add_u32 s22, s65, s20
	s_addc_u32 s23, s66, s21
	s_add_i32 s68, s46, 0x100
	v_add_u32_e32 v159, s68, v156
	ds_read_b128 v[160:163], v159
	ds_read_b128 v[164:167], v159 offset:1024
	ds_read_b128 v[168:171], v159 offset:2048
	ds_read_b128 v[172:175], v159 offset:3072
	s_cmpk_eq_i32 s20, 0x1500
	s_cselect_b32 s25, s19, s13
	s_cselect_b32 s24, s18, s12
	s_cselect_b32 s23, s7, s23
	s_cselect_b32 s22, s6, s22
	v_lshl_add_u64 v[230:231], v[150:151], 0, s[20:21]
	s_add_i32 m0, s39, 0xc000
	ds_read_b128 v[176:179], v157
	ds_read_b128 v[180:183], v157 offset:1024
	ds_read_b128 v[184:187], v157 offset:2048
	ds_read_b128 v[210:213], v157 offset:3072
	ds_read_b128 v[214:217], v157 offset:4096
	ds_read_b128 v[218:221], v157 offset:5120
	ds_read_b128 v[222:225], v157 offset:6144
	ds_read_b128 v[226:229], v157 offset:7168
	global_load_lds_dwordx4 v[230:231], off
	v_lshl_add_u64 v[230:231], v[152:153], 0, s[20:21]
	s_add_i32 m0, s39, 0xe000
	s_nop 0
	global_load_lds_dwordx4 v[230:231], off
	s_waitcnt lgkmcnt(8)
	s_barrier
	s_waitcnt lgkmcnt(0)
	s_waitcnt lgkmcnt(0)
	v_mfma_f32_16x16x32_bf16 v[124:127], v[160:163], v[176:179], v[124:127]
	v_mfma_f32_16x16x32_bf16 v[120:123], v[168:171], v[176:179], v[120:123]
	v_mfma_f32_16x16x32_bf16 v[116:119], v[160:163], v[184:187], v[116:119]
	v_mfma_f32_16x16x32_bf16 v[112:115], v[168:171], v[184:187], v[112:115]
	v_mfma_f32_16x16x32_bf16 v[108:111], v[160:163], v[214:217], v[108:111]
	v_mfma_f32_16x16x32_bf16 v[104:107], v[168:171], v[214:217], v[104:107]
	v_mfma_f32_16x16x32_bf16 v[100:103], v[160:163], v[222:225], v[100:103]
	v_mfma_f32_16x16x32_bf16 v[96:99], v[168:171], v[222:225], v[96:99]
	v_mfma_f32_16x16x32_bf16 v[124:127], v[164:167], v[180:183], v[124:127]
	v_mfma_f32_16x16x32_bf16 v[120:123], v[172:175], v[180:183], v[120:123]
	v_mfma_f32_16x16x32_bf16 v[116:119], v[164:167], v[210:213], v[116:119]
	v_mfma_f32_16x16x32_bf16 v[112:115], v[172:175], v[210:213], v[112:115]
	v_mfma_f32_16x16x32_bf16 v[108:111], v[164:167], v[218:221], v[108:111]
	v_mfma_f32_16x16x32_bf16 v[104:107], v[172:175], v[218:221], v[104:107]
	v_mfma_f32_16x16x32_bf16 v[100:103], v[164:167], v[226:229], v[100:103]
	v_mfma_f32_16x16x32_bf16 v[96:99], v[172:175], v[226:229], v[96:99]
	s_barrier
	s_add_i32 s69, s48, 0x100
	s_add_i32 s12, s68, s38
	v_add_u32_e32 v159, s69, v156
	v_lshl_add_u64 v[246:247], s[22:23], 0, v[138:139]
	s_mov_b32 m0, s12
	ds_read_b128 v[230:233], v159
	ds_read_b128 v[234:237], v159 offset:1024
	ds_read_b128 v[238:241], v159 offset:2048
	ds_read_b128 v[242:245], v159 offset:3072
	global_load_lds_dwordx4 v[246:247], off
	v_lshl_add_u64 v[248:249], s[22:23], 0, v[132:133]
	s_add_i32 m0, s12, 0x2000
	s_nop 0
	global_load_lds_dwordx4 v[248:249], off
	s_barrier
	s_waitcnt lgkmcnt(0)
	s_waitcnt lgkmcnt(0)
	v_mfma_f32_16x16x32_bf16 v[60:63], v[230:233], v[176:179], v[60:63]
	v_mfma_f32_16x16x32_bf16 v[56:59], v[238:241], v[176:179], v[56:59]
	v_mfma_f32_16x16x32_bf16 v[52:55], v[230:233], v[184:187], v[52:55]
	v_mfma_f32_16x16x32_bf16 v[48:51], v[238:241], v[184:187], v[48:51]
	v_mfma_f32_16x16x32_bf16 v[44:47], v[230:233], v[214:217], v[44:47]
	v_mfma_f32_16x16x32_bf16 v[40:43], v[238:241], v[214:217], v[40:43]
	v_mfma_f32_16x16x32_bf16 v[36:39], v[230:233], v[222:225], v[36:39]
	v_mfma_f32_16x16x32_bf16 v[32:35], v[238:241], v[222:225], v[32:35]
	v_mfma_f32_16x16x32_bf16 v[60:63], v[234:237], v[180:183], v[60:63]
	v_mfma_f32_16x16x32_bf16 v[56:59], v[242:245], v[180:183], v[56:59]
	v_mfma_f32_16x16x32_bf16 v[52:55], v[234:237], v[210:213], v[52:55]
	v_mfma_f32_16x16x32_bf16 v[48:51], v[242:245], v[210:213], v[48:51]
	v_mfma_f32_16x16x32_bf16 v[44:47], v[234:237], v[218:221], v[44:47]
	v_mfma_f32_16x16x32_bf16 v[40:43], v[242:245], v[218:221], v[40:43]
	v_mfma_f32_16x16x32_bf16 v[36:39], v[234:237], v[226:229], v[36:39]
	v_mfma_f32_16x16x32_bf16 v[32:35], v[242:245], v[226:229], v[32:35]
	s_mov_b32 m0, s39
	v_lshl_add_u64 v[250:251], s[24:25], 0, v[128:129]
	s_barrier
	ds_read_b128 v[176:179], v157 offset:16384
	ds_read_b128 v[180:183], v157 offset:17408
	ds_read_b128 v[184:187], v157 offset:18432
	ds_read_b128 v[210:213], v157 offset:19456
	ds_read_b128 v[214:217], v157 offset:20480
	ds_read_b128 v[218:221], v157 offset:21504
	ds_read_b128 v[222:225], v157 offset:22528
	ds_read_b128 v[226:229], v157 offset:23552
	global_load_lds_dwordx4 v[250:251], off
	v_lshl_add_u64 v[252:253], s[24:25], 0, v[130:131]
	s_mov_b32 m0, s40
	s_nop 0
	global_load_lds_dwordx4 v[252:253], off
	s_barrier
	s_waitcnt lgkmcnt(0)
	s_waitcnt lgkmcnt(0)
	v_mfma_f32_16x16x32_bf16 v[92:95], v[160:163], v[176:179], v[92:95]
	v_mfma_f32_16x16x32_bf16 v[88:91], v[168:171], v[176:179], v[88:91]
	v_mfma_f32_16x16x32_bf16 v[84:87], v[160:163], v[184:187], v[84:87]
	v_mfma_f32_16x16x32_bf16 v[80:83], v[168:171], v[184:187], v[80:83]
	v_mfma_f32_16x16x32_bf16 v[76:79], v[160:163], v[214:217], v[76:79]
	v_mfma_f32_16x16x32_bf16 v[72:75], v[168:171], v[214:217], v[72:75]
	v_mfma_f32_16x16x32_bf16 v[68:71], v[160:163], v[222:225], v[68:71]
	v_mfma_f32_16x16x32_bf16 v[64:67], v[168:171], v[222:225], v[64:67]
	v_mfma_f32_16x16x32_bf16 v[92:95], v[164:167], v[180:183], v[92:95]
	v_mfma_f32_16x16x32_bf16 v[88:91], v[172:175], v[180:183], v[88:91]
	v_mfma_f32_16x16x32_bf16 v[84:87], v[164:167], v[210:213], v[84:87]
	v_mfma_f32_16x16x32_bf16 v[80:83], v[172:175], v[210:213], v[80:83]
	v_mfma_f32_16x16x32_bf16 v[76:79], v[164:167], v[218:221], v[76:79]
	v_mfma_f32_16x16x32_bf16 v[72:75], v[172:175], v[218:221], v[72:75]
	v_mfma_f32_16x16x32_bf16 v[68:71], v[164:167], v[226:229], v[68:71]
	v_mfma_f32_16x16x32_bf16 v[64:67], v[172:175], v[226:229], v[64:67]
	s_barrier
; #define PG8_STAGE(bufoff, gbase, voff) do { _Pragma("unroll") for (int _i = 0; _i < 2; ++_i) \
;         __builtin_amdgcn_global_load_lds((const unsigned*)((const char*)(gbase) + (voff)[_i]), (PG8_LAS unsigned*)(lds + (bufoff) + ldsw + _i * 8192), 16, 0, 0); } while (0)
; #define PG8_LDA(dst, b, h) do { _Pragma("unroll") for (int m = 0; m < 4; ++m) _Pragma("unroll") for (int k = 0; k < 2; ++k) dst[m][k] = *(const PG8_LAS bf16x8*)(lds + PG8_SA(b, h) + aoff + m * 2048 + k * 1024); } while (0)
; #define PG8_LDB(dst, b, h) do { _Pragma("unroll") for (int n = 0; n < 2; ++n) _Pragma("unroll") for (int k = 0; k < 2; ++k) dst[n][k] = *(const PG8_LAS bf16x8*)(lds + PG8_SB(b, h) + boff + n * 2048 + k * 1024); } while (0)
; #define PG8_MMA(ai, bj, At, Bt) do { __builtin_amdgcn_s_setprio(1); _Pragma("unroll") for (int m = 0; m < 4; ++m) _Pragma("unroll") for (int n = 0; n < 2; ++n) _Pragma("unroll") for (int k = 0; k < 2; ++k) \
;         acc[ai][bj][m][n] = __builtin_amdgcn_mfma_f32_16x16x32_bf16(Bt[n][k], At[m][k], acc[ai][bj][m][n], 0, 0, 0); __builtin_amdgcn_s_setprio(0); } while (0)
; #define PG8_WAIT_V(n) asm volatile("s_waitcnt vmcnt(" #n ")" ::: "memory")
; #define PG8_WAIT_L(n) asm volatile("s_waitcnt lgkmcnt(" #n ")" ::: "memory")
; #define PG8_BAR __builtin_amdgcn_s_barrier()
; #define PG8_SCHED __builtin_amdgcn_sched_barrier(0)
; template <class Epi, class Sched>
; __device__ __forceinline__ void gemm_phase(PG8_LAS unsigned char* lds, const Gemm g, const Sched& S, const Epi& E) {
;     ...
;             PG8_STAGE(PG8_SB(0, 1), b2 + hstep, voffB);
;             PG8_WAIT_V(6); PG8_BAR; PG8_MMA(1, 1, At, B1); PG8_BAR;
;             PG8_LDB(B0, 1, 0); PG8_SCHED; PG8_LDA(At, 1, 0); PG8_STAGE(PG8_SA(0, 1), a2 + hstep, voffA);
;             PG8_WAIT_L(8); PG8_BAR; PG8_WAIT_L(0); PG8_MMA(0, 0, At, B0); PG8_BAR; PG8_SCHED;
;             PG8_LDB(B1, 1, 1); PG8_STAGE(PG8_SB(1, 0), b3, voffB);
;             PG8_BAR; PG8_WAIT_L(0); PG8_MMA(0, 1, At, B1); PG8_BAR;
;             PG8_LDA(At, 1, 1); PG8_STAGE(PG8_SA(1, 0), a3, voffA);
;             PG8_BAR; PG8_WAIT_L(0); PG8_MMA(1, 0, At, B0); PG8_BAR; PG8_SCHED;
	s_add_u32 s12, s22, 0xb0000
	s_addc_u32 s13, s23, 0
	s_add_i32 s68, s69, s38
	v_lshl_add_u64 v[160:161], s[12:13], 0, v[138:139]
	s_mov_b32 m0, s68
	s_nop 0
	global_load_lds_dwordx4 v[160:161], off
	v_lshl_add_u64 v[160:161], s[12:13], 0, v[132:133]
	s_add_i32 m0, s68, 0x2000
	s_nop 0
	global_load_lds_dwordx4 v[160:161], off
	s_waitcnt vmcnt(6)
	s_barrier
	v_mfma_f32_16x16x32_bf16 v[28:31], v[230:233], v[176:179], v[28:31]
	v_mfma_f32_16x16x32_bf16 v[24:27], v[238:241], v[176:179], v[24:27]
	v_mfma_f32_16x16x32_bf16 v[20:23], v[230:233], v[184:187], v[20:23]
	v_mfma_f32_16x16x32_bf16 v[16:19], v[238:241], v[184:187], v[16:19]
	v_mfma_f32_16x16x32_bf16 v[12:15], v[230:233], v[214:217], v[12:15]
	v_mfma_f32_16x16x32_bf16 v[8:11], v[238:241], v[214:217], v[8:11]
	v_mfma_f32_16x16x32_bf16 v[4:7], v[230:233], v[222:225], v[4:7]
	v_mfma_f32_16x16x32_bf16 v[0:3], v[238:241], v[222:225], v[0:3]
	v_mfma_f32_16x16x32_bf16 v[28:31], v[234:237], v[180:183], v[28:31]
	v_mfma_f32_16x16x32_bf16 v[24:27], v[242:245], v[180:183], v[24:27]
	v_mfma_f32_16x16x32_bf16 v[20:23], v[234:237], v[210:213], v[20:23]
	v_mfma_f32_16x16x32_bf16 v[16:19], v[242:245], v[210:213], v[16:19]
	v_mfma_f32_16x16x32_bf16 v[12:15], v[234:237], v[218:221], v[12:15]
	v_mfma_f32_16x16x32_bf16 v[8:11], v[242:245], v[218:221], v[8:11]
	v_mfma_f32_16x16x32_bf16 v[4:7], v[234:237], v[226:229], v[4:7]
	v_mfma_f32_16x16x32_bf16 v[0:3], v[242:245], v[226:229], v[0:3]
	s_add_i32 s68, s51, 0x100
	v_add_u32_e32 v159, s68, v156
	s_barrier
	ds_read_b128 v[160:163], v159
	ds_read_b128 v[164:167], v159 offset:1024
	ds_read_b128 v[168:171], v159 offset:2048
	ds_read_b128 v[172:175], v159 offset:3072
	s_add_u32 s12, s24, 0xb0000
	s_addc_u32 s13, s25, 0
	s_mov_b32 m0, s41
	v_lshl_add_u64 v[230:231], s[12:13], 0, v[128:129]
	ds_read_b128 v[176:179], v157 offset:32768
	ds_read_b128 v[180:183], v157 offset:33792
	ds_read_b128 v[184:187], v157 offset:34816
	ds_read_b128 v[210:213], v157 offset:35840
	ds_read_b128 v[214:217], v157 offset:36864
	ds_read_b128 v[218:221], v157 offset:37888
	ds_read_b128 v[222:225], v157 offset:38912
	ds_read_b128 v[226:229], v157 offset:39936
	global_load_lds_dwordx4 v[230:231], off
	v_lshl_add_u64 v[230:231], s[12:13], 0, v[130:131]
	s_mov_b32 m0, s58
	s_nop 0
	global_load_lds_dwordx4 v[230:231], off
	s_waitcnt lgkmcnt(8)
	s_barrier
	s_waitcnt lgkmcnt(0)
	s_waitcnt lgkmcnt(0)
	v_mfma_f32_16x16x32_bf16 v[124:127], v[160:163], v[176:179], v[124:127]
	v_mfma_f32_16x16x32_bf16 v[120:123], v[168:171], v[176:179], v[120:123]
	v_mfma_f32_16x16x32_bf16 v[116:119], v[160:163], v[184:187], v[116:119]
	v_mfma_f32_16x16x32_bf16 v[112:115], v[168:171], v[184:187], v[112:115]
	v_mfma_f32_16x16x32_bf16 v[108:111], v[160:163], v[214:217], v[108:111]
	v_mfma_f32_16x16x32_bf16 v[104:107], v[168:171], v[214:217], v[104:107]
	v_mfma_f32_16x16x32_bf16 v[100:103], v[160:163], v[222:225], v[100:103]
	v_mfma_f32_16x16x32_bf16 v[96:99], v[168:171], v[222:225], v[96:99]
	v_mfma_f32_16x16x32_bf16 v[124:127], v[164:167], v[180:183], v[124:127]
	v_mfma_f32_16x16x32_bf16 v[120:123], v[172:175], v[180:183], v[120:123]
	v_mfma_f32_16x16x32_bf16 v[116:119], v[164:167], v[210:213], v[116:119]
	v_mfma_f32_16x16x32_bf16 v[112:115], v[172:175], v[210:213], v[112:115]
	v_mfma_f32_16x16x32_bf16 v[108:111], v[164:167], v[218:221], v[108:111]
	v_mfma_f32_16x16x32_bf16 v[104:107], v[172:175], v[218:221], v[104:107]
	v_mfma_f32_16x16x32_bf16 v[100:103], v[164:167], v[226:229], v[100:103]
	v_mfma_f32_16x16x32_bf16 v[96:99], v[172:175], v[226:229], v[96:99]
	s_barrier
	s_add_i32 s24, s55, 0x100
	s_add_i32 s12, s68, s38
	v_add_u32_e32 v159, s24, v156
	v_lshl_add_u64 v[246:247], v[246:247], 0, s[94:95]
	s_mov_b32 m0, s12
	ds_read_b128 v[230:233], v159
	ds_read_b128 v[234:237], v159 offset:1024
	ds_read_b128 v[238:241], v159 offset:2048
	ds_read_b128 v[242:245], v159 offset:3072
	global_load_lds_dwordx4 v[246:247], off
	v_lshl_add_u64 v[246:247], v[248:249], 0, s[94:95]
	s_add_i32 m0, s12, 0x2000
	s_nop 0
	global_load_lds_dwordx4 v[246:247], off
	s_barrier
	s_waitcnt lgkmcnt(0)
	s_waitcnt lgkmcnt(0)
	v_mfma_f32_16x16x32_bf16 v[60:63], v[230:233], v[176:179], v[60:63]
	v_mfma_f32_16x16x32_bf16 v[56:59], v[238:241], v[176:179], v[56:59]
	v_mfma_f32_16x16x32_bf16 v[52:55], v[230:233], v[184:187], v[52:55]
	v_mfma_f32_16x16x32_bf16 v[48:51], v[238:241], v[184:187], v[48:51]
	v_mfma_f32_16x16x32_bf16 v[44:47], v[230:233], v[214:217], v[44:47]
	v_mfma_f32_16x16x32_bf16 v[40:43], v[238:241], v[214:217], v[40:43]
	v_mfma_f32_16x16x32_bf16 v[36:39], v[230:233], v[222:225], v[36:39]
	v_mfma_f32_16x16x32_bf16 v[32:35], v[238:241], v[222:225], v[32:35]
	v_mfma_f32_16x16x32_bf16 v[60:63], v[234:237], v[180:183], v[60:63]
	v_mfma_f32_16x16x32_bf16 v[56:59], v[242:245], v[180:183], v[56:59]
	v_mfma_f32_16x16x32_bf16 v[52:55], v[234:237], v[210:213], v[52:55]
	v_mfma_f32_16x16x32_bf16 v[48:51], v[242:245], v[210:213], v[48:51]
	v_mfma_f32_16x16x32_bf16 v[44:47], v[234:237], v[218:221], v[44:47]
	v_mfma_f32_16x16x32_bf16 v[40:43], v[242:245], v[218:221], v[40:43]
	v_mfma_f32_16x16x32_bf16 v[36:39], v[234:237], v[226:229], v[36:39]
	v_mfma_f32_16x16x32_bf16 v[32:35], v[242:245], v[226:229], v[32:35]
	s_mov_b32 m0, s59
	v_lshl_add_u64 v[246:247], v[250:251], 0, s[94:95]
	s_barrier
	ds_read_b128 v[176:179], v157 offset:49152
	ds_read_b128 v[180:183], v157 offset:50176
	ds_read_b128 v[184:187], v157 offset:51200
	ds_read_b128 v[210:213], v157 offset:52224
	ds_read_b128 v[214:217], v157 offset:53248
	ds_read_b128 v[218:221], v157 offset:54272
	ds_read_b128 v[222:225], v157 offset:55296
	ds_read_b128 v[226:229], v157 offset:56320
	global_load_lds_dwordx4 v[246:247], off
	v_lshl_add_u64 v[246:247], v[252:253], 0, s[94:95]
	s_mov_b32 m0, s60
	s_nop 0
	global_load_lds_dwordx4 v[246:247], off
	s_barrier
; #define PG8_STAGE(bufoff, gbase, voff) do { _Pragma("unroll") for (int _i = 0; _i < 2; ++_i) \
;         __builtin_amdgcn_global_load_lds((const unsigned*)((const char*)(gbase) + (voff)[_i]), (PG8_LAS unsigned*)(lds + (bufoff) + ldsw + _i * 8192), 16, 0, 0); } while (0)
; #define PG8_MMA(ai, bj, At, Bt) do { __builtin_amdgcn_s_setprio(1); _Pragma("unroll") for (int m = 0; m < 4; ++m) _Pragma("unroll") for (int n = 0; n < 2; ++n) _Pragma("unroll") for (int k = 0; k < 2; ++k) \
;         acc[ai][bj][m][n] = __builtin_amdgcn_mfma_f32_16x16x32_bf16(Bt[n][k], At[m][k], acc[ai][bj][m][n], 0, 0, 0); __builtin_amdgcn_s_setprio(0); } while (0)
; #define PG8_WAIT_V(n) asm volatile("s_waitcnt vmcnt(" #n ")" ::: "memory")
; #define PG8_WAIT_L(n) asm volatile("s_waitcnt lgkmcnt(" #n ")" ::: "memory")
; #define PG8_BAR __builtin_amdgcn_s_barrier()
; #define PG8_SCHED __builtin_amdgcn_sched_barrier(0)
; template <class Epi, class Sched>
; __device__ __forceinline__ void gemm_phase(PG8_LAS unsigned char* lds, const Gemm g, const Sched& S, const Epi& E) {
;     ...
;             PG8_BAR; PG8_WAIT_L(0); PG8_MMA(1, 0, At, B0); PG8_BAR; PG8_SCHED;
;             PG8_STAGE(PG8_SB(1, 1), b3 + hstep, voffB);
;             PG8_WAIT_V(6); PG8_BAR; PG8_MMA(1, 1, At, B1); PG8_BAR;
;         }
;         if constexpr (!Epi::AFTER_DRAIN) { E(acc, cur, wr, wc, fr, fq); S.done(cur); }
;         if (!has_next) break;
; #pragma unroll
;         for (int a = 0; a < 2; ++a)
; #pragma unroll
;             for (int b = 0; b < 2; ++b)
; #pragma unroll
;                 for (int m = 0; m < 4; ++m)
; #pragma unroll
;                     for (int n = 0; n < 2; ++n) acc[a][b][m][n] = (f32x4){0.f, 0.f, 0.f, 0.f};
;         cur = nxt; cA = nA; cB = nB; ++ui;
	s_waitcnt lgkmcnt(0)
	s_waitcnt lgkmcnt(0)
	v_mfma_f32_16x16x32_bf16 v[92:95], v[160:163], v[176:179], v[92:95]
	v_mfma_f32_16x16x32_bf16 v[88:91], v[168:171], v[176:179], v[88:91]
	v_mfma_f32_16x16x32_bf16 v[84:87], v[160:163], v[184:187], v[84:87]
	v_mfma_f32_16x16x32_bf16 v[80:83], v[168:171], v[184:187], v[80:83]
	v_mfma_f32_16x16x32_bf16 v[76:79], v[160:163], v[214:217], v[76:79]
	v_mfma_f32_16x16x32_bf16 v[72:75], v[168:171], v[214:217], v[72:75]
	v_mfma_f32_16x16x32_bf16 v[68:71], v[160:163], v[222:225], v[68:71]
	v_mfma_f32_16x16x32_bf16 v[64:67], v[168:171], v[222:225], v[64:67]
	v_mfma_f32_16x16x32_bf16 v[92:95], v[164:167], v[180:183], v[92:95]
	v_mfma_f32_16x16x32_bf16 v[88:91], v[172:175], v[180:183], v[88:91]
	v_mfma_f32_16x16x32_bf16 v[84:87], v[164:167], v[210:213], v[84:87]
	v_mfma_f32_16x16x32_bf16 v[80:83], v[172:175], v[210:213], v[80:83]
	v_mfma_f32_16x16x32_bf16 v[76:79], v[164:167], v[218:221], v[76:79]
	v_mfma_f32_16x16x32_bf16 v[72:75], v[172:175], v[218:221], v[72:75]
	v_mfma_f32_16x16x32_bf16 v[68:71], v[164:167], v[226:229], v[68:71]
	v_mfma_f32_16x16x32_bf16 v[64:67], v[172:175], v[226:229], v[64:67]
	s_barrier
	s_add_u32 s12, s22, 0xb0080
	s_addc_u32 s13, s23, 0
	s_add_i32 s22, s24, s38
	v_lshl_add_u64 v[160:161], s[12:13], 0, v[138:139]
	s_mov_b32 m0, s22
	s_nop 0
	global_load_lds_dwordx4 v[160:161], off
	v_lshl_add_u64 v[160:161], s[12:13], 0, v[132:133]
	s_add_i32 m0, s22, 0x2000
	s_nop 0
	global_load_lds_dwordx4 v[160:161], off
	s_waitcnt vmcnt(6)
	s_barrier
	v_mfma_f32_16x16x32_bf16 v[28:31], v[230:233], v[176:179], v[28:31]
	v_mfma_f32_16x16x32_bf16 v[24:27], v[238:241], v[176:179], v[24:27]
	v_mfma_f32_16x16x32_bf16 v[20:23], v[230:233], v[184:187], v[20:23]
	v_mfma_f32_16x16x32_bf16 v[16:19], v[238:241], v[184:187], v[16:19]
	v_mfma_f32_16x16x32_bf16 v[12:15], v[230:233], v[214:217], v[12:15]
	v_mfma_f32_16x16x32_bf16 v[8:11], v[238:241], v[214:217], v[8:11]
	v_mfma_f32_16x16x32_bf16 v[4:7], v[230:233], v[222:225], v[4:7]
	v_mfma_f32_16x16x32_bf16 v[0:3], v[238:241], v[222:225], v[0:3]
	v_mfma_f32_16x16x32_bf16 v[28:31], v[234:237], v[180:183], v[28:31]
	v_mfma_f32_16x16x32_bf16 v[24:27], v[242:245], v[180:183], v[24:27]
	v_mfma_f32_16x16x32_bf16 v[20:23], v[234:237], v[210:213], v[20:23]
	v_mfma_f32_16x16x32_bf16 v[16:19], v[242:245], v[210:213], v[16:19]
	v_mfma_f32_16x16x32_bf16 v[12:15], v[234:237], v[218:221], v[12:15]
	v_mfma_f32_16x16x32_bf16 v[8:11], v[242:245], v[218:221], v[8:11]
	v_mfma_f32_16x16x32_bf16 v[4:7], v[234:237], v[226:229], v[4:7]
	v_mfma_f32_16x16x32_bf16 v[0:3], v[242:245], v[226:229], v[0:3]
	s_add_i32 s67, s67, 2
	s_add_u32 s20, s20, 0x100
	s_addc_u32 s21, s21, 0
	s_cmp_gt_u32 s67, 41
	s_barrier
	s_cbranch_scc0 .LBB0_1165
	s_add_u32 s20, s65, 0xffffff00
	s_addc_u32 s21, s66, -1
	s_and_b64 vcc, exec, s[0:1]
	s_cbranch_vccnz .LBB0_1168
	v_mov_b32_e32 v0, 0
	s_mov_b32 s27, s62
	s_mov_b32 s8, s63
	s_mov_b64 s[16:17], s[18:19]
	s_mov_b32 s61, s64
	v_mov_b32_e32 v1, v0
	v_mov_b32_e32 v2, v0
	v_mov_b32_e32 v3, v0
	v_mov_b32_e32 v4, v0
	v_mov_b32_e32 v5, v0
	v_mov_b32_e32 v6, v0
	v_mov_b32_e32 v7, v0
	v_mov_b32_e32 v8, v0
	v_mov_b32_e32 v9, v0
	v_mov_b32_e32 v10, v0
	v_mov_b32_e32 v11, v0
	v_mov_b32_e32 v12, v0
	v_mov_b32_e32 v13, v0
	v_mov_b32_e32 v14, v0
	v_mov_b32_e32 v15, v0
	v_mov_b32_e32 v16, v0
	v_mov_b32_e32 v17, v0
	v_mov_b32_e32 v18, v0
	v_mov_b32_e32 v19, v0
	v_mov_b32_e32 v20, v0
	v_mov_b32_e32 v21, v0
	v_mov_b32_e32 v22, v0
	v_mov_b32_e32 v23, v0
	v_mov_b32_e32 v24, v0
	v_mov_b32_e32 v25, v0
	v_mov_b32_e32 v26, v0
	v_mov_b32_e32 v27, v0
	v_mov_b32_e32 v28, v0
	v_mov_b32_e32 v29, v0
	v_mov_b32_e32 v30, v0
	v_mov_b32_e32 v31, v0
	v_mov_b32_e32 v64, v0
	v_mov_b32_e32 v65, v0
	v_mov_b32_e32 v66, v0
	v_mov_b32_e32 v67, v0
	v_mov_b32_e32 v68, v0
	v_mov_b32_e32 v69, v0
	v_mov_b32_e32 v70, v0
	v_mov_b32_e32 v71, v0
	v_mov_b32_e32 v72, v0
	v_mov_b32_e32 v73, v0
	v_mov_b32_e32 v74, v0
	v_mov_b32_e32 v75, v0
	v_mov_b32_e32 v76, v0
	v_mov_b32_e32 v77, v0
	v_mov_b32_e32 v78, v0
	v_mov_b32_e32 v79, v0
	v_mov_b32_e32 v80, v0
	v_mov_b32_e32 v81, v0
	v_mov_b32_e32 v82, v0
	v_mov_b32_e32 v83, v0
	v_mov_b32_e32 v84, v0
	v_mov_b32_e32 v85, v0
	v_mov_b32_e32 v86, v0
	v_mov_b32_e32 v87, v0
	v_mov_b32_e32 v88, v0
	v_mov_b32_e32 v89, v0
	v_mov_b32_e32 v90, v0
	v_mov_b32_e32 v91, v0
	v_mov_b32_e32 v92, v0
	v_mov_b32_e32 v93, v0
	v_mov_b32_e32 v94, v0
	v_mov_b32_e32 v95, v0
	v_mov_b32_e32 v32, v0
	v_mov_b32_e32 v33, v0
	v_mov_b32_e32 v34, v0
	v_mov_b32_e32 v35, v0
	v_mov_b32_e32 v36, v0
	v_mov_b32_e32 v37, v0
	v_mov_b32_e32 v38, v0
	v_mov_b32_e32 v39, v0
	v_mov_b32_e32 v40, v0
	v_mov_b32_e32 v41, v0
	v_mov_b32_e32 v42, v0
	v_mov_b32_e32 v43, v0
	v_mov_b32_e32 v44, v0
	v_mov_b32_e32 v45, v0
	v_mov_b32_e32 v46, v0
	v_mov_b32_e32 v47, v0
	v_mov_b32_e32 v48, v0
	v_mov_b32_e32 v49, v0
	v_mov_b32_e32 v50, v0
	v_mov_b32_e32 v51, v0
	v_mov_b32_e32 v52, v0
	v_mov_b32_e32 v53, v0
	v_mov_b32_e32 v54, v0
	v_mov_b32_e32 v55, v0
	v_mov_b32_e32 v56, v0
	v_mov_b32_e32 v57, v0
	v_mov_b32_e32 v58, v0
	v_mov_b32_e32 v59, v0
	v_mov_b32_e32 v60, v0
	v_mov_b32_e32 v61, v0
	v_mov_b32_e32 v62, v0
	v_mov_b32_e32 v63, v0
	v_mov_b32_e32 v96, v0
	v_mov_b32_e32 v97, v0
	v_mov_b32_e32 v98, v0
	v_mov_b32_e32 v99, v0
	v_mov_b32_e32 v100, v0
	v_mov_b32_e32 v101, v0
	v_mov_b32_e32 v102, v0
	v_mov_b32_e32 v103, v0
	v_mov_b32_e32 v104, v0
	v_mov_b32_e32 v105, v0
	v_mov_b32_e32 v106, v0
	v_mov_b32_e32 v107, v0
	v_mov_b32_e32 v108, v0
	v_mov_b32_e32 v109, v0
	v_mov_b32_e32 v110, v0
	v_mov_b32_e32 v111, v0
	v_mov_b32_e32 v112, v0
	v_mov_b32_e32 v113, v0
	v_mov_b32_e32 v114, v0
	v_mov_b32_e32 v115, v0
	v_mov_b32_e32 v116, v0
	v_mov_b32_e32 v117, v0
	v_mov_b32_e32 v118, v0
	v_mov_b32_e32 v119, v0
	v_mov_b32_e32 v120, v0
	v_mov_b32_e32 v121, v0
	v_mov_b32_e32 v122, v0
	v_mov_b32_e32 v123, v0
	v_mov_b32_e32 v124, v0
	v_mov_b32_e32 v125, v0
	v_mov_b32_e32 v126, v0
	v_mov_b32_e32 v127, v0
	s_andn2_b64 vcc, exec, s[4:5]
	s_cbranch_vccnz .LBB0_1169
	s_branch .LBB0_1170
